# static s_setprio 1 for waves 4-7 in every GEMM tile loop, per-phase priority flips removed, priority reset at grid syncs (on top of v16)
# speedup vs baseline: 1.0146x; 1.0104x over previous
.LBB0_21:
	s_or_b64 exec, exec, s[4:5]
	v_lshrrev_b32_e32 v1, 20, v0
	v_lshrrev_b32_e32 v0, 10, v0
	v_or_b32_e32 v0, v0, v1
	s_movk_i32 s0, 0x3ff
	v_and_or_b32 v0, v0, s0, v154
	v_cmp_eq_u32_e64 s[58:59], 0, v0
	s_waitcnt lgkmcnt(0)
	s_barrier
	s_setprio 0
	s_and_saveexec_b64 s[4:5], s[58:59]
	s_cbranch_execz .LBB0_31
	buffer_wbl2 sc1
	s_waitcnt vmcnt(0)
	s_load_dwordx2 s[6:7], s[68:69], 0x58
	v_mov_b32_e32 v2, 0
	s_mov_b64 s[8:9], exec
	v_mbcnt_lo_u32_b32 v1, s8, 0
	v_mbcnt_hi_u32_b32 v1, s9, v1
	s_waitcnt lgkmcnt(0)
	global_load_dword v0, v2, s[6:7] offset:40
	v_cmp_eq_u32_e32 vcc, 0, v1
	s_and_saveexec_b64 s[10:11], vcc
	s_cbranch_execz .LBB0_24
	s_bcnt1_i32_b64 s0, s[8:9]
	v_mov_b32_e32 v3, s0
	global_atomic_add v3, v2, v3, s[6:7] offset:32 sc0

.LBB0_34:
	s_lshl_b32 s6, s6, 5
	s_and_b32 s13, s6, 0x60
	s_mov_b64 s[6:7], 0x80
	s_add_i32 m0, s9, 0x18000
	v_lshl_add_u64 v[6:7], v[6:7], 0, s[6:7]
	s_lshl_b32 s12, s5, 13
	s_lshl_b32 s14, s13, 7
	s_waitcnt vmcnt(4)
	s_barrier
	global_load_lds_dwordx4 v[6:7], off
	v_lshl_add_u64 v[4:5], v[4:5], 0, s[6:7]
	s_add_i32 m0, s9, 0x1a000
	s_add_i32 s71, s9, 0x8000
	s_add_i32 s72, s9, 0xa000
	global_load_lds_dwordx4 v[4:5], off
	v_lshl_add_u64 v[2:3], v[2:3], 0, s[6:7]
	s_mov_b32 m0, s71
	s_add_u32 s10, s90, 0x40080
	global_load_lds_dwordx4 v[2:3], off
	v_lshl_add_u64 v[0:1], v[0:1], 0, s[6:7]
	s_mov_b32 m0, s72
	s_addc_u32 s11, s91, 0
	global_load_lds_dwordx4 v[0:1], off
	s_add_i32 m0, s9, 0x1c000
	v_lshl_add_u64 v[0:1], s[10:11], 0, v[132:133]
	global_load_lds_dwordx4 v[0:1], off
	v_lshl_add_u64 v[0:1], s[10:11], 0, v[128:129]
	s_add_i32 m0, s9, 0x1e000
	s_add_i32 s74, 0, 0x10000
	global_load_lds_dwordx4 v[0:1], off
	v_lshrrev_b32_e32 v1, 1, v8
	v_and_b32_e32 v1, 24, v1
	v_and_b32_e32 v0, 15, v8
	v_lshlrev_b32_e32 v2, 1, v1
	v_lshl_or_b32 v144, s5, 6, v0
	v_lshl_or_b32 v0, v0, 6, v2
	v_lshlrev_b32_e32 v2, 2, v8
	v_and_b32_e32 v2, 32, v2
	v_bitop3_b32 v3, v0, s12, v2 bitop3:0xde
	v_bitop3_b32 v145, v0, s14, v2 bitop3:0xde
	v_lshlrev_b32_e32 v0, 14, v13
	v_and_b32_e32 v0, 0xffff8000, v0
	v_or_b32_e32 v146, s13, v1
	v_lshl_add_u32 v0, v12, 11, v0
	v_and_b32_e32 v1, 1, v13
	v_lshl_or_b32 v0, v1, 6, v0
	v_lshl_add_u32 v136, v14, 1, v0
	v_lshlrev_b32_e32 v0, 14, v9
	v_and_b32_e32 v0, 0xffff8000, v0
	s_waitcnt vmcnt(6)
	v_lshl_add_u32 v0, v10, 11, v0
	v_and_b32_e32 v1, 1, v9
	v_lshl_or_b32 v0, v1, 6, v0
	s_add_i32 s75, 0, 0x14000
	s_sext_i32_i8 s77, s4
	s_ashr_i32 s73, s3, 31
	v_mov_b32_e32 v137, v133
	v_lshl_add_u32 v138, v11, 1, v0
	v_mov_b32_e32 v139, v133
	v_mov_b64_e32 v[140:141], 0x1680
	v_mov_b64_e32 v[142:143], 0x167f
	v_add_u32_e32 v147, s74, v145
	v_add_u32_e32 v148, 0, v3
	v_add_u32_e32 v149, s75, v145
	s_movk_i32 s76, 0x1e00
	s_barrier
	v_readfirstlane_b32 s4, v154
	s_bitcmp1_b32 s4, 8
	s_cbranch_scc0 .Lprio_35
	s_setprio 1
.Lprio_35:
.LBB0_35:
	s_add_i32 s70, s70, 1
	s_mul_i32 s4, s70, s73
	s_mul_hi_u32 s5, s70, s3
	s_add_i32 s5, s5, s4
	s_mul_i32 s4, s70, s3
	s_add_u32 s14, s4, s2
	s_addc_u32 s15, s5, s33
	v_cmp_gt_i64_e64 s[4:5], s[14:15], v[142:143]
	s_and_b64 vcc, exec, s[4:5]
	s_cbranch_vccnz .LBB0_37
	s_ashr_i32 s10, s14, 31
	s_lshr_b32 s10, s10, 29
	s_add_i32 s10, s14, s10
	s_ashr_i32 s11, s10, 3
	s_and_b32 s10, s10, -8
	s_sub_i32 s10, s14, s10
	s_cmp_lt_i32 s10, 0
	s_cselect_b32 s12, s34, 0x2d0
	s_mul_i32 s10, s12, s10
	s_add_i32 s10, s10, s11
	s_mul_hi_i32 s11, s10, 0x88888889
	s_add_i32 s11, s11, s10
	s_lshr_b32 s12, s11, 31
	s_ashr_i32 s11, s11, 6
	s_add_i32 s11, s11, s12
	s_lshl_b32 s12, s11, 3
	s_sub_i32 s13, 0x180, s12
	s_min_i32 s13, s13, 8
	s_abs_i32 s78, s13
	v_cvt_f32_u32_e32 v0, s78
	s_sub_i32 s80, 0, s78
	s_mulk_i32 s11, 0x78
	s_sub_i32 s11, s10, s11
	v_rcp_iflag_f32_e32 v0, v0
	s_abs_i32 s10, s11
	s_xor_b32 s79, s11, s13
	s_ashr_i32 s79, s79, 31
	v_mul_f32_e32 v0, 0x4f7ffffe, v0
	v_cvt_u32_f32_e32 v0, v0
	s_nop 0
	v_readfirstlane_b32 s81, v0
	s_mul_i32 s80, s80, s81
	s_mul_hi_u32 s80, s81, s80
	s_add_i32 s81, s81, s80
	s_mul_hi_u32 s80, s10, s81
	s_mul_i32 s81, s80, s78
	s_sub_i32 s10, s10, s81
	s_add_i32 s82, s80, 1
	s_sub_i32 s81, s10, s78
	s_cmp_ge_u32 s10, s78
	s_cselect_b32 s80, s82, s80
	s_cselect_b32 s10, s81, s10
	s_add_i32 s81, s80, 1
	s_cmp_ge_u32 s10, s78
	s_cselect_b32 s10, s81, s80
	s_xor_b32 s10, s10, s79
	s_sub_i32 s10, s10, s79
	s_mul_i32 s13, s10, s13
	s_sub_i32 s11, s11, s13
	s_add_i32 s12, s11, s12

.LBB0_38:
	ds_read_b128 v[150:153], v147
	ds_read_b128 v[156:159], v147 offset:1024
	ds_read_b128 v[160:163], v147 offset:2048
	ds_read_b128 v[164:167], v147 offset:3072
	s_add_u32 s83, s88, 0xfffc0080
	s_addc_u32 s90, s89, -1
	s_cmp_eq_u32 s82, 12
	s_cselect_b32 s93, s13, s90
	s_cselect_b32 s92, s78, s83
	s_cselect_b32 s91, s11, s81
	s_cselect_b32 s90, s79, s80
	v_lshl_add_u64 v[200:201], s[88:89], 0, v[136:137]
	s_add_i32 m0, s9, 0xc000
	ds_read_b128 v[168:171], v148
	ds_read_b128 v[172:175], v148 offset:1024
	ds_read_b128 v[176:179], v148 offset:2048
	ds_read_b128 v[180:183], v148 offset:3072
	ds_read_b128 v[184:187], v148 offset:4096
	ds_read_b128 v[188:191], v148 offset:5120
	ds_read_b128 v[192:195], v148 offset:6144
	ds_read_b128 v[196:199], v148 offset:7168
	global_load_lds_dwordx4 v[200:201], off
	v_lshl_add_u64 v[200:201], s[88:89], 0, v[138:139]
	s_add_i32 m0, s9, 0xe000
	s_nop 0
	global_load_lds_dwordx4 v[200:201], off
	s_waitcnt lgkmcnt(8)
	s_barrier
	s_waitcnt lgkmcnt(0)
	s_waitcnt lgkmcnt(0)
	v_mfma_f32_16x16x32_bf16 v[124:127], v[150:153], v[168:171], v[124:127]
	v_mfma_f32_16x16x32_bf16 v[120:123], v[160:163], v[168:171], v[120:123]
	v_mfma_f32_16x16x32_bf16 v[116:119], v[150:153], v[176:179], v[116:119]
	v_mfma_f32_16x16x32_bf16 v[112:115], v[160:163], v[176:179], v[112:115]
	v_mfma_f32_16x16x32_bf16 v[100:103], v[150:153], v[184:187], v[100:103]
	v_mfma_f32_16x16x32_bf16 v[96:99], v[160:163], v[184:187], v[96:99]
	v_mfma_f32_16x16x32_bf16 v[84:87], v[150:153], v[192:195], v[84:87]
	v_mfma_f32_16x16x32_bf16 v[80:83], v[160:163], v[192:195], v[80:83]
	v_mfma_f32_16x16x32_bf16 v[124:127], v[156:159], v[172:175], v[124:127]
	v_mfma_f32_16x16x32_bf16 v[120:123], v[164:167], v[172:175], v[120:123]
	v_mfma_f32_16x16x32_bf16 v[116:119], v[156:159], v[180:183], v[116:119]
	v_mfma_f32_16x16x32_bf16 v[112:115], v[164:167], v[180:183], v[112:115]
	v_mfma_f32_16x16x32_bf16 v[100:103], v[156:159], v[188:191], v[100:103]
	v_mfma_f32_16x16x32_bf16 v[96:99], v[164:167], v[188:191], v[96:99]
	v_mfma_f32_16x16x32_bf16 v[84:87], v[156:159], v[196:199], v[84:87]
	v_mfma_f32_16x16x32_bf16 v[80:83], v[164:167], v[196:199], v[80:83]
	s_barrier
	s_add_i32 s83, s74, s1
	v_lshl_add_u64 v[216:217], s[90:91], 0, v[132:133]
	s_mov_b32 m0, s83
	ds_read_b128 v[200:203], v149
	ds_read_b128 v[204:207], v149 offset:1024
	ds_read_b128 v[208:211], v149 offset:2048
	ds_read_b128 v[212:215], v149 offset:3072
	global_load_lds_dwordx4 v[216:217], off
	v_lshl_add_u64 v[218:219], s[90:91], 0, v[128:129]
	s_add_i32 m0, s83, 0x2000
	s_nop 0
	global_load_lds_dwordx4 v[218:219], off
	s_barrier
	s_waitcnt lgkmcnt(0)
	s_waitcnt lgkmcnt(0)
	v_mfma_f32_16x16x32_bf16 v[108:111], v[200:203], v[168:171], v[108:111]
	v_mfma_f32_16x16x32_bf16 v[104:107], v[208:211], v[168:171], v[104:107]
	v_mfma_f32_16x16x32_bf16 v[92:95], v[200:203], v[176:179], v[92:95]
	v_mfma_f32_16x16x32_bf16 v[88:91], v[208:211], v[176:179], v[88:91]
	v_mfma_f32_16x16x32_bf16 v[76:79], v[200:203], v[184:187], v[76:79]
	v_mfma_f32_16x16x32_bf16 v[72:75], v[208:211], v[184:187], v[72:75]
	v_mfma_f32_16x16x32_bf16 v[68:71], v[200:203], v[192:195], v[68:71]
	v_mfma_f32_16x16x32_bf16 v[64:67], v[208:211], v[192:195], v[64:67]
	v_mfma_f32_16x16x32_bf16 v[108:111], v[204:207], v[172:175], v[108:111]
	v_mfma_f32_16x16x32_bf16 v[104:107], v[212:215], v[172:175], v[104:107]
	v_mfma_f32_16x16x32_bf16 v[92:95], v[204:207], v[180:183], v[92:95]
	v_mfma_f32_16x16x32_bf16 v[88:91], v[212:215], v[180:183], v[88:91]
	v_mfma_f32_16x16x32_bf16 v[76:79], v[204:207], v[188:191], v[76:79]
	v_mfma_f32_16x16x32_bf16 v[72:75], v[212:215], v[188:191], v[72:75]
	v_mfma_f32_16x16x32_bf16 v[68:71], v[204:207], v[196:199], v[68:71]
	v_mfma_f32_16x16x32_bf16 v[64:67], v[212:215], v[196:199], v[64:67]
	s_mov_b32 m0, s9
	v_lshl_add_u64 v[220:221], s[92:93], 0, v[134:135]
	s_barrier
	ds_read_b128 v[168:171], v148 offset:16384
	ds_read_b128 v[172:175], v148 offset:17408
	ds_read_b128 v[176:179], v148 offset:18432
	ds_read_b128 v[180:183], v148 offset:19456
	ds_read_b128 v[184:187], v148 offset:20480
	ds_read_b128 v[188:191], v148 offset:21504
	ds_read_b128 v[192:195], v148 offset:22528
	ds_read_b128 v[196:199], v148 offset:23552
	global_load_lds_dwordx4 v[220:221], off
	v_lshl_add_u64 v[222:223], s[92:93], 0, v[130:131]
	s_mov_b32 m0, s35
	s_nop 0
	global_load_lds_dwordx4 v[222:223], off
	s_barrier
	s_waitcnt lgkmcnt(0)
	s_waitcnt lgkmcnt(0)
	v_mfma_f32_16x16x32_bf16 v[60:63], v[150:153], v[168:171], v[60:63]
	v_mfma_f32_16x16x32_bf16 v[56:59], v[160:163], v[168:171], v[56:59]
	v_mfma_f32_16x16x32_bf16 v[52:55], v[150:153], v[176:179], v[52:55]
	v_mfma_f32_16x16x32_bf16 v[48:51], v[160:163], v[176:179], v[48:51]
	v_mfma_f32_16x16x32_bf16 v[36:39], v[150:153], v[184:187], v[36:39]
	v_mfma_f32_16x16x32_bf16 v[32:35], v[160:163], v[184:187], v[32:35]
	v_mfma_f32_16x16x32_bf16 v[20:23], v[150:153], v[192:195], v[20:23]
	v_mfma_f32_16x16x32_bf16 v[16:19], v[160:163], v[192:195], v[16:19]
	v_mfma_f32_16x16x32_bf16 v[60:63], v[156:159], v[172:175], v[60:63]
	v_mfma_f32_16x16x32_bf16 v[56:59], v[164:167], v[172:175], v[56:59]
	v_mfma_f32_16x16x32_bf16 v[52:55], v[156:159], v[180:183], v[52:55]
	v_mfma_f32_16x16x32_bf16 v[48:51], v[164:167], v[180:183], v[48:51]
	v_mfma_f32_16x16x32_bf16 v[36:39], v[156:159], v[188:191], v[36:39]
	v_mfma_f32_16x16x32_bf16 v[32:35], v[164:167], v[188:191], v[32:35]
	v_mfma_f32_16x16x32_bf16 v[20:23], v[156:159], v[196:199], v[20:23]
	v_mfma_f32_16x16x32_bf16 v[16:19], v[164:167], v[196:199], v[16:19]
	s_barrier
	s_add_u32 s94, s90, 0x40000
	s_addc_u32 s95, s91, 0
	s_add_i32 s83, s75, s1
	v_lshl_add_u64 v[150:151], s[94:95], 0, v[132:133]
	s_mov_b32 m0, s83
	s_nop 0
	global_load_lds_dwordx4 v[150:151], off
	v_lshl_add_u64 v[150:151], s[94:95], 0, v[128:129]
	s_add_i32 m0, s83, 0x2000
	s_nop 0
	global_load_lds_dwordx4 v[150:151], off
	s_waitcnt vmcnt(6)
	s_barrier
	v_mfma_f32_16x16x32_bf16 v[44:47], v[200:203], v[168:171], v[44:47]
	v_mfma_f32_16x16x32_bf16 v[40:43], v[208:211], v[168:171], v[40:43]
	v_mfma_f32_16x16x32_bf16 v[28:31], v[200:203], v[176:179], v[28:31]
	v_mfma_f32_16x16x32_bf16 v[24:27], v[208:211], v[176:179], v[24:27]
	v_mfma_f32_16x16x32_bf16 v[12:15], v[200:203], v[184:187], v[12:15]
	v_mfma_f32_16x16x32_bf16 v[8:11], v[208:211], v[184:187], v[8:11]
	v_mfma_f32_16x16x32_bf16 v[4:7], v[200:203], v[192:195], v[4:7]
	v_mfma_f32_16x16x32_bf16 v[0:3], v[208:211], v[192:195], v[0:3]
	v_mfma_f32_16x16x32_bf16 v[44:47], v[204:207], v[172:175], v[44:47]
	v_mfma_f32_16x16x32_bf16 v[40:43], v[212:215], v[172:175], v[40:43]
	v_mfma_f32_16x16x32_bf16 v[28:31], v[204:207], v[180:183], v[28:31]
	v_mfma_f32_16x16x32_bf16 v[24:27], v[212:215], v[180:183], v[24:27]
	v_mfma_f32_16x16x32_bf16 v[12:15], v[204:207], v[188:191], v[12:15]
	v_mfma_f32_16x16x32_bf16 v[8:11], v[212:215], v[188:191], v[8:11]
	v_mfma_f32_16x16x32_bf16 v[4:7], v[204:207], v[196:199], v[4:7]
	v_mfma_f32_16x16x32_bf16 v[0:3], v[212:215], v[196:199], v[0:3]
	s_add_i32 s83, 0, 0x18000
	v_add_u32_e32 v164, s83, v145
	s_barrier
	ds_read_b128 v[150:153], v164
	ds_read_b128 v[156:159], v164 offset:1024
	ds_read_b128 v[160:163], v164 offset:2048
	ds_read_b128 v[164:167], v164 offset:3072
	s_add_u32 s92, s92, 0x40000
	s_addc_u32 s93, s93, 0
	s_mov_b32 m0, s68
	v_lshl_add_u64 v[200:201], s[92:93], 0, v[134:135]
	ds_read_b128 v[168:171], v148 offset:32768
	ds_read_b128 v[172:175], v148 offset:33792
	ds_read_b128 v[176:179], v148 offset:34816
	ds_read_b128 v[180:183], v148 offset:35840
	ds_read_b128 v[184:187], v148 offset:36864
	ds_read_b128 v[188:191], v148 offset:37888
	ds_read_b128 v[192:195], v148 offset:38912
	ds_read_b128 v[196:199], v148 offset:39936
	global_load_lds_dwordx4 v[200:201], off
	v_lshl_add_u64 v[200:201], s[92:93], 0, v[130:131]
	s_mov_b32 m0, s69
	s_nop 0
	global_load_lds_dwordx4 v[200:201], off
	s_waitcnt lgkmcnt(8)
	s_barrier
	s_waitcnt lgkmcnt(0)
	s_waitcnt lgkmcnt(0)
	v_mfma_f32_16x16x32_bf16 v[124:127], v[150:153], v[168:171], v[124:127]
	v_mfma_f32_16x16x32_bf16 v[120:123], v[160:163], v[168:171], v[120:123]
	v_mfma_f32_16x16x32_bf16 v[116:119], v[150:153], v[176:179], v[116:119]
	v_mfma_f32_16x16x32_bf16 v[112:115], v[160:163], v[176:179], v[112:115]
	v_mfma_f32_16x16x32_bf16 v[100:103], v[150:153], v[184:187], v[100:103]
	v_mfma_f32_16x16x32_bf16 v[96:99], v[160:163], v[184:187], v[96:99]
	v_mfma_f32_16x16x32_bf16 v[84:87], v[150:153], v[192:195], v[84:87]
	v_mfma_f32_16x16x32_bf16 v[80:83], v[160:163], v[192:195], v[80:83]
	v_mfma_f32_16x16x32_bf16 v[124:127], v[156:159], v[172:175], v[124:127]
	v_mfma_f32_16x16x32_bf16 v[120:123], v[164:167], v[172:175], v[120:123]
	v_mfma_f32_16x16x32_bf16 v[116:119], v[156:159], v[180:183], v[116:119]
	v_mfma_f32_16x16x32_bf16 v[112:115], v[164:167], v[180:183], v[112:115]
	v_mfma_f32_16x16x32_bf16 v[100:103], v[156:159], v[188:191], v[100:103]
	v_mfma_f32_16x16x32_bf16 v[96:99], v[164:167], v[188:191], v[96:99]
	v_mfma_f32_16x16x32_bf16 v[84:87], v[156:159], v[196:199], v[84:87]
	v_mfma_f32_16x16x32_bf16 v[80:83], v[164:167], v[196:199], v[80:83]
	s_barrier
	s_add_i32 s92, 0, 0x1c000
	s_add_i32 s83, s83, s1
	v_add_u32_e32 v212, s92, v145
	v_lshl_add_u64 v[216:217], v[216:217], 0, s[6:7]
	s_mov_b32 m0, s83
	ds_read_b128 v[200:203], v212
	ds_read_b128 v[204:207], v212 offset:1024
	ds_read_b128 v[208:211], v212 offset:2048
	ds_read_b128 v[212:215], v212 offset:3072
	global_load_lds_dwordx4 v[216:217], off
	v_lshl_add_u64 v[216:217], v[218:219], 0, s[6:7]
	s_add_i32 m0, s83, 0x2000
	s_nop 0
	global_load_lds_dwordx4 v[216:217], off
	s_barrier
	s_waitcnt lgkmcnt(0)
	s_waitcnt lgkmcnt(0)
	v_mfma_f32_16x16x32_bf16 v[108:111], v[200:203], v[168:171], v[108:111]
	v_mfma_f32_16x16x32_bf16 v[104:107], v[208:211], v[168:171], v[104:107]
	v_mfma_f32_16x16x32_bf16 v[92:95], v[200:203], v[176:179], v[92:95]
	v_mfma_f32_16x16x32_bf16 v[88:91], v[208:211], v[176:179], v[88:91]
	v_mfma_f32_16x16x32_bf16 v[76:79], v[200:203], v[184:187], v[76:79]
	v_mfma_f32_16x16x32_bf16 v[72:75], v[208:211], v[184:187], v[72:75]
	v_mfma_f32_16x16x32_bf16 v[68:71], v[200:203], v[192:195], v[68:71]
	v_mfma_f32_16x16x32_bf16 v[64:67], v[208:211], v[192:195], v[64:67]
	v_mfma_f32_16x16x32_bf16 v[108:111], v[204:207], v[172:175], v[108:111]
	v_mfma_f32_16x16x32_bf16 v[104:107], v[212:215], v[172:175], v[104:107]
	v_mfma_f32_16x16x32_bf16 v[92:95], v[204:207], v[180:183], v[92:95]
	v_mfma_f32_16x16x32_bf16 v[88:91], v[212:215], v[180:183], v[88:91]
	v_mfma_f32_16x16x32_bf16 v[76:79], v[204:207], v[188:191], v[76:79]
	v_mfma_f32_16x16x32_bf16 v[72:75], v[212:215], v[188:191], v[72:75]
	v_mfma_f32_16x16x32_bf16 v[68:71], v[204:207], v[196:199], v[68:71]
	v_mfma_f32_16x16x32_bf16 v[64:67], v[212:215], v[196:199], v[64:67]
	s_mov_b32 m0, s71
	v_lshl_add_u64 v[216:217], v[220:221], 0, s[6:7]
	s_barrier
	ds_read_b128 v[168:171], v148 offset:49152
	ds_read_b128 v[172:175], v148 offset:50176
	ds_read_b128 v[176:179], v148 offset:51200
	ds_read_b128 v[180:183], v148 offset:52224
	ds_read_b128 v[184:187], v148 offset:53248
	ds_read_b128 v[188:191], v148 offset:54272
	ds_read_b128 v[192:195], v148 offset:55296
	ds_read_b128 v[196:199], v148 offset:56320
	global_load_lds_dwordx4 v[216:217], off
	v_lshl_add_u64 v[216:217], v[222:223], 0, s[6:7]
	s_mov_b32 m0, s72
	s_nop 0
	global_load_lds_dwordx4 v[216:217], off
	s_barrier
	s_waitcnt lgkmcnt(0)
	s_waitcnt lgkmcnt(0)
	v_mfma_f32_16x16x32_bf16 v[60:63], v[150:153], v[168:171], v[60:63]
	v_mfma_f32_16x16x32_bf16 v[56:59], v[160:163], v[168:171], v[56:59]
	v_mfma_f32_16x16x32_bf16 v[52:55], v[150:153], v[176:179], v[52:55]
	v_mfma_f32_16x16x32_bf16 v[48:51], v[160:163], v[176:179], v[48:51]
	v_mfma_f32_16x16x32_bf16 v[36:39], v[150:153], v[184:187], v[36:39]
	v_mfma_f32_16x16x32_bf16 v[32:35], v[160:163], v[184:187], v[32:35]
	v_mfma_f32_16x16x32_bf16 v[20:23], v[150:153], v[192:195], v[20:23]
	v_mfma_f32_16x16x32_bf16 v[16:19], v[160:163], v[192:195], v[16:19]
	v_mfma_f32_16x16x32_bf16 v[60:63], v[156:159], v[172:175], v[60:63]
	v_mfma_f32_16x16x32_bf16 v[56:59], v[164:167], v[172:175], v[56:59]
	v_mfma_f32_16x16x32_bf16 v[52:55], v[156:159], v[180:183], v[52:55]
	v_mfma_f32_16x16x32_bf16 v[48:51], v[164:167], v[180:183], v[48:51]
	v_mfma_f32_16x16x32_bf16 v[36:39], v[156:159], v[188:191], v[36:39]
	v_mfma_f32_16x16x32_bf16 v[32:35], v[164:167], v[188:191], v[32:35]
	v_mfma_f32_16x16x32_bf16 v[20:23], v[156:159], v[196:199], v[20:23]
	v_mfma_f32_16x16x32_bf16 v[16:19], v[164:167], v[196:199], v[16:19]
	s_barrier
	s_add_u32 s90, s90, 0x40080
	s_addc_u32 s91, s91, 0
	s_add_i32 s83, s92, s1
	v_lshl_add_u64 v[150:151], s[90:91], 0, v[132:133]
	s_mov_b32 m0, s83
	s_nop 0
	global_load_lds_dwordx4 v[150:151], off
	v_lshl_add_u64 v[150:151], s[90:91], 0, v[128:129]
	s_add_i32 m0, s83, 0x2000
	s_nop 0
	global_load_lds_dwordx4 v[150:151], off
	s_waitcnt vmcnt(6)
	s_barrier
	v_mfma_f32_16x16x32_bf16 v[44:47], v[200:203], v[168:171], v[44:47]
	v_mfma_f32_16x16x32_bf16 v[40:43], v[208:211], v[168:171], v[40:43]
	v_mfma_f32_16x16x32_bf16 v[28:31], v[200:203], v[176:179], v[28:31]
	v_mfma_f32_16x16x32_bf16 v[24:27], v[208:211], v[176:179], v[24:27]
	v_mfma_f32_16x16x32_bf16 v[12:15], v[200:203], v[184:187], v[12:15]
	v_mfma_f32_16x16x32_bf16 v[8:11], v[208:211], v[184:187], v[8:11]
	v_mfma_f32_16x16x32_bf16 v[4:7], v[200:203], v[192:195], v[4:7]
	v_mfma_f32_16x16x32_bf16 v[0:3], v[208:211], v[192:195], v[0:3]
	v_mfma_f32_16x16x32_bf16 v[44:47], v[204:207], v[172:175], v[44:47]
	v_mfma_f32_16x16x32_bf16 v[40:43], v[212:215], v[172:175], v[40:43]
	v_mfma_f32_16x16x32_bf16 v[28:31], v[204:207], v[180:183], v[28:31]
	v_mfma_f32_16x16x32_bf16 v[24:27], v[212:215], v[180:183], v[24:27]
	v_mfma_f32_16x16x32_bf16 v[12:15], v[204:207], v[188:191], v[12:15]
	v_mfma_f32_16x16x32_bf16 v[8:11], v[212:215], v[188:191], v[8:11]
	v_mfma_f32_16x16x32_bf16 v[4:7], v[204:207], v[196:199], v[4:7]
	v_mfma_f32_16x16x32_bf16 v[0:3], v[212:215], v[196:199], v[0:3]
	s_add_i32 s82, s82, 2
	s_add_u32 s88, s88, 0x100
	s_addc_u32 s89, s89, 0
	s_add_u32 s80, s80, 0x100
	s_addc_u32 s81, s81, 0
	s_cmp_gt_u32 s82, 13
	s_barrier
	s_cbranch_scc0 .LBB0_38
	v_lshl_add_u32 v152, s8, 8, v144
	v_lshl_or_b32 v150, s77, 8, v146
	v_cvt_pk_bf16_f32 v124, v124, v125
	v_cvt_pk_bf16_f32 v125, v126, v127
	v_cvt_pk_bf16_f32 v126, v120, v121
	v_mov_b64_e32 v[120:121], s[42:43]
	v_ashrrev_i32_e32 v151, 31, v150
	v_cvt_pk_bf16_f32 v68, v68, v69
	v_cvt_pk_bf16_f32 v69, v70, v71
	v_cvt_pk_bf16_f32 v70, v64, v65
	v_add_u32_e32 v64, 0x80, v152
	v_cvt_pk_bf16_f32 v127, v122, v123
	v_mad_i64_i32 v[122:123], s[78:79], v152, s76, v[120:121]
	v_lshlrev_b64 v[150:151], 1, v[150:151]
	v_cvt_pk_bf16_f32 v60, v60, v61
	v_cvt_pk_bf16_f32 v61, v62, v63
	v_cvt_pk_bf16_f32 v62, v56, v57
	v_mad_i64_i32 v[56:57], s[78:79], v64, s76, v[120:121]
	v_lshl_add_u64 v[122:123], v[122:123], 0, v[150:151]
	v_cvt_pk_bf16_f32 v108, v108, v109
	v_cvt_pk_bf16_f32 v109, v110, v111
	v_cvt_pk_bf16_f32 v110, v104, v105
	v_cvt_pk_bf16_f32 v111, v106, v107
	v_lshl_add_u64 v[56:57], v[56:57], 0, v[150:151]
	v_cvt_pk_bf16_f32 v44, v44, v45
	v_cvt_pk_bf16_f32 v45, v46, v47
	v_cvt_pk_bf16_f32 v46, v40, v41
	v_cvt_pk_bf16_f32 v47, v42, v43
	global_store_dwordx4 v[122:123], v[108:111], off offset:256
	global_store_dwordx4 v[56:57], v[44:47], off offset:256
	v_cvt_pk_bf16_f32 v92, v92, v93
	v_or_b32_e32 v108, 16, v152
	v_add_u32_e32 v44, 0x90, v152
	v_mad_i64_i32 v[108:109], s[78:79], v108, s76, v[120:121]
	v_mad_i64_i32 v[44:45], s[78:79], v44, s76, v[120:121]
	v_lshl_add_u64 v[108:109], v[108:109], 0, v[150:151]
	v_cvt_pk_bf16_f32 v93, v94, v95
	v_cvt_pk_bf16_f32 v94, v88, v89
	v_cvt_pk_bf16_f32 v95, v90, v91
	v_lshl_add_u64 v[44:45], v[44:45], 0, v[150:151]
	v_cvt_pk_bf16_f32 v28, v28, v29
	v_cvt_pk_bf16_f32 v29, v30, v31
	v_cvt_pk_bf16_f32 v30, v24, v25
	v_cvt_pk_bf16_f32 v31, v26, v27
	global_store_dwordx4 v[108:109], v[92:95], off offset:256
	global_store_dwordx4 v[44:45], v[28:31], off offset:256
	v_cvt_pk_bf16_f32 v76, v76, v77
	v_or_b32_e32 v92, 32, v152
	v_add_u32_e32 v28, 0xa0, v152
	v_mad_i64_i32 v[92:93], s[78:79], v92, s76, v[120:121]
	v_mad_i64_i32 v[28:29], s[78:79], v28, s76, v[120:121]
	v_lshl_add_u64 v[92:93], v[92:93], 0, v[150:151]
	v_cvt_pk_bf16_f32 v77, v78, v79
	v_cvt_pk_bf16_f32 v78, v72, v73
	v_cvt_pk_bf16_f32 v79, v74, v75
	v_lshl_add_u64 v[28:29], v[28:29], 0, v[150:151]
	v_cvt_pk_bf16_f32 v12, v12, v13
	v_cvt_pk_bf16_f32 v13, v14, v15
	v_cvt_pk_bf16_f32 v14, v8, v9
	v_cvt_pk_bf16_f32 v15, v10, v11
	global_store_dwordx4 v[92:93], v[76:79], off offset:256
	global_store_dwordx4 v[28:29], v[12:15], off offset:256
	v_cvt_pk_bf16_f32 v104, v116, v117
	v_or_b32_e32 v76, 48, v152
	v_add_u32_e32 v12, 0xb0, v152
	v_mad_i64_i32 v[76:77], s[78:79], v76, s76, v[120:121]
	v_mad_i64_i32 v[12:13], s[78:79], v12, s76, v[120:121]
	v_cvt_pk_bf16_f32 v105, v118, v119
	v_cvt_pk_bf16_f32 v106, v112, v113
	v_cvt_pk_bf16_f32 v107, v114, v115
	v_cvt_pk_bf16_f32 v88, v100, v101
	v_cvt_pk_bf16_f32 v89, v102, v103
	v_cvt_pk_bf16_f32 v90, v96, v97
	v_cvt_pk_bf16_f32 v91, v98, v99
	v_cvt_pk_bf16_f32 v72, v84, v85
	v_cvt_pk_bf16_f32 v73, v86, v87
	v_cvt_pk_bf16_f32 v74, v80, v81
	v_cvt_pk_bf16_f32 v75, v82, v83
	v_lshl_add_u64 v[76:77], v[76:77], 0, v[150:151]
	v_cvt_pk_bf16_f32 v71, v66, v67
	v_cvt_pk_bf16_f32 v63, v58, v59
	v_cvt_pk_bf16_f32 v40, v52, v53
	v_cvt_pk_bf16_f32 v41, v54, v55
	v_cvt_pk_bf16_f32 v42, v48, v49
	v_cvt_pk_bf16_f32 v43, v50, v51
	v_cvt_pk_bf16_f32 v24, v36, v37
	v_cvt_pk_bf16_f32 v25, v38, v39
	v_cvt_pk_bf16_f32 v26, v32, v33
	v_cvt_pk_bf16_f32 v27, v34, v35
	v_cvt_pk_bf16_f32 v8, v20, v21
	v_cvt_pk_bf16_f32 v9, v22, v23
	v_cvt_pk_bf16_f32 v10, v16, v17
	v_cvt_pk_bf16_f32 v11, v18, v19
	v_lshl_add_u64 v[12:13], v[12:13], 0, v[150:151]
	v_cvt_pk_bf16_f32 v4, v4, v5
	v_cvt_pk_bf16_f32 v5, v6, v7
	v_cvt_pk_bf16_f32 v6, v0, v1
	v_cvt_pk_bf16_f32 v7, v2, v3
	s_and_b64 vcc, exec, s[4:5]
	s_mov_b32 s77, s10
	s_mov_b32 s8, s12
	s_mov_b64 s[90:91], s[86:87]
	s_mov_b64 s[88:89], s[14:15]
	global_store_dwordx4 v[122:123], v[124:127], off
	global_store_dwordx4 v[108:109], v[104:107], off
	global_store_dwordx4 v[92:93], v[88:91], off
	global_store_dwordx4 v[76:77], v[72:75], off
	global_store_dwordx4 v[76:77], v[68:71], off offset:256
	global_store_dwordx4 v[56:57], v[60:63], off
	global_store_dwordx4 v[44:45], v[40:43], off
	global_store_dwordx4 v[28:29], v[24:27], off
	global_store_dwordx4 v[12:13], v[8:11], off
	global_store_dwordx4 v[12:13], v[4:7], off offset:256
	s_cbranch_vccz .LBB0_35
	s_waitcnt vmcnt(0)
	s_cmpk_gt_u32 s0, 0xff
	v_readlane_b32 s33, v228, 32
	v_readlane_b32 s56, v228, 35
	s_cbranch_scc1 .LBB0_42
	s_barrier

.LBB0_43:
	s_waitcnt vmcnt(0) lgkmcnt(0)
	s_barrier
	s_setprio 0
	s_and_saveexec_b64 s[4:5], s[58:59]
	s_cbranch_execz .LBB0_53
	buffer_wbl2 sc1
	s_waitcnt vmcnt(0)
	s_load_dwordx2 s[6:7], s[68:69], -0x8
	s_load_dword s0, s[68:69], 0x0
	v_mov_b32_e32 v0, 0
	v_mov_b32_e32 v1, 1
	v_mov_b32_e32 v3, 0
	s_mov_b64 s[8:9], 0
	s_waitcnt lgkmcnt(0)
	s_add_u32 s6, s6, 0x2300080
	s_addc_u32 s7, s7, 0
	s_mul_i32 s0, s0, 1
	global_atomic_add v0, v1, s[6:7]

.LBB0_460:
	s_barrier
	s_setprio 0
	s_and_saveexec_b64 s[4:5], s[80:81]
	s_cbranch_execz .LBB0_470
	buffer_wbl2 sc1
	s_waitcnt vmcnt(0)
	s_load_dwordx2 s[6:7], s[78:79], -0x8
	s_load_dword s0, s[78:79], 0x0
	v_mov_b32_e32 v0, 0
	v_mov_b32_e32 v1, 1
	v_mov_b32_e32 v3, 0
	s_mov_b64 s[14:15], 0
	s_waitcnt lgkmcnt(0)
	s_add_u32 s6, s6, 0x2300080
	s_addc_u32 s7, s7, 0
	s_mul_i32 s0, s0, 2
	global_atomic_add v0, v1, s[6:7]

.LBB0_517:
	s_or_b64 exec, exec, s[14:15]
	s_barrier
	s_setprio 0
	s_and_saveexec_b64 s[4:5], s[80:81]
	s_cbranch_execz .LBB0_527
	buffer_wbl2 sc1
	s_waitcnt vmcnt(0)
	s_load_dwordx2 s[6:7], s[78:79], -0x8
	s_load_dword s0, s[78:79], 0x0
	v_mov_b32_e32 v0, 0
	v_mov_b32_e32 v1, 1
	v_mov_b32_e32 v3, 0
	s_mov_b64 s[14:15], 0
	s_waitcnt lgkmcnt(0)
	s_add_u32 s6, s6, 0x2300080
	s_addc_u32 s7, s7, 0
	s_mul_i32 s0, s0, 3
	global_atomic_add v0, v1, s[6:7]

.LBB0_543:
	s_lshl_b32 s6, s6, 5
	s_and_b32 s25, s6, 0x60
	s_mov_b64 s[6:7], 0x80
	s_add_i32 m0, s51, 0x18000
	v_lshl_add_u64 v[6:7], v[6:7], 0, s[6:7]
	s_lshl_b32 s24, s5, 13
	s_lshl_b32 s40, s25, 7
	s_waitcnt vmcnt(4)
	s_barrier
	global_load_lds_dwordx4 v[6:7], off
	v_lshl_add_u64 v[4:5], v[4:5], 0, s[6:7]
	s_add_i32 m0, s51, 0x1a000
	s_add_i32 s76, s51, 0x8000
	s_add_i32 s77, s51, 0xa000
	global_load_lds_dwordx4 v[4:5], off
	v_lshl_add_u64 v[2:3], v[2:3], 0, s[6:7]
	s_mov_b32 m0, s76
	s_add_u32 s14, s52, 0x10080
	global_load_lds_dwordx4 v[2:3], off
	v_lshl_add_u64 v[0:1], v[0:1], 0, s[6:7]
	s_mov_b32 m0, s77
	s_addc_u32 s15, s53, 0
	global_load_lds_dwordx4 v[0:1], off
	s_add_i32 m0, s51, 0x1c000
	v_lshl_add_u64 v[0:1], s[14:15], 0, v[132:133]
	global_load_lds_dwordx4 v[0:1], off
	v_lshl_add_u64 v[0:1], s[14:15], 0, v[128:129]
	s_add_i32 m0, s51, 0x1e000
	s_add_i32 s79, 0, 0x10000
	global_load_lds_dwordx4 v[0:1], off
	v_lshrrev_b32_e32 v1, 1, v8
	v_and_b32_e32 v1, 24, v1
	v_and_b32_e32 v0, 15, v8
	v_lshlrev_b32_e32 v2, 1, v1
	v_lshl_or_b32 v146, s5, 6, v0
	v_lshl_or_b32 v0, v0, 6, v2
	v_lshlrev_b32_e32 v2, 2, v8
	v_and_b32_e32 v2, 32, v2
	s_waitcnt vmcnt(6)
	v_bitop3_b32 v3, v0, s24, v2 bitop3:0xde
	v_bitop3_b32 v147, v0, s40, v2 bitop3:0xde
	s_sext_i32_i8 s81, s4
	s_ashr_i32 s78, s3, 31
	v_or_b32_e32 v148, s25, v1
	v_mov_b64_e32 v[136:137], 0x600
	v_mov_b64_e32 v[138:139], 0x5ff
	v_add_u32_e32 v149, s79, v147
	v_add_u32_e32 v150, 0, v3
	v_add_u32_e32 v151, s72, v147
	s_mov_b64 s[14:15], 0x58000
	s_mov_b32 s80, 0x58000
	s_barrier
	v_readfirstlane_b32 s4, v154
	s_bitcmp1_b32 s4, 8
	s_cbranch_scc0 .Lprio_544
	s_setprio 1
.Lprio_544:
.LBB0_544:
	s_add_i32 s75, s75, 1
	s_mul_i32 s4, s75, s78
	s_mul_hi_u32 s5, s75, s3
	s_add_i32 s5, s5, s4
	s_mul_i32 s4, s75, s3
	s_add_u32 s46, s4, s2
	s_addc_u32 s47, s5, s35
	v_cmp_gt_i64_e64 s[4:5], s[46:47], v[138:139]
	s_and_b64 vcc, exec, s[4:5]
	s_cbranch_vccnz .LBB0_546
	s_ashr_i32 s24, s46, 31
	s_lshr_b32 s24, s24, 29
	s_add_i32 s24, s46, s24
	s_ashr_i32 s25, s24, 3
	s_and_b32 s24, s24, -8
	s_sub_i32 s24, s46, s24
	s_cmp_lt_i32 s24, 0
	s_cselect_b32 s40, s70, 0xc0
	s_mul_i32 s24, s40, s24
	s_add_i32 s24, s24, s25
	s_ashr_i32 s25, s24, 31
	s_lshr_b32 s25, s25, 27
	s_add_i32 s25, s24, s25
	s_ashr_i32 s40, s25, 5
	s_lshl_b32 s40, s40, 3
	s_sub_i32 s41, 0x180, s40
	s_min_i32 s41, s41, 8
	s_abs_i32 s48, s41
	v_cvt_f32_u32_e32 v0, s48
	s_sub_i32 s56, 0, s48
	s_andn2_b32 s25, s25, 31
	s_sub_i32 s25, s24, s25
	v_rcp_iflag_f32_e32 v0, v0
	s_abs_i32 s24, s25
	s_xor_b32 s49, s25, s41
	s_ashr_i32 s49, s49, 31
	v_mul_f32_e32 v0, 0x4f7ffffe, v0
	v_cvt_u32_f32_e32 v0, v0
	s_nop 0
	v_readfirstlane_b32 s57, v0
	s_mul_i32 s56, s56, s57
	s_mul_hi_u32 s56, s57, s56
	s_add_i32 s57, s57, s56
	s_mul_hi_u32 s56, s24, s57
	s_mul_i32 s57, s56, s48
	s_sub_i32 s24, s24, s57
	s_add_i32 s58, s56, 1
	s_sub_i32 s57, s24, s48
	s_cmp_ge_u32 s24, s48
	s_cselect_b32 s56, s58, s56
	s_cselect_b32 s24, s57, s24
	s_add_i32 s57, s56, 1
	s_cmp_ge_u32 s24, s48
	s_cselect_b32 s24, s57, s56
	s_xor_b32 s24, s24, s49
	s_sub_i32 s24, s24, s49
	s_mul_i32 s41, s24, s41
	s_sub_i32 s25, s25, s41
	s_add_i32 s40, s25, s40

.LBB0_547:
	s_add_u32 s68, s54, s60
	s_addc_u32 s69, s55, s61
	s_add_u32 s64, s68, 0x100
	s_addc_u32 s65, s69, 0
	s_and_b64 s[62:63], s[58:59], exec
	s_cselect_b32 s65, s41, s65
	s_cselect_b32 s64, s82, s64
	s_add_u32 s60, s52, s60
	s_addc_u32 s61, s53, s61
	s_add_u32 s60, s60, 0x100
	s_addc_u32 s61, s61, 0
	s_and_b64 s[58:59], s[58:59], exec
	s_cselect_b32 s67, s25, s61
	s_cselect_b32 s66, s83, s60
	s_add_u32 s68, s68, 0x10080
	s_addc_u32 s69, s69, 0
	s_add_i32 s94, s79, s1
	s_add_i32 m0, s51, 0xc000
	s_add_i32 s95, s51, 0xe000
	s_add_i32 s93, s94, 0x2000
	s_add_u32 s62, s66, 0x10000
	s_addc_u32 s63, s67, 0
	s_add_i32 s92, s72, s1
	ds_read_b128 v[140:143], v149
	ds_read_b128 v[156:159], v149 offset:1024
	ds_read_b128 v[160:163], v149 offset:2048
	ds_read_b128 v[164:167], v149 offset:3072
	s_add_i32 s91, s92, 0x2000
	s_add_i32 s90, 0, 0x18000
	s_add_u32 s60, s64, 0x10000
	s_addc_u32 s61, s65, 0
	s_add_i32 s89, s90, s1
	s_add_i32 s88, s89, 0x2000
	s_add_u32 s58, s66, 0x10080
	s_addc_u32 s59, s67, 0
	s_add_i32 s87, s97, s1
	s_add_i32 s86, s87, 0x2000
	v_lshl_add_u64 v[144:145], s[68:69], 0, v[134:135]
	ds_read_b128 v[168:171], v150
	ds_read_b128 v[172:175], v150 offset:1024
	ds_read_b128 v[176:179], v150 offset:2048
	ds_read_b128 v[180:183], v150 offset:3072
	ds_read_b128 v[184:187], v150 offset:4096
	ds_read_b128 v[188:191], v150 offset:5120
	ds_read_b128 v[192:195], v150 offset:6144
	ds_read_b128 v[196:199], v150 offset:7168
	global_load_lds_dwordx4 v[144:145], off
	v_lshl_add_u64 v[144:145], s[68:69], 0, v[130:131]
	s_mov_b32 m0, s95
	s_nop 0
	global_load_lds_dwordx4 v[144:145], off
	s_waitcnt lgkmcnt(8)
	s_barrier
	s_waitcnt lgkmcnt(0)
	s_waitcnt lgkmcnt(0)
	v_mfma_f32_16x16x32_bf16 v[124:127], v[140:143], v[168:171], v[124:127]
	v_mfma_f32_16x16x32_bf16 v[120:123], v[160:163], v[168:171], v[120:123]
	v_mfma_f32_16x16x32_bf16 v[112:115], v[140:143], v[176:179], v[112:115]
	v_mfma_f32_16x16x32_bf16 v[104:107], v[160:163], v[176:179], v[104:107]
	v_mfma_f32_16x16x32_bf16 v[92:95], v[140:143], v[184:187], v[92:95]
	v_mfma_f32_16x16x32_bf16 v[88:91], v[160:163], v[184:187], v[88:91]
	v_mfma_f32_16x16x32_bf16 v[80:83], v[140:143], v[192:195], v[80:83]
	v_mfma_f32_16x16x32_bf16 v[72:75], v[160:163], v[192:195], v[72:75]
	v_mfma_f32_16x16x32_bf16 v[124:127], v[156:159], v[172:175], v[124:127]
	v_mfma_f32_16x16x32_bf16 v[120:123], v[164:167], v[172:175], v[120:123]
	v_mfma_f32_16x16x32_bf16 v[112:115], v[156:159], v[180:183], v[112:115]
	v_mfma_f32_16x16x32_bf16 v[104:107], v[164:167], v[180:183], v[104:107]
	v_mfma_f32_16x16x32_bf16 v[92:95], v[156:159], v[188:191], v[92:95]
	v_mfma_f32_16x16x32_bf16 v[88:91], v[164:167], v[188:191], v[88:91]
	v_mfma_f32_16x16x32_bf16 v[80:83], v[156:159], v[196:199], v[80:83]
	v_mfma_f32_16x16x32_bf16 v[72:75], v[164:167], v[196:199], v[72:75]
	s_barrier
	s_mov_b32 m0, s94
	v_lshl_add_u64 v[144:145], s[66:67], 0, v[132:133]
	ds_read_b128 v[200:203], v151
	ds_read_b128 v[204:207], v151 offset:1024
	ds_read_b128 v[208:211], v151 offset:2048
	ds_read_b128 v[212:215], v151 offset:3072
	global_load_lds_dwordx4 v[144:145], off
	v_lshl_add_u64 v[152:153], s[66:67], 0, v[128:129]
	s_mov_b32 m0, s93
	s_nop 0
	global_load_lds_dwordx4 v[152:153], off
	s_barrier
	s_waitcnt lgkmcnt(0)
	s_waitcnt lgkmcnt(0)
	v_mfma_f32_16x16x32_bf16 v[116:119], v[200:203], v[168:171], v[116:119]
	v_mfma_f32_16x16x32_bf16 v[108:111], v[208:211], v[168:171], v[108:111]
	v_mfma_f32_16x16x32_bf16 v[100:103], v[200:203], v[176:179], v[100:103]
	v_mfma_f32_16x16x32_bf16 v[96:99], v[208:211], v[176:179], v[96:99]
	v_mfma_f32_16x16x32_bf16 v[84:87], v[200:203], v[184:187], v[84:87]
	v_mfma_f32_16x16x32_bf16 v[76:79], v[208:211], v[184:187], v[76:79]
	v_mfma_f32_16x16x32_bf16 v[68:71], v[200:203], v[192:195], v[68:71]
	v_mfma_f32_16x16x32_bf16 v[64:67], v[208:211], v[192:195], v[64:67]
	v_mfma_f32_16x16x32_bf16 v[116:119], v[204:207], v[172:175], v[116:119]
	v_mfma_f32_16x16x32_bf16 v[108:111], v[212:215], v[172:175], v[108:111]
	v_mfma_f32_16x16x32_bf16 v[100:103], v[204:207], v[180:183], v[100:103]
	v_mfma_f32_16x16x32_bf16 v[96:99], v[212:215], v[180:183], v[96:99]
	v_mfma_f32_16x16x32_bf16 v[84:87], v[204:207], v[188:191], v[84:87]
	v_mfma_f32_16x16x32_bf16 v[76:79], v[212:215], v[188:191], v[76:79]
	v_mfma_f32_16x16x32_bf16 v[68:71], v[204:207], v[196:199], v[68:71]
	v_mfma_f32_16x16x32_bf16 v[64:67], v[212:215], v[196:199], v[64:67]
	s_mov_b32 m0, s51
	v_lshl_add_u64 v[216:217], s[64:65], 0, v[134:135]
	s_barrier
	ds_read_b128 v[168:171], v150 offset:16384
	ds_read_b128 v[172:175], v150 offset:17408
	ds_read_b128 v[176:179], v150 offset:18432
	ds_read_b128 v[180:183], v150 offset:19456
	ds_read_b128 v[184:187], v150 offset:20480
	ds_read_b128 v[188:191], v150 offset:21504
	ds_read_b128 v[192:195], v150 offset:22528
	ds_read_b128 v[196:199], v150 offset:23552
	global_load_lds_dwordx4 v[216:217], off
	v_lshl_add_u64 v[218:219], s[64:65], 0, v[130:131]
	s_mov_b32 m0, s71
	s_nop 0
	global_load_lds_dwordx4 v[218:219], off
	s_barrier
	s_waitcnt lgkmcnt(0)
	s_waitcnt lgkmcnt(0)
	v_mfma_f32_16x16x32_bf16 v[60:63], v[140:143], v[168:171], v[60:63]
	v_mfma_f32_16x16x32_bf16 v[56:59], v[160:163], v[168:171], v[56:59]
	v_mfma_f32_16x16x32_bf16 v[52:55], v[140:143], v[176:179], v[52:55]
	v_mfma_f32_16x16x32_bf16 v[48:51], v[160:163], v[176:179], v[48:51]
	v_mfma_f32_16x16x32_bf16 v[28:31], v[140:143], v[184:187], v[28:31]
	v_mfma_f32_16x16x32_bf16 v[20:23], v[160:163], v[184:187], v[20:23]
	v_mfma_f32_16x16x32_bf16 v[24:27], v[140:143], v[192:195], v[24:27]
	v_mfma_f32_16x16x32_bf16 v[16:19], v[160:163], v[192:195], v[16:19]
	v_mfma_f32_16x16x32_bf16 v[60:63], v[156:159], v[172:175], v[60:63]
	v_mfma_f32_16x16x32_bf16 v[56:59], v[164:167], v[172:175], v[56:59]
	v_mfma_f32_16x16x32_bf16 v[52:55], v[156:159], v[180:183], v[52:55]
	v_mfma_f32_16x16x32_bf16 v[48:51], v[164:167], v[180:183], v[48:51]
	v_mfma_f32_16x16x32_bf16 v[28:31], v[156:159], v[188:191], v[28:31]
	v_mfma_f32_16x16x32_bf16 v[20:23], v[164:167], v[188:191], v[20:23]
	v_mfma_f32_16x16x32_bf16 v[24:27], v[156:159], v[196:199], v[24:27]
	v_mfma_f32_16x16x32_bf16 v[16:19], v[164:167], v[196:199], v[16:19]
	s_barrier
	s_mov_b32 m0, s92
	v_lshl_add_u64 v[140:141], s[62:63], 0, v[132:133]
	global_load_lds_dwordx4 v[140:141], off
	v_lshl_add_u64 v[140:141], s[62:63], 0, v[128:129]
	s_mov_b32 m0, s91
	s_nop 0
	global_load_lds_dwordx4 v[140:141], off
	s_waitcnt vmcnt(6)
	s_barrier
	v_mfma_f32_16x16x32_bf16 v[44:47], v[200:203], v[168:171], v[44:47]
	v_mfma_f32_16x16x32_bf16 v[40:43], v[208:211], v[168:171], v[40:43]
	v_mfma_f32_16x16x32_bf16 v[36:39], v[200:203], v[176:179], v[36:39]
	v_mfma_f32_16x16x32_bf16 v[32:35], v[208:211], v[176:179], v[32:35]
	v_mfma_f32_16x16x32_bf16 v[12:15], v[200:203], v[184:187], v[12:15]
	v_mfma_f32_16x16x32_bf16 v[4:7], v[208:211], v[184:187], v[4:7]
	v_mfma_f32_16x16x32_bf16 v[8:11], v[200:203], v[192:195], v[8:11]
	v_mfma_f32_16x16x32_bf16 v[0:3], v[208:211], v[192:195], v[0:3]
	v_mfma_f32_16x16x32_bf16 v[44:47], v[204:207], v[172:175], v[44:47]
	v_mfma_f32_16x16x32_bf16 v[40:43], v[212:215], v[172:175], v[40:43]
	v_mfma_f32_16x16x32_bf16 v[36:39], v[204:207], v[180:183], v[36:39]
	v_mfma_f32_16x16x32_bf16 v[32:35], v[212:215], v[180:183], v[32:35]
	v_mfma_f32_16x16x32_bf16 v[12:15], v[204:207], v[188:191], v[12:15]
	v_mfma_f32_16x16x32_bf16 v[4:7], v[212:215], v[188:191], v[4:7]
	v_mfma_f32_16x16x32_bf16 v[8:11], v[204:207], v[196:199], v[8:11]
	v_mfma_f32_16x16x32_bf16 v[0:3], v[212:215], v[196:199], v[0:3]
	v_add_u32_e32 v164, s90, v147
	s_barrier
	ds_read_b128 v[140:143], v164
	ds_read_b128 v[156:159], v164 offset:1024
	ds_read_b128 v[160:163], v164 offset:2048
	ds_read_b128 v[164:167], v164 offset:3072
	s_mov_b32 m0, s73
	v_lshl_add_u64 v[200:201], s[60:61], 0, v[134:135]
	ds_read_b128 v[168:171], v150 offset:32768
	ds_read_b128 v[172:175], v150 offset:33792
	ds_read_b128 v[176:179], v150 offset:34816
	ds_read_b128 v[180:183], v150 offset:35840
	ds_read_b128 v[184:187], v150 offset:36864
	ds_read_b128 v[188:191], v150 offset:37888
	ds_read_b128 v[192:195], v150 offset:38912
	ds_read_b128 v[196:199], v150 offset:39936
	global_load_lds_dwordx4 v[200:201], off
	v_lshl_add_u64 v[200:201], s[60:61], 0, v[130:131]
	s_mov_b32 m0, s74
	s_nop 0
	global_load_lds_dwordx4 v[200:201], off
	s_waitcnt lgkmcnt(8)
	s_barrier
	s_waitcnt lgkmcnt(0)
	s_waitcnt lgkmcnt(0)
	v_mfma_f32_16x16x32_bf16 v[124:127], v[140:143], v[168:171], v[124:127]
	v_mfma_f32_16x16x32_bf16 v[120:123], v[160:163], v[168:171], v[120:123]
	v_mfma_f32_16x16x32_bf16 v[112:115], v[140:143], v[176:179], v[112:115]
	v_mfma_f32_16x16x32_bf16 v[104:107], v[160:163], v[176:179], v[104:107]
	v_mfma_f32_16x16x32_bf16 v[92:95], v[140:143], v[184:187], v[92:95]
	v_mfma_f32_16x16x32_bf16 v[88:91], v[160:163], v[184:187], v[88:91]
	v_mfma_f32_16x16x32_bf16 v[80:83], v[140:143], v[192:195], v[80:83]
	v_mfma_f32_16x16x32_bf16 v[72:75], v[160:163], v[192:195], v[72:75]
	v_mfma_f32_16x16x32_bf16 v[124:127], v[156:159], v[172:175], v[124:127]
	v_mfma_f32_16x16x32_bf16 v[120:123], v[164:167], v[172:175], v[120:123]
	v_mfma_f32_16x16x32_bf16 v[112:115], v[156:159], v[180:183], v[112:115]
	v_mfma_f32_16x16x32_bf16 v[104:107], v[164:167], v[180:183], v[104:107]
	v_mfma_f32_16x16x32_bf16 v[92:95], v[156:159], v[188:191], v[92:95]
	v_mfma_f32_16x16x32_bf16 v[88:91], v[164:167], v[188:191], v[88:91]
	v_mfma_f32_16x16x32_bf16 v[80:83], v[156:159], v[196:199], v[80:83]
	v_mfma_f32_16x16x32_bf16 v[72:75], v[164:167], v[196:199], v[72:75]
	s_barrier
	s_mov_b32 m0, s89
	v_add_u32_e32 v212, s97, v147
	v_lshl_add_u64 v[144:145], v[144:145], 0, s[6:7]
	ds_read_b128 v[200:203], v212
	ds_read_b128 v[204:207], v212 offset:1024
	ds_read_b128 v[208:211], v212 offset:2048
	ds_read_b128 v[212:215], v212 offset:3072
	global_load_lds_dwordx4 v[144:145], off
	v_lshl_add_u64 v[144:145], v[152:153], 0, s[6:7]
	s_mov_b32 m0, s88
	s_nop 0
	global_load_lds_dwordx4 v[144:145], off
	s_barrier
	s_waitcnt lgkmcnt(0)
	s_waitcnt lgkmcnt(0)
	v_mfma_f32_16x16x32_bf16 v[116:119], v[200:203], v[168:171], v[116:119]
	v_mfma_f32_16x16x32_bf16 v[108:111], v[208:211], v[168:171], v[108:111]
	v_mfma_f32_16x16x32_bf16 v[100:103], v[200:203], v[176:179], v[100:103]
	v_mfma_f32_16x16x32_bf16 v[96:99], v[208:211], v[176:179], v[96:99]
	v_mfma_f32_16x16x32_bf16 v[84:87], v[200:203], v[184:187], v[84:87]
	v_mfma_f32_16x16x32_bf16 v[76:79], v[208:211], v[184:187], v[76:79]
	v_mfma_f32_16x16x32_bf16 v[68:71], v[200:203], v[192:195], v[68:71]
	v_mfma_f32_16x16x32_bf16 v[64:67], v[208:211], v[192:195], v[64:67]
	v_mfma_f32_16x16x32_bf16 v[116:119], v[204:207], v[172:175], v[116:119]
	v_mfma_f32_16x16x32_bf16 v[108:111], v[212:215], v[172:175], v[108:111]
	v_mfma_f32_16x16x32_bf16 v[100:103], v[204:207], v[180:183], v[100:103]
	v_mfma_f32_16x16x32_bf16 v[96:99], v[212:215], v[180:183], v[96:99]
	v_mfma_f32_16x16x32_bf16 v[84:87], v[204:207], v[188:191], v[84:87]
	v_mfma_f32_16x16x32_bf16 v[76:79], v[212:215], v[188:191], v[76:79]
	v_mfma_f32_16x16x32_bf16 v[68:71], v[204:207], v[196:199], v[68:71]
	v_mfma_f32_16x16x32_bf16 v[64:67], v[212:215], v[196:199], v[64:67]
	s_mov_b32 m0, s76
	v_lshl_add_u64 v[144:145], v[216:217], 0, s[6:7]
	s_barrier
	ds_read_b128 v[168:171], v150 offset:49152
	ds_read_b128 v[172:175], v150 offset:50176
	ds_read_b128 v[176:179], v150 offset:51200
	ds_read_b128 v[180:183], v150 offset:52224
	ds_read_b128 v[184:187], v150 offset:53248
	ds_read_b128 v[188:191], v150 offset:54272
	ds_read_b128 v[192:195], v150 offset:55296
	ds_read_b128 v[196:199], v150 offset:56320
	global_load_lds_dwordx4 v[144:145], off
	v_lshl_add_u64 v[144:145], v[218:219], 0, s[6:7]
	s_mov_b32 m0, s77
	s_nop 0
	global_load_lds_dwordx4 v[144:145], off
	s_barrier
	s_waitcnt lgkmcnt(0)
	s_waitcnt lgkmcnt(0)
	v_mfma_f32_16x16x32_bf16 v[60:63], v[140:143], v[168:171], v[60:63]
	v_mfma_f32_16x16x32_bf16 v[56:59], v[160:163], v[168:171], v[56:59]
	v_mfma_f32_16x16x32_bf16 v[52:55], v[140:143], v[176:179], v[52:55]
	v_mfma_f32_16x16x32_bf16 v[48:51], v[160:163], v[176:179], v[48:51]
	v_mfma_f32_16x16x32_bf16 v[28:31], v[140:143], v[184:187], v[28:31]
	v_mfma_f32_16x16x32_bf16 v[20:23], v[160:163], v[184:187], v[20:23]
	v_mfma_f32_16x16x32_bf16 v[24:27], v[140:143], v[192:195], v[24:27]
	v_mfma_f32_16x16x32_bf16 v[16:19], v[160:163], v[192:195], v[16:19]
	v_mfma_f32_16x16x32_bf16 v[60:63], v[156:159], v[172:175], v[60:63]
	v_mfma_f32_16x16x32_bf16 v[56:59], v[164:167], v[172:175], v[56:59]
	v_mfma_f32_16x16x32_bf16 v[52:55], v[156:159], v[180:183], v[52:55]
	v_mfma_f32_16x16x32_bf16 v[48:51], v[164:167], v[180:183], v[48:51]
	v_mfma_f32_16x16x32_bf16 v[28:31], v[156:159], v[188:191], v[28:31]
	v_mfma_f32_16x16x32_bf16 v[20:23], v[164:167], v[188:191], v[20:23]
	v_mfma_f32_16x16x32_bf16 v[24:27], v[156:159], v[196:199], v[24:27]
	v_mfma_f32_16x16x32_bf16 v[16:19], v[164:167], v[196:199], v[16:19]
	s_barrier
	s_mov_b32 m0, s87
	v_lshl_add_u64 v[140:141], s[58:59], 0, v[132:133]
	global_load_lds_dwordx4 v[140:141], off
	v_lshl_add_u64 v[140:141], s[58:59], 0, v[128:129]
	s_mov_b32 m0, s86
	s_nop 0
	global_load_lds_dwordx4 v[140:141], off
	s_waitcnt vmcnt(6)
	s_barrier
	v_mfma_f32_16x16x32_bf16 v[44:47], v[200:203], v[168:171], v[44:47]
	v_mfma_f32_16x16x32_bf16 v[40:43], v[208:211], v[168:171], v[40:43]
	v_mfma_f32_16x16x32_bf16 v[36:39], v[200:203], v[176:179], v[36:39]
	v_mfma_f32_16x16x32_bf16 v[32:35], v[208:211], v[176:179], v[32:35]
	v_mfma_f32_16x16x32_bf16 v[12:15], v[200:203], v[184:187], v[12:15]
	v_mfma_f32_16x16x32_bf16 v[4:7], v[208:211], v[184:187], v[4:7]
	v_mfma_f32_16x16x32_bf16 v[8:11], v[200:203], v[192:195], v[8:11]
	v_mfma_f32_16x16x32_bf16 v[0:3], v[208:211], v[192:195], v[0:3]
	v_mfma_f32_16x16x32_bf16 v[44:47], v[204:207], v[172:175], v[44:47]
	v_mfma_f32_16x16x32_bf16 v[40:43], v[212:215], v[172:175], v[40:43]
	v_mfma_f32_16x16x32_bf16 v[36:39], v[204:207], v[180:183], v[36:39]
	v_mfma_f32_16x16x32_bf16 v[32:35], v[212:215], v[180:183], v[32:35]
	v_mfma_f32_16x16x32_bf16 v[12:15], v[204:207], v[188:191], v[12:15]
	v_mfma_f32_16x16x32_bf16 v[4:7], v[212:215], v[188:191], v[4:7]
	v_mfma_f32_16x16x32_bf16 v[8:11], v[204:207], v[196:199], v[8:11]
	v_mfma_f32_16x16x32_bf16 v[0:3], v[212:215], v[196:199], v[0:3]
	s_andn2_b64 vcc, exec, s[56:57]
	s_mov_b64 s[58:59], -1
	s_mov_b64 s[56:57], 0
	s_mov_b64 s[60:61], 0x100
	s_barrier
	s_cbranch_vccz .LBB0_547
	v_lshl_add_u32 v142, s50, 8, v146
	v_lshl_or_b32 v140, s81, 8, v148
	v_ashrrev_i32_e32 v143, 31, v142
	v_lshlrev_b64 v[144:145], 11, v[142:143]
	v_ashrrev_i32_e32 v141, 31, v140
	v_lshl_add_u64 v[152:153], s[28:29], 0, v[144:145]
	v_lshlrev_b64 v[144:145], 1, v[140:141]
	v_lshl_add_u64 v[140:141], v[152:153], 0, v[144:145]
	v_or_b32_e32 v152, 16, v142
	v_ashrrev_i32_e32 v153, 31, v152
	v_lshlrev_b64 v[152:153], 11, v[152:153]
	global_load_dwordx4 v[156:159], v[140:141], off
	global_load_dwordx4 v[160:163], v[140:141], off offset:256
	v_lshl_add_u64 v[152:153], s[28:29], 0, v[152:153]
	v_lshl_add_u64 v[152:153], v[152:153], 0, v[144:145]
	global_load_dwordx4 v[164:167], v[152:153], off
	global_load_dwordx4 v[168:171], v[152:153], off offset:256
	s_waitcnt vmcnt(0)
	v_lshlrev_b32_e32 v172, 16, v156
	v_and_b32_e32 v173, 0xffff0000, v156
	v_lshlrev_b32_e32 v156, 16, v157
	v_and_b32_e32 v157, 0xffff0000, v157
	v_lshlrev_b32_e32 v176, 16, v160
	v_and_b32_e32 v177, 0xffff0000, v160
	v_lshlrev_b32_e32 v160, 16, v161
	v_and_b32_e32 v161, 0xffff0000, v161
	v_lshlrev_b32_e32 v178, 16, v162
	v_and_b32_e32 v179, 0xffff0000, v162
	v_lshlrev_b32_e32 v162, 16, v163
	v_and_b32_e32 v163, 0xffff0000, v163
	v_lshlrev_b32_e32 v174, 16, v158
	v_and_b32_e32 v175, 0xffff0000, v158
	v_lshlrev_b32_e32 v158, 16, v159
	v_and_b32_e32 v159, 0xffff0000, v159
	v_pk_mul_f32 v[126:127], v[126:127], v[156:157]
	v_pk_mul_f32 v[118:119], v[118:119], v[160:161]
	v_pk_mul_f32 v[156:157], v[110:111], v[162:163]
	v_lshlrev_b32_e32 v160, 16, v164
	v_and_b32_e32 v161, 0xffff0000, v164
	v_lshlrev_b32_e32 v162, 16, v165
	v_and_b32_e32 v163, 0xffff0000, v165
	v_lshlrev_b32_e32 v164, 16, v166
	v_and_b32_e32 v165, 0xffff0000, v166
	v_lshlrev_b32_e32 v166, 16, v167
	v_and_b32_e32 v167, 0xffff0000, v167
	v_pk_mul_f32 v[124:125], v[124:125], v[172:173]
	v_pk_mul_f32 v[122:123], v[122:123], v[158:159]
	v_pk_mul_f32 v[120:121], v[120:121], v[174:175]
	v_lshlrev_b32_e32 v172, 16, v168
	v_and_b32_e32 v173, 0xffff0000, v168
	v_lshlrev_b32_e32 v168, 16, v169
	v_and_b32_e32 v169, 0xffff0000, v169
	v_lshlrev_b32_e32 v174, 16, v170
	v_and_b32_e32 v175, 0xffff0000, v170
	v_lshlrev_b32_e32 v170, 16, v171
	v_and_b32_e32 v171, 0xffff0000, v171
	v_pk_mul_f32 v[114:115], v[114:115], v[162:163]
	v_pk_mul_f32 v[112:113], v[112:113], v[160:161]
	v_pk_mul_f32 v[106:107], v[106:107], v[166:167]
	v_pk_mul_f32 v[104:105], v[104:105], v[164:165]
	v_pk_mul_f32 v[116:117], v[116:117], v[176:177]
	v_pk_mul_f32 v[158:159], v[108:109], v[178:179]
	v_cvt_pk_bf16_f32 v108, v124, v125
	v_cvt_pk_bf16_f32 v109, v126, v127
	v_cvt_pk_bf16_f32 v110, v120, v121
	v_cvt_pk_bf16_f32 v111, v122, v123
	v_pk_mul_f32 v[102:103], v[102:103], v[168:169]
	v_pk_mul_f32 v[100:101], v[100:101], v[172:173]
	v_pk_mul_f32 v[120:121], v[98:99], v[170:171]
	v_pk_mul_f32 v[122:123], v[96:97], v[174:175]
	v_cvt_pk_bf16_f32 v96, v112, v113
	v_cvt_pk_bf16_f32 v97, v114, v115
	v_cvt_pk_bf16_f32 v98, v104, v105
	v_cvt_pk_bf16_f32 v99, v106, v107
	v_cvt_pk_bf16_f32 v116, v116, v117
	v_cvt_pk_bf16_f32 v117, v118, v119
	v_cvt_pk_bf16_f32 v118, v158, v159
	v_cvt_pk_bf16_f32 v119, v156, v157
	global_store_dwordx4 v[140:141], v[108:111], off
	global_store_dwordx4 v[140:141], v[116:119], off offset:256
	v_cvt_pk_bf16_f32 v100, v100, v101
	v_cvt_pk_bf16_f32 v101, v102, v103
	v_cvt_pk_bf16_f32 v102, v122, v123
	v_cvt_pk_bf16_f32 v103, v120, v121
	global_store_dwordx4 v[152:153], v[96:99], off
	global_store_dwordx4 v[152:153], v[100:103], off offset:256
	s_nop 0
	v_or_b32_e32 v96, 32, v142
	v_ashrrev_i32_e32 v97, 31, v96
	v_lshlrev_b64 v[96:97], 11, v[96:97]
	v_or_b32_e32 v104, 48, v142
	v_lshl_add_u64 v[96:97], s[28:29], 0, v[96:97]
	v_ashrrev_i32_e32 v105, 31, v104
	v_lshl_add_u64 v[112:113], v[96:97], 0, v[144:145]
	v_lshlrev_b64 v[104:105], 11, v[104:105]
	global_load_dwordx4 v[96:99], v[112:113], off
	global_load_dwordx4 v[100:103], v[112:113], off offset:256
	v_lshl_add_u64 v[104:105], s[28:29], 0, v[104:105]
	v_lshl_add_u64 v[114:115], v[104:105], 0, v[144:145]
	global_load_dwordx4 v[104:107], v[114:115], off
	global_load_dwordx4 v[108:111], v[114:115], off offset:256
	s_waitcnt vmcnt(0)
	v_lshlrev_b32_e32 v116, 16, v96
	v_and_b32_e32 v117, 0xffff0000, v96
	v_lshlrev_b32_e32 v96, 16, v97
	v_and_b32_e32 v97, 0xffff0000, v97
	v_lshlrev_b32_e32 v120, 16, v100
	v_and_b32_e32 v121, 0xffff0000, v100
	v_lshlrev_b32_e32 v100, 16, v101
	v_and_b32_e32 v101, 0xffff0000, v101
	v_lshlrev_b32_e32 v122, 16, v102
	v_and_b32_e32 v123, 0xffff0000, v102
	v_lshlrev_b32_e32 v102, 16, v103
	v_and_b32_e32 v103, 0xffff0000, v103
	v_lshlrev_b32_e32 v118, 16, v98
	v_and_b32_e32 v119, 0xffff0000, v98
	v_lshlrev_b32_e32 v98, 16, v99
	v_and_b32_e32 v99, 0xffff0000, v99
	v_pk_mul_f32 v[94:95], v[94:95], v[96:97]
	v_pk_mul_f32 v[86:87], v[86:87], v[100:101]
	v_pk_mul_f32 v[96:97], v[78:79], v[102:103]
	v_lshlrev_b32_e32 v100, 16, v104
	v_and_b32_e32 v101, 0xffff0000, v104
	v_lshlrev_b32_e32 v102, 16, v105
	v_and_b32_e32 v103, 0xffff0000, v105
	v_lshlrev_b32_e32 v104, 16, v106
	v_and_b32_e32 v105, 0xffff0000, v106
	v_lshlrev_b32_e32 v106, 16, v107
	v_and_b32_e32 v107, 0xffff0000, v107
	v_pk_mul_f32 v[92:93], v[92:93], v[116:117]
	v_pk_mul_f32 v[90:91], v[90:91], v[98:99]
	v_pk_mul_f32 v[88:89], v[88:89], v[118:119]
	v_lshlrev_b32_e32 v116, 16, v108
	v_and_b32_e32 v117, 0xffff0000, v108
	v_lshlrev_b32_e32 v108, 16, v109
	v_and_b32_e32 v109, 0xffff0000, v109
	v_lshlrev_b32_e32 v118, 16, v110
	v_and_b32_e32 v119, 0xffff0000, v110
	v_lshlrev_b32_e32 v110, 16, v111
	v_and_b32_e32 v111, 0xffff0000, v111
	v_pk_mul_f32 v[82:83], v[82:83], v[102:103]
	v_pk_mul_f32 v[80:81], v[80:81], v[100:101]
	v_pk_mul_f32 v[74:75], v[74:75], v[106:107]
	v_pk_mul_f32 v[72:73], v[72:73], v[104:105]
	v_pk_mul_f32 v[84:85], v[84:85], v[120:121]
	v_pk_mul_f32 v[98:99], v[76:77], v[122:123]
	v_cvt_pk_bf16_f32 v76, v92, v93
	v_cvt_pk_bf16_f32 v77, v94, v95
	v_cvt_pk_bf16_f32 v78, v88, v89
	v_cvt_pk_bf16_f32 v79, v90, v91
	v_pk_mul_f32 v[70:71], v[70:71], v[108:109]
	v_pk_mul_f32 v[68:69], v[68:69], v[116:117]
	v_pk_mul_f32 v[88:89], v[66:67], v[110:111]
	v_pk_mul_f32 v[90:91], v[64:65], v[118:119]
	v_cvt_pk_bf16_f32 v64, v80, v81
	v_cvt_pk_bf16_f32 v65, v82, v83
	v_cvt_pk_bf16_f32 v66, v72, v73
	v_cvt_pk_bf16_f32 v67, v74, v75
	v_cvt_pk_bf16_f32 v84, v84, v85
	v_cvt_pk_bf16_f32 v85, v86, v87
	v_cvt_pk_bf16_f32 v86, v98, v99
	v_cvt_pk_bf16_f32 v87, v96, v97
	global_store_dwordx4 v[112:113], v[76:79], off
	global_store_dwordx4 v[112:113], v[84:87], off offset:256
	v_cvt_pk_bf16_f32 v68, v68, v69
	v_cvt_pk_bf16_f32 v69, v70, v71
	v_cvt_pk_bf16_f32 v70, v90, v91
	v_cvt_pk_bf16_f32 v71, v88, v89
	global_store_dwordx4 v[114:115], v[64:67], off
	global_store_dwordx4 v[114:115], v[68:71], off offset:256
	s_mov_b32 s25, 0x40000
	v_add_co_u32_e32 v80, vcc, s25, v140
	s_mov_b64 s[52:53], 0x40000
	s_nop 0
	v_addc_co_u32_e32 v81, vcc, 0, v141, vcc
	s_mov_b32 s25, 0x48000
	v_lshl_add_u64 v[82:83], v[140:141], 0, s[52:53]
	v_add_co_u32_e32 v84, vcc, s25, v140
	s_mov_b64 s[52:53], 0x48000
	global_load_dwordx4 v[64:67], v[80:81], off
	global_load_dwordx4 v[68:71], v[82:83], off offset:256
	v_addc_co_u32_e32 v85, vcc, 0, v141, vcc
	v_lshl_add_u64 v[86:87], v[140:141], 0, s[52:53]
	global_load_dwordx4 v[72:75], v[84:85], off
	global_load_dwordx4 v[76:79], v[86:87], off offset:256
	s_waitcnt vmcnt(0)
	v_lshlrev_b32_e32 v88, 16, v64
	v_and_b32_e32 v89, 0xffff0000, v64
	v_lshlrev_b32_e32 v64, 16, v65
	v_and_b32_e32 v65, 0xffff0000, v65
	v_lshlrev_b32_e32 v90, 16, v66
	v_and_b32_e32 v91, 0xffff0000, v66
	v_lshlrev_b32_e32 v66, 16, v67
	v_and_b32_e32 v67, 0xffff0000, v67
	v_lshlrev_b32_e32 v92, 16, v68
	v_and_b32_e32 v93, 0xffff0000, v68
	v_lshlrev_b32_e32 v68, 16, v69
	v_and_b32_e32 v69, 0xffff0000, v69
	v_lshlrev_b32_e32 v94, 16, v70
	v_and_b32_e32 v95, 0xffff0000, v70
	v_lshlrev_b32_e32 v70, 16, v71
	v_and_b32_e32 v71, 0xffff0000, v71
	v_lshlrev_b32_e32 v96, 16, v72
	v_and_b32_e32 v97, 0xffff0000, v72
	v_lshlrev_b32_e32 v72, 16, v73
	v_and_b32_e32 v73, 0xffff0000, v73
	v_lshlrev_b32_e32 v98, 16, v74
	v_and_b32_e32 v99, 0xffff0000, v74
	v_lshlrev_b32_e32 v74, 16, v75
	v_and_b32_e32 v75, 0xffff0000, v75
	v_lshlrev_b32_e32 v100, 16, v76
	v_and_b32_e32 v101, 0xffff0000, v76
	v_lshlrev_b32_e32 v76, 16, v77
	v_and_b32_e32 v77, 0xffff0000, v77
	v_lshlrev_b32_e32 v102, 16, v78
	v_and_b32_e32 v103, 0xffff0000, v78
	v_lshlrev_b32_e32 v78, 16, v79
	v_and_b32_e32 v79, 0xffff0000, v79
	v_pk_mul_f32 v[62:63], v[62:63], v[64:65]
	v_pk_mul_f32 v[60:61], v[60:61], v[88:89]
	v_pk_mul_f32 v[58:59], v[58:59], v[66:67]
	v_pk_mul_f32 v[56:57], v[56:57], v[90:91]
	v_pk_mul_f32 v[46:47], v[46:47], v[68:69]
	v_pk_mul_f32 v[44:45], v[44:45], v[92:93]
	v_pk_mul_f32 v[42:43], v[42:43], v[70:71]
	v_pk_mul_f32 v[40:41], v[40:41], v[94:95]
	v_pk_mul_f32 v[54:55], v[54:55], v[72:73]
	v_pk_mul_f32 v[52:53], v[52:53], v[96:97]
	v_pk_mul_f32 v[50:51], v[50:51], v[74:75]
	v_pk_mul_f32 v[48:49], v[48:49], v[98:99]
	v_pk_mul_f32 v[64:65], v[38:39], v[76:77]
	v_pk_mul_f32 v[66:67], v[36:37], v[100:101]
	v_pk_mul_f32 v[68:69], v[34:35], v[78:79]
	v_pk_mul_f32 v[70:71], v[32:33], v[102:103]
	v_cvt_pk_bf16_f32 v32, v60, v61
	v_cvt_pk_bf16_f32 v33, v62, v63
	v_cvt_pk_bf16_f32 v34, v56, v57
	v_cvt_pk_bf16_f32 v35, v58, v59
	v_cvt_pk_bf16_f32 v36, v44, v45
	v_cvt_pk_bf16_f32 v37, v46, v47
	v_cvt_pk_bf16_f32 v38, v40, v41
	v_cvt_pk_bf16_f32 v39, v42, v43
	v_cvt_pk_bf16_f32 v40, v52, v53
	v_cvt_pk_bf16_f32 v41, v54, v55
	v_cvt_pk_bf16_f32 v42, v48, v49
	v_cvt_pk_bf16_f32 v43, v50, v51
	v_cvt_pk_bf16_f32 v44, v66, v67
	v_cvt_pk_bf16_f32 v45, v64, v65
	v_cvt_pk_bf16_f32 v46, v70, v71
	v_cvt_pk_bf16_f32 v47, v68, v69
	global_store_dwordx4 v[80:81], v[32:35], off
	global_store_dwordx4 v[82:83], v[36:39], off offset:256
	global_store_dwordx4 v[84:85], v[40:43], off
	global_store_dwordx4 v[86:87], v[44:47], off offset:256
	v_add_co_u32_e32 v48, vcc, s80, v140
	s_mov_b32 s25, 0x50000
	s_nop 0
	v_addc_co_u32_e32 v49, vcc, 0, v141, vcc
	v_add_co_u32_e32 v52, vcc, s25, v140
	v_lshl_add_u64 v[50:51], v[140:141], 0, s[14:15]
	s_nop 0
	v_addc_co_u32_e32 v53, vcc, 0, v141, vcc
	s_mov_b64 s[52:53], 0x50000
	global_load_dwordx4 v[32:35], v[48:49], off
	global_load_dwordx4 v[36:39], v[50:51], off offset:256
	global_load_dwordx4 v[40:43], v[52:53], off
	v_lshl_add_u64 v[54:55], v[140:141], 0, s[52:53]
	global_load_dwordx4 v[44:47], v[54:55], off offset:256
	s_and_b64 vcc, exec, s[4:5]
	s_mov_b32 s81, s24
	s_mov_b32 s50, s40
	s_mov_b64 s[52:53], s[48:49]
	s_mov_b64 s[54:55], s[46:47]
	s_waitcnt vmcnt(0)
	v_lshlrev_b32_e32 v56, 16, v32
	v_lshlrev_b32_e32 v60, 16, v36
	v_and_b32_e32 v61, 0xffff0000, v36
	v_lshlrev_b32_e32 v36, 16, v37
	v_and_b32_e32 v37, 0xffff0000, v37
	v_lshlrev_b32_e32 v64, 16, v40
	v_and_b32_e32 v65, 0xffff0000, v40
	v_lshlrev_b32_e32 v40, 16, v41
	v_and_b32_e32 v41, 0xffff0000, v41
	v_lshlrev_b32_e32 v66, 16, v42
	v_and_b32_e32 v67, 0xffff0000, v42
	v_lshlrev_b32_e32 v42, 16, v43
	v_and_b32_e32 v43, 0xffff0000, v43
	v_and_b32_e32 v57, 0xffff0000, v32
	v_lshlrev_b32_e32 v32, 16, v33
	v_and_b32_e32 v33, 0xffff0000, v33
	v_lshlrev_b32_e32 v58, 16, v34
	v_and_b32_e32 v59, 0xffff0000, v34
	v_lshlrev_b32_e32 v34, 16, v35
	v_and_b32_e32 v35, 0xffff0000, v35
	v_lshlrev_b32_e32 v62, 16, v38
	v_and_b32_e32 v63, 0xffff0000, v38
	v_lshlrev_b32_e32 v38, 16, v39
	v_and_b32_e32 v39, 0xffff0000, v39
	v_lshlrev_b32_e32 v68, 16, v44
	v_and_b32_e32 v69, 0xffff0000, v44
	v_lshlrev_b32_e32 v44, 16, v45
	v_and_b32_e32 v45, 0xffff0000, v45
	v_lshlrev_b32_e32 v70, 16, v46
	v_and_b32_e32 v71, 0xffff0000, v46
	v_lshlrev_b32_e32 v46, 16, v47
	v_and_b32_e32 v47, 0xffff0000, v47
	v_pk_mul_f32 v[10:11], v[10:11], v[36:37]
	v_pk_mul_f32 v[8:9], v[8:9], v[60:61]
	v_pk_mul_f32 v[30:31], v[30:31], v[40:41]
	v_pk_mul_f32 v[28:29], v[28:29], v[64:65]
	v_pk_mul_f32 v[22:23], v[22:23], v[42:43]
	v_pk_mul_f32 v[20:21], v[20:21], v[66:67]
	v_pk_mul_f32 v[26:27], v[26:27], v[32:33]
	v_pk_mul_f32 v[24:25], v[24:25], v[56:57]
	v_pk_mul_f32 v[18:19], v[18:19], v[34:35]
	v_pk_mul_f32 v[16:17], v[16:17], v[58:59]
	v_pk_mul_f32 v[32:33], v[2:3], v[38:39]
	v_pk_mul_f32 v[34:35], v[0:1], v[62:63]
	v_pk_mul_f32 v[14:15], v[14:15], v[44:45]
	v_pk_mul_f32 v[12:13], v[12:13], v[68:69]
	v_pk_mul_f32 v[36:37], v[6:7], v[46:47]
	v_pk_mul_f32 v[38:39], v[4:5], v[70:71]
	v_cvt_pk_bf16_f32 v4, v8, v9
	v_cvt_pk_bf16_f32 v5, v10, v11
	v_cvt_pk_bf16_f32 v8, v28, v29
	v_cvt_pk_bf16_f32 v9, v30, v31
	v_cvt_pk_bf16_f32 v10, v20, v21
	v_cvt_pk_bf16_f32 v11, v22, v23
	v_cvt_pk_bf16_f32 v0, v24, v25
	v_cvt_pk_bf16_f32 v1, v26, v27
	v_cvt_pk_bf16_f32 v2, v16, v17
	v_cvt_pk_bf16_f32 v3, v18, v19
	v_cvt_pk_bf16_f32 v6, v34, v35
	v_cvt_pk_bf16_f32 v7, v32, v33
	v_cvt_pk_bf16_f32 v12, v12, v13
	v_cvt_pk_bf16_f32 v13, v14, v15
	v_cvt_pk_bf16_f32 v14, v38, v39
	v_cvt_pk_bf16_f32 v15, v36, v37
	global_store_dwordx4 v[52:53], v[8:11], off
	global_store_dwordx4 v[54:55], v[12:15], off offset:256
	global_store_dwordx4 v[48:49], v[0:3], off
	global_store_dwordx4 v[50:51], v[4:7], off offset:256
	s_cbranch_vccz .LBB0_544
	s_waitcnt vmcnt(0)
	v_readlane_b32 s78, v228, 33
	v_readlane_b32 s80, v228, 36
	s_cmpk_gt_u32 s0, 0xff
	v_readlane_b32 s76, v228, 32
	v_readlane_b32 s79, v228, 34
	v_readlane_b32 s77, v228, 35
	v_readlane_b32 s81, v228, 37
	s_cbranch_scc1 .LBB0_551
	s_barrier

.LBB0_552:
	s_waitcnt lgkmcnt(0)
	s_barrier
	s_setprio 0
	s_and_saveexec_b64 s[4:5], s[80:81]
	s_cbranch_execz .LBB0_562
	buffer_wbl2 sc1
	s_waitcnt vmcnt(0)
	s_load_dwordx2 s[6:7], s[78:79], -0x8
	s_load_dword s0, s[78:79], 0x0
	v_mov_b32_e32 v0, 0
	v_mov_b32_e32 v1, 1
	v_mov_b32_e32 v3, 0
	s_mov_b64 s[8:9], 0
	s_waitcnt lgkmcnt(0)
	s_add_u32 s6, s6, 0x2300080
	s_addc_u32 s7, s7, 0
	s_mul_i32 s0, s0, 4
	global_atomic_add v0, v1, s[6:7]

.LBB0_565:
	s_lshl_b32 s8, s8, 5
	s_and_b32 s25, s8, 0x60
	s_mov_b64 s[8:9], 0x80
	s_add_i32 m0, s57, 0x18000
	v_lshl_add_u64 v[6:7], v[6:7], 0, s[8:9]
	s_lshl_b32 s24, s5, 13
	s_lshl_b32 s40, s25, 7
	s_waitcnt vmcnt(4)
	s_barrier
	global_load_lds_dwordx4 v[6:7], off
	v_lshl_add_u64 v[4:5], v[4:5], 0, s[8:9]
	s_add_i32 m0, s57, 0x1a000
	s_add_i32 s69, s57, 0x8000
	s_add_i32 s70, s57, 0xa000
	global_load_lds_dwordx4 v[4:5], off
	v_lshl_add_u64 v[2:3], v[2:3], 0, s[8:9]
	s_mov_b32 m0, s69
	s_add_u32 s14, s60, 0x40080
	global_load_lds_dwordx4 v[2:3], off
	v_lshl_add_u64 v[0:1], v[0:1], 0, s[8:9]
	s_mov_b32 m0, s70
	s_addc_u32 s15, s61, 0
	global_load_lds_dwordx4 v[0:1], off
	s_add_i32 m0, s57, 0x1c000
	v_lshl_add_u64 v[0:1], s[14:15], 0, v[132:133]
	global_load_lds_dwordx4 v[0:1], off
	v_lshl_add_u64 v[0:1], s[14:15], 0, v[128:129]
	s_add_i32 m0, s57, 0x1e000
	s_add_i32 s73, 0, 0x10000
	global_load_lds_dwordx4 v[0:1], off
	v_lshrrev_b32_e32 v1, 1, v9
	v_and_b32_e32 v1, 24, v1
	v_and_b32_e32 v0, 15, v9
	v_lshlrev_b32_e32 v2, 1, v1
	v_lshl_or_b32 v152, s5, 6, v0
	v_lshl_or_b32 v0, v0, 6, v2
	v_lshlrev_b32_e32 v2, 2, v9
	v_and_b32_e32 v2, 32, v2
	v_bitop3_b32 v3, v0, s24, v2 bitop3:0xde
	v_bitop3_b32 v153, v0, s40, v2 bitop3:0xde
	v_lshlrev_b32_e32 v0, 14, v13
	v_and_b32_e32 v0, 0xffff8000, v0
	v_or_b32_e32 v156, s25, v1
	v_lshl_add_u32 v0, v12, 11, v0
	v_and_b32_e32 v1, 1, v13
	v_lshl_or_b32 v0, v1, 6, v0
	v_lshl_add_u32 v136, v14, 1, v0
	v_lshlrev_b32_e32 v0, 14, v8
	v_and_b32_e32 v0, 0xffff8000, v0
	s_waitcnt vmcnt(6)
	v_lshl_add_u32 v0, v10, 11, v0
	v_and_b32_e32 v1, 1, v8
	v_lshl_or_b32 v0, v1, 6, v0
	s_sext_i32_i8 s78, s4
	s_ashr_i32 s71, s3, 31
	v_mov_b32_e32 v137, v133
	v_lshl_add_u32 v138, v11, 1, v0
	v_mov_b32_e32 v139, v133
	v_mov_b64_e32 v[140:141], 0xc00
	v_mov_b64_e32 v[142:143], 0xbff
	v_add_u32_e32 v157, s73, v153
	v_add_u32_e32 v158, 0, v3
	v_add_u32_e32 v159, s72, v153
	s_mov_b64 s[14:15], 0x80000
	s_mov_b32 s74, 0x80000
	s_mov_b64 s[24:25], 0x90000
	s_mov_b32 s75, 0x90000
	s_mov_b64 s[40:41], 0xa0000
	s_mov_b32 s76, 0xa0000
	s_mov_b64 s[46:47], 0xb0000
	s_mov_b32 s77, 0xb0000
	s_barrier
	v_readfirstlane_b32 s4, v154
	s_bitcmp1_b32 s4, 8
	s_cbranch_scc0 .Lprio_566
	s_setprio 1
.Lprio_566:
.LBB0_566:
	s_add_i32 s68, s68, 1
	s_mul_i32 s4, s68, s71
	s_mul_hi_u32 s5, s68, s3
	s_add_i32 s5, s5, s4
	s_mul_i32 s4, s68, s3
	s_add_u32 s52, s4, s2
	s_addc_u32 s53, s5, s35
	v_cmp_gt_i64_e64 s[4:5], s[52:53], v[142:143]
	s_and_b64 vcc, exec, s[4:5]
	s_cbranch_vccnz .LBB0_568
	s_ashr_i32 s48, s52, 31
	s_lshr_b32 s48, s48, 29
	s_add_i32 s48, s52, s48
	s_ashr_i32 s49, s48, 3
	s_and_b32 s48, s48, -8
	s_sub_i32 s48, s52, s48
	s_cmp_lt_i32 s48, 0
	s_cselect_b32 s50, s64, 0x180
	s_mul_i32 s48, s50, s48
	s_add_i32 s48, s48, s49
	s_ashr_i32 s49, s48, 31
	s_lshr_b32 s49, s49, 26
	s_add_i32 s49, s48, s49
	s_ashr_i32 s50, s49, 6
	s_lshl_b32 s50, s50, 3
	s_sub_i32 s51, 0x180, s50
	s_min_i32 s51, s51, 8
	s_abs_i32 s54, s51
	v_cvt_f32_u32_e32 v0, s54
	s_sub_i32 s62, 0, s54
	s_andn2_b32 s49, s49, 63
	s_sub_i32 s49, s48, s49
	v_rcp_iflag_f32_e32 v0, v0
	s_abs_i32 s48, s49
	s_xor_b32 s55, s49, s51
	s_ashr_i32 s55, s55, 31
	v_mul_f32_e32 v0, 0x4f7ffffe, v0
	v_cvt_u32_f32_e32 v0, v0
	s_nop 0
	v_readfirstlane_b32 s63, v0
	s_mul_i32 s62, s62, s63
	s_mul_hi_u32 s62, s63, s62
	s_add_i32 s63, s63, s62
	s_mul_hi_u32 s62, s48, s63
	s_mul_i32 s63, s62, s54
	s_sub_i32 s48, s48, s63
	s_add_i32 s79, s62, 1
	s_sub_i32 s63, s48, s54
	s_cmp_ge_u32 s48, s54
	s_cselect_b32 s62, s79, s62
	s_cselect_b32 s48, s63, s48
	s_add_i32 s63, s62, 1
	s_cmp_ge_u32 s48, s54
	s_cselect_b32 s48, s63, s62
	s_xor_b32 s48, s48, s55
	s_sub_i32 s48, s48, s55
	s_mul_i32 s51, s48, s51
	s_sub_i32 s49, s49, s51
	s_add_i32 s50, s49, s50

.LBB0_569:
	ds_read_b128 v[144:147], v157
	ds_read_b128 v[148:151], v157 offset:1024
	ds_read_b128 v[160:163], v157 offset:2048
	ds_read_b128 v[164:167], v157 offset:3072
	s_add_u32 s60, s58, 0xfffc0080
	s_addc_u32 s61, s59, -1
	s_cmp_eq_u32 s83, 12
	s_cselect_b32 s63, s51, s61
	s_cselect_b32 s62, s79, s60
	s_cselect_b32 s61, s49, s82
	s_cselect_b32 s60, s80, s81
	v_lshl_add_u64 v[200:201], s[58:59], 0, v[136:137]
	s_add_i32 m0, s57, 0xc000
	ds_read_b128 v[168:171], v158
	ds_read_b128 v[172:175], v158 offset:1024
	ds_read_b128 v[176:179], v158 offset:2048
	ds_read_b128 v[180:183], v158 offset:3072
	ds_read_b128 v[184:187], v158 offset:4096
	ds_read_b128 v[188:191], v158 offset:5120
	ds_read_b128 v[192:195], v158 offset:6144
	ds_read_b128 v[196:199], v158 offset:7168
	global_load_lds_dwordx4 v[200:201], off
	v_lshl_add_u64 v[200:201], s[58:59], 0, v[138:139]
	s_add_i32 m0, s57, 0xe000
	s_nop 0
	global_load_lds_dwordx4 v[200:201], off
	s_waitcnt lgkmcnt(8)
	s_barrier
	s_waitcnt lgkmcnt(0)
	s_waitcnt lgkmcnt(0)
	v_mfma_f32_16x16x32_bf16 v[124:127], v[144:147], v[168:171], v[124:127]
	v_mfma_f32_16x16x32_bf16 v[120:123], v[160:163], v[168:171], v[120:123]
	v_mfma_f32_16x16x32_bf16 v[108:111], v[144:147], v[176:179], v[108:111]
	v_mfma_f32_16x16x32_bf16 v[104:107], v[160:163], v[176:179], v[104:107]
	v_mfma_f32_16x16x32_bf16 v[92:95], v[144:147], v[184:187], v[92:95]
	v_mfma_f32_16x16x32_bf16 v[88:91], v[160:163], v[184:187], v[88:91]
	v_mfma_f32_16x16x32_bf16 v[76:79], v[144:147], v[192:195], v[76:79]
	v_mfma_f32_16x16x32_bf16 v[72:75], v[160:163], v[192:195], v[72:75]
	v_mfma_f32_16x16x32_bf16 v[124:127], v[148:151], v[172:175], v[124:127]
	v_mfma_f32_16x16x32_bf16 v[120:123], v[164:167], v[172:175], v[120:123]
	v_mfma_f32_16x16x32_bf16 v[108:111], v[148:151], v[180:183], v[108:111]
	v_mfma_f32_16x16x32_bf16 v[104:107], v[164:167], v[180:183], v[104:107]
	v_mfma_f32_16x16x32_bf16 v[92:95], v[148:151], v[188:191], v[92:95]
	v_mfma_f32_16x16x32_bf16 v[88:91], v[164:167], v[188:191], v[88:91]
	v_mfma_f32_16x16x32_bf16 v[76:79], v[148:151], v[196:199], v[76:79]
	v_mfma_f32_16x16x32_bf16 v[72:75], v[164:167], v[196:199], v[72:75]
	s_barrier
	s_add_i32 s86, s73, s34
	v_lshl_add_u64 v[216:217], s[60:61], 0, v[132:133]
	s_mov_b32 m0, s86
	ds_read_b128 v[200:203], v159
	ds_read_b128 v[204:207], v159 offset:1024
	ds_read_b128 v[208:211], v159 offset:2048
	ds_read_b128 v[212:215], v159 offset:3072
	global_load_lds_dwordx4 v[216:217], off
	v_lshl_add_u64 v[218:219], s[60:61], 0, v[128:129]
	s_add_i32 m0, s86, 0x2000
	s_nop 0
	global_load_lds_dwordx4 v[218:219], off
	s_barrier
	s_waitcnt lgkmcnt(0)
	s_waitcnt lgkmcnt(0)
	v_mfma_f32_16x16x32_bf16 v[116:119], v[200:203], v[168:171], v[116:119]
	v_mfma_f32_16x16x32_bf16 v[112:115], v[208:211], v[168:171], v[112:115]
	v_mfma_f32_16x16x32_bf16 v[100:103], v[200:203], v[176:179], v[100:103]
	v_mfma_f32_16x16x32_bf16 v[96:99], v[208:211], v[176:179], v[96:99]
	v_mfma_f32_16x16x32_bf16 v[84:87], v[200:203], v[184:187], v[84:87]
	v_mfma_f32_16x16x32_bf16 v[80:83], v[208:211], v[184:187], v[80:83]
	v_mfma_f32_16x16x32_bf16 v[68:71], v[200:203], v[192:195], v[68:71]
	v_mfma_f32_16x16x32_bf16 v[64:67], v[208:211], v[192:195], v[64:67]
	v_mfma_f32_16x16x32_bf16 v[116:119], v[204:207], v[172:175], v[116:119]
	v_mfma_f32_16x16x32_bf16 v[112:115], v[212:215], v[172:175], v[112:115]
	v_mfma_f32_16x16x32_bf16 v[100:103], v[204:207], v[180:183], v[100:103]
	v_mfma_f32_16x16x32_bf16 v[96:99], v[212:215], v[180:183], v[96:99]
	v_mfma_f32_16x16x32_bf16 v[84:87], v[204:207], v[188:191], v[84:87]
	v_mfma_f32_16x16x32_bf16 v[80:83], v[212:215], v[188:191], v[80:83]
	v_mfma_f32_16x16x32_bf16 v[68:71], v[204:207], v[196:199], v[68:71]
	v_mfma_f32_16x16x32_bf16 v[64:67], v[212:215], v[196:199], v[64:67]
	s_mov_b32 m0, s57
	v_lshl_add_u64 v[220:221], s[62:63], 0, v[134:135]
	s_barrier
	ds_read_b128 v[168:171], v158 offset:16384
	ds_read_b128 v[172:175], v158 offset:17408
	ds_read_b128 v[176:179], v158 offset:18432
	ds_read_b128 v[180:183], v158 offset:19456
	ds_read_b128 v[184:187], v158 offset:20480
	ds_read_b128 v[188:191], v158 offset:21504
	ds_read_b128 v[192:195], v158 offset:22528
	ds_read_b128 v[196:199], v158 offset:23552
	global_load_lds_dwordx4 v[220:221], off
	v_lshl_add_u64 v[222:223], s[62:63], 0, v[130:131]
	s_mov_b32 m0, s65
	s_nop 0
	global_load_lds_dwordx4 v[222:223], off
	s_barrier
	s_waitcnt lgkmcnt(0)
	s_waitcnt lgkmcnt(0)
	v_mfma_f32_16x16x32_bf16 v[60:63], v[144:147], v[168:171], v[60:63]
	v_mfma_f32_16x16x32_bf16 v[56:59], v[160:163], v[168:171], v[56:59]
	v_mfma_f32_16x16x32_bf16 v[44:47], v[144:147], v[176:179], v[44:47]
	v_mfma_f32_16x16x32_bf16 v[40:43], v[160:163], v[176:179], v[40:43]
	v_mfma_f32_16x16x32_bf16 v[28:31], v[144:147], v[184:187], v[28:31]
	v_mfma_f32_16x16x32_bf16 v[24:27], v[160:163], v[184:187], v[24:27]
	v_mfma_f32_16x16x32_bf16 v[12:15], v[144:147], v[192:195], v[12:15]
	v_mfma_f32_16x16x32_bf16 v[8:11], v[160:163], v[192:195], v[8:11]
	v_mfma_f32_16x16x32_bf16 v[60:63], v[148:151], v[172:175], v[60:63]
	v_mfma_f32_16x16x32_bf16 v[56:59], v[164:167], v[172:175], v[56:59]
	v_mfma_f32_16x16x32_bf16 v[44:47], v[148:151], v[180:183], v[44:47]
	v_mfma_f32_16x16x32_bf16 v[40:43], v[164:167], v[180:183], v[40:43]
	v_mfma_f32_16x16x32_bf16 v[28:31], v[148:151], v[188:191], v[28:31]
	v_mfma_f32_16x16x32_bf16 v[24:27], v[164:167], v[188:191], v[24:27]
	v_mfma_f32_16x16x32_bf16 v[12:15], v[148:151], v[196:199], v[12:15]
	v_mfma_f32_16x16x32_bf16 v[8:11], v[164:167], v[196:199], v[8:11]
	s_barrier
	s_add_u32 s86, s60, 0x40000
	s_addc_u32 s87, s61, 0
	s_add_i32 s88, s72, s34
	v_lshl_add_u64 v[144:145], s[86:87], 0, v[132:133]
	s_mov_b32 m0, s88
	s_nop 0
	global_load_lds_dwordx4 v[144:145], off
	v_lshl_add_u64 v[144:145], s[86:87], 0, v[128:129]
	s_add_i32 m0, s88, 0x2000
	s_nop 0
	global_load_lds_dwordx4 v[144:145], off
	s_waitcnt vmcnt(6)
	s_barrier
	v_mfma_f32_16x16x32_bf16 v[52:55], v[200:203], v[168:171], v[52:55]
	v_mfma_f32_16x16x32_bf16 v[48:51], v[208:211], v[168:171], v[48:51]
	v_mfma_f32_16x16x32_bf16 v[36:39], v[200:203], v[176:179], v[36:39]
	v_mfma_f32_16x16x32_bf16 v[32:35], v[208:211], v[176:179], v[32:35]
	v_mfma_f32_16x16x32_bf16 v[20:23], v[200:203], v[184:187], v[20:23]
	v_mfma_f32_16x16x32_bf16 v[16:19], v[208:211], v[184:187], v[16:19]
	v_mfma_f32_16x16x32_bf16 v[4:7], v[200:203], v[192:195], v[4:7]
	v_mfma_f32_16x16x32_bf16 v[0:3], v[208:211], v[192:195], v[0:3]
	v_mfma_f32_16x16x32_bf16 v[52:55], v[204:207], v[172:175], v[52:55]
	v_mfma_f32_16x16x32_bf16 v[48:51], v[212:215], v[172:175], v[48:51]
	v_mfma_f32_16x16x32_bf16 v[36:39], v[204:207], v[180:183], v[36:39]
	v_mfma_f32_16x16x32_bf16 v[32:35], v[212:215], v[180:183], v[32:35]
	v_mfma_f32_16x16x32_bf16 v[20:23], v[204:207], v[188:191], v[20:23]
	v_mfma_f32_16x16x32_bf16 v[16:19], v[212:215], v[188:191], v[16:19]
	v_mfma_f32_16x16x32_bf16 v[4:7], v[204:207], v[196:199], v[4:7]
	v_mfma_f32_16x16x32_bf16 v[0:3], v[212:215], v[196:199], v[0:3]
	s_add_i32 s86, 0, 0x18000
	v_add_u32_e32 v164, s86, v153
	s_barrier
	ds_read_b128 v[144:147], v164
	ds_read_b128 v[148:151], v164 offset:1024
	ds_read_b128 v[160:163], v164 offset:2048
	ds_read_b128 v[164:167], v164 offset:3072
	s_add_u32 s62, s62, 0x40000
	s_addc_u32 s63, s63, 0
	s_mov_b32 m0, s66
	v_lshl_add_u64 v[200:201], s[62:63], 0, v[134:135]
	ds_read_b128 v[168:171], v158 offset:32768
	ds_read_b128 v[172:175], v158 offset:33792
	ds_read_b128 v[176:179], v158 offset:34816
	ds_read_b128 v[180:183], v158 offset:35840
	ds_read_b128 v[184:187], v158 offset:36864
	ds_read_b128 v[188:191], v158 offset:37888
	ds_read_b128 v[192:195], v158 offset:38912
	ds_read_b128 v[196:199], v158 offset:39936
	global_load_lds_dwordx4 v[200:201], off
	v_lshl_add_u64 v[200:201], s[62:63], 0, v[130:131]
	s_mov_b32 m0, s67
	s_nop 0
	global_load_lds_dwordx4 v[200:201], off
	s_waitcnt lgkmcnt(8)
	s_barrier
	s_waitcnt lgkmcnt(0)
	s_waitcnt lgkmcnt(0)
	v_mfma_f32_16x16x32_bf16 v[124:127], v[144:147], v[168:171], v[124:127]
	v_mfma_f32_16x16x32_bf16 v[120:123], v[160:163], v[168:171], v[120:123]
	v_mfma_f32_16x16x32_bf16 v[108:111], v[144:147], v[176:179], v[108:111]
	v_mfma_f32_16x16x32_bf16 v[104:107], v[160:163], v[176:179], v[104:107]
	v_mfma_f32_16x16x32_bf16 v[92:95], v[144:147], v[184:187], v[92:95]
	v_mfma_f32_16x16x32_bf16 v[88:91], v[160:163], v[184:187], v[88:91]
	v_mfma_f32_16x16x32_bf16 v[76:79], v[144:147], v[192:195], v[76:79]
	v_mfma_f32_16x16x32_bf16 v[72:75], v[160:163], v[192:195], v[72:75]
	v_mfma_f32_16x16x32_bf16 v[124:127], v[148:151], v[172:175], v[124:127]
	v_mfma_f32_16x16x32_bf16 v[120:123], v[164:167], v[172:175], v[120:123]
	v_mfma_f32_16x16x32_bf16 v[108:111], v[148:151], v[180:183], v[108:111]
	v_mfma_f32_16x16x32_bf16 v[104:107], v[164:167], v[180:183], v[104:107]
	v_mfma_f32_16x16x32_bf16 v[92:95], v[148:151], v[188:191], v[92:95]
	v_mfma_f32_16x16x32_bf16 v[88:91], v[164:167], v[188:191], v[88:91]
	v_mfma_f32_16x16x32_bf16 v[76:79], v[148:151], v[196:199], v[76:79]
	v_mfma_f32_16x16x32_bf16 v[72:75], v[164:167], v[196:199], v[72:75]
	s_barrier
	s_add_i32 s62, s86, s34
	v_add_u32_e32 v212, s97, v153
	v_lshl_add_u64 v[216:217], v[216:217], 0, s[8:9]
	s_mov_b32 m0, s62
	ds_read_b128 v[200:203], v212
	ds_read_b128 v[204:207], v212 offset:1024
	ds_read_b128 v[208:211], v212 offset:2048
	ds_read_b128 v[212:215], v212 offset:3072
	global_load_lds_dwordx4 v[216:217], off
	v_lshl_add_u64 v[216:217], v[218:219], 0, s[8:9]
	s_add_i32 m0, s62, 0x2000
	s_nop 0
	global_load_lds_dwordx4 v[216:217], off
	s_barrier
	s_waitcnt lgkmcnt(0)
	s_waitcnt lgkmcnt(0)
	v_mfma_f32_16x16x32_bf16 v[116:119], v[200:203], v[168:171], v[116:119]
	v_mfma_f32_16x16x32_bf16 v[112:115], v[208:211], v[168:171], v[112:115]
	v_mfma_f32_16x16x32_bf16 v[100:103], v[200:203], v[176:179], v[100:103]
	v_mfma_f32_16x16x32_bf16 v[96:99], v[208:211], v[176:179], v[96:99]
	v_mfma_f32_16x16x32_bf16 v[84:87], v[200:203], v[184:187], v[84:87]
	v_mfma_f32_16x16x32_bf16 v[80:83], v[208:211], v[184:187], v[80:83]
	v_mfma_f32_16x16x32_bf16 v[68:71], v[200:203], v[192:195], v[68:71]
	v_mfma_f32_16x16x32_bf16 v[64:67], v[208:211], v[192:195], v[64:67]
	v_mfma_f32_16x16x32_bf16 v[116:119], v[204:207], v[172:175], v[116:119]
	v_mfma_f32_16x16x32_bf16 v[112:115], v[212:215], v[172:175], v[112:115]
	v_mfma_f32_16x16x32_bf16 v[100:103], v[204:207], v[180:183], v[100:103]
	v_mfma_f32_16x16x32_bf16 v[96:99], v[212:215], v[180:183], v[96:99]
	v_mfma_f32_16x16x32_bf16 v[84:87], v[204:207], v[188:191], v[84:87]
	v_mfma_f32_16x16x32_bf16 v[80:83], v[212:215], v[188:191], v[80:83]
	v_mfma_f32_16x16x32_bf16 v[68:71], v[204:207], v[196:199], v[68:71]
	v_mfma_f32_16x16x32_bf16 v[64:67], v[212:215], v[196:199], v[64:67]
	s_mov_b32 m0, s69
	v_lshl_add_u64 v[216:217], v[220:221], 0, s[8:9]
	s_barrier
	ds_read_b128 v[168:171], v158 offset:49152
	ds_read_b128 v[172:175], v158 offset:50176
	ds_read_b128 v[176:179], v158 offset:51200
	ds_read_b128 v[180:183], v158 offset:52224
	ds_read_b128 v[184:187], v158 offset:53248
	ds_read_b128 v[188:191], v158 offset:54272
	ds_read_b128 v[192:195], v158 offset:55296
	ds_read_b128 v[196:199], v158 offset:56320
	global_load_lds_dwordx4 v[216:217], off
	v_lshl_add_u64 v[216:217], v[222:223], 0, s[8:9]
	s_mov_b32 m0, s70
	s_nop 0
	global_load_lds_dwordx4 v[216:217], off
	s_barrier
	s_waitcnt lgkmcnt(0)
	s_waitcnt lgkmcnt(0)
	v_mfma_f32_16x16x32_bf16 v[60:63], v[144:147], v[168:171], v[60:63]
	v_mfma_f32_16x16x32_bf16 v[56:59], v[160:163], v[168:171], v[56:59]
	v_mfma_f32_16x16x32_bf16 v[44:47], v[144:147], v[176:179], v[44:47]
	v_mfma_f32_16x16x32_bf16 v[40:43], v[160:163], v[176:179], v[40:43]
	v_mfma_f32_16x16x32_bf16 v[28:31], v[144:147], v[184:187], v[28:31]
	v_mfma_f32_16x16x32_bf16 v[24:27], v[160:163], v[184:187], v[24:27]
	v_mfma_f32_16x16x32_bf16 v[12:15], v[144:147], v[192:195], v[12:15]
	v_mfma_f32_16x16x32_bf16 v[8:11], v[160:163], v[192:195], v[8:11]
	v_mfma_f32_16x16x32_bf16 v[60:63], v[148:151], v[172:175], v[60:63]
	v_mfma_f32_16x16x32_bf16 v[56:59], v[164:167], v[172:175], v[56:59]
	v_mfma_f32_16x16x32_bf16 v[44:47], v[148:151], v[180:183], v[44:47]
	v_mfma_f32_16x16x32_bf16 v[40:43], v[164:167], v[180:183], v[40:43]
	v_mfma_f32_16x16x32_bf16 v[28:31], v[148:151], v[188:191], v[28:31]
	v_mfma_f32_16x16x32_bf16 v[24:27], v[164:167], v[188:191], v[24:27]
	v_mfma_f32_16x16x32_bf16 v[12:15], v[148:151], v[196:199], v[12:15]
	v_mfma_f32_16x16x32_bf16 v[8:11], v[164:167], v[196:199], v[8:11]
	s_barrier
	s_add_u32 s60, s60, 0x40080
	s_addc_u32 s61, s61, 0
	s_add_i32 s62, s97, s34
	v_lshl_add_u64 v[144:145], s[60:61], 0, v[132:133]
	s_mov_b32 m0, s62
	s_nop 0
	global_load_lds_dwordx4 v[144:145], off
	v_lshl_add_u64 v[144:145], s[60:61], 0, v[128:129]
	s_add_i32 m0, s62, 0x2000
	s_nop 0
	global_load_lds_dwordx4 v[144:145], off
	s_waitcnt vmcnt(6)
	s_barrier
	v_mfma_f32_16x16x32_bf16 v[52:55], v[200:203], v[168:171], v[52:55]
	v_mfma_f32_16x16x32_bf16 v[48:51], v[208:211], v[168:171], v[48:51]
	v_mfma_f32_16x16x32_bf16 v[36:39], v[200:203], v[176:179], v[36:39]
	v_mfma_f32_16x16x32_bf16 v[32:35], v[208:211], v[176:179], v[32:35]
	v_mfma_f32_16x16x32_bf16 v[20:23], v[200:203], v[184:187], v[20:23]
	v_mfma_f32_16x16x32_bf16 v[16:19], v[208:211], v[184:187], v[16:19]
	v_mfma_f32_16x16x32_bf16 v[4:7], v[200:203], v[192:195], v[4:7]
	v_mfma_f32_16x16x32_bf16 v[0:3], v[208:211], v[192:195], v[0:3]
	v_mfma_f32_16x16x32_bf16 v[52:55], v[204:207], v[172:175], v[52:55]
	v_mfma_f32_16x16x32_bf16 v[48:51], v[212:215], v[172:175], v[48:51]
	v_mfma_f32_16x16x32_bf16 v[36:39], v[204:207], v[180:183], v[36:39]
	v_mfma_f32_16x16x32_bf16 v[32:35], v[212:215], v[180:183], v[32:35]
	v_mfma_f32_16x16x32_bf16 v[20:23], v[204:207], v[188:191], v[20:23]
	v_mfma_f32_16x16x32_bf16 v[16:19], v[212:215], v[188:191], v[16:19]
	v_mfma_f32_16x16x32_bf16 v[4:7], v[204:207], v[196:199], v[4:7]
	v_mfma_f32_16x16x32_bf16 v[0:3], v[212:215], v[196:199], v[0:3]
	s_add_i32 s83, s83, 2
	s_add_u32 s58, s58, 0x100
	s_addc_u32 s59, s59, 0
	s_add_u32 s81, s81, 0x100
	s_addc_u32 s82, s82, 0
	s_cmp_gt_u32 s83, 13
	s_barrier
	s_cbranch_scc0 .LBB0_569
	v_lshl_or_b32 v146, s78, 8, v156
	v_ashrrev_i32_e32 v147, 31, v146
	v_lshl_add_u64 v[144:145], v[146:147], 2, s[44:45]
	global_load_dwordx4 v[160:163], v[144:145], off
	global_load_dwordx4 v[164:167], v[144:145], off offset:16
	v_lshl_add_u32 v148, s56, 8, v152
	v_ashrrev_i32_e32 v149, 31, v148
	v_lshlrev_b64 v[168:169], 12, v[148:149]
	v_lshlrev_b64 v[150:151], 1, v[146:147]
	v_lshl_add_u64 v[146:147], s[6:7], 0, v[168:169]
	v_lshl_add_u64 v[146:147], v[146:147], 0, v[150:151]
	s_mov_b32 s78, s48
	s_mov_b32 s56, s50
	s_mov_b64 s[60:61], s[54:55]
	s_mov_b64 s[58:59], s[52:53]
	s_waitcnt vmcnt(0)
	v_add_f32_e32 v124, v124, v160
	v_add_f32_e32 v120, v120, v164
	v_add_f32_e32 v125, v125, v161
	v_add_f32_e32 v121, v121, v165
	v_add_f32_e32 v126, v126, v162
	v_add_f32_e32 v122, v122, v166
	v_add_f32_e32 v127, v127, v163
	v_add_f32_e32 v123, v123, v167
	v_mul_f32_e32 v124, 0xbfb8aa3b, v124
	v_mul_f32_e32 v120, 0xbfb8aa3b, v120
	v_mul_f32_e32 v125, 0xbfb8aa3b, v125
	v_mul_f32_e32 v121, 0xbfb8aa3b, v121
	v_mul_f32_e32 v126, 0xbfb8aa3b, v126
	v_mul_f32_e32 v122, 0xbfb8aa3b, v122
	v_mul_f32_e32 v127, 0xbfb8aa3b, v127
	v_mul_f32_e32 v123, 0xbfb8aa3b, v123
	v_exp_f32_e32 v124, v124
	v_exp_f32_e32 v120, v120
	v_exp_f32_e32 v125, v125
	v_exp_f32_e32 v121, v121
	v_exp_f32_e32 v126, v126
	v_exp_f32_e32 v122, v122
	v_exp_f32_e32 v127, v127
	v_exp_f32_e32 v123, v123
	v_add_f32_e32 v124, 1.0, v124
	v_add_f32_e32 v120, 1.0, v120
	v_add_f32_e32 v125, 1.0, v125
	v_add_f32_e32 v121, 1.0, v121
	v_add_f32_e32 v126, 1.0, v126
	v_add_f32_e32 v122, 1.0, v122
	v_add_f32_e32 v127, 1.0, v127
	v_add_f32_e32 v123, 1.0, v123
	v_rcp_f32_e32 v124, v124
	v_rcp_f32_e32 v149, v120
	v_rcp_f32_e32 v120, v125
	v_rcp_f32_e32 v125, v121
	v_rcp_f32_e32 v121, v126
	v_rcp_f32_e32 v126, v127
	v_rcp_f32_e32 v127, v122
	v_rcp_f32_e32 v123, v123
	v_cvt_pk_bf16_f32 v120, v124, v120
	v_cvt_pk_bf16_f32 v121, v121, v126
	v_cvt_pk_bf16_f32 v122, v149, v125
	v_cvt_pk_bf16_f32 v123, v127, v123
	global_store_dwordx4 v[146:147], v[120:123], off
	global_load_dwordx4 v[120:123], v[144:145], off offset:512
	s_nop 0
	global_load_dwordx4 v[124:127], v[144:145], off offset:528
	s_waitcnt vmcnt(0)
	v_add_f32_e32 v116, v116, v120
	v_add_f32_e32 v112, v112, v124
	v_add_f32_e32 v117, v117, v121
	v_add_f32_e32 v113, v113, v125
	v_add_f32_e32 v118, v118, v122
	v_add_f32_e32 v114, v114, v126
	v_add_f32_e32 v119, v119, v123
	v_add_f32_e32 v115, v115, v127
	v_mul_f32_e32 v116, 0xbfb8aa3b, v116
	v_mul_f32_e32 v112, 0xbfb8aa3b, v112
	v_mul_f32_e32 v117, 0xbfb8aa3b, v117
	v_mul_f32_e32 v113, 0xbfb8aa3b, v113
	v_mul_f32_e32 v118, 0xbfb8aa3b, v118
	v_mul_f32_e32 v114, 0xbfb8aa3b, v114
	v_mul_f32_e32 v119, 0xbfb8aa3b, v119
	v_mul_f32_e32 v115, 0xbfb8aa3b, v115
	v_exp_f32_e32 v116, v116
	v_exp_f32_e32 v112, v112
	v_exp_f32_e32 v117, v117
	v_exp_f32_e32 v113, v113
	v_exp_f32_e32 v118, v118
	v_exp_f32_e32 v114, v114
	v_exp_f32_e32 v119, v119
	v_exp_f32_e32 v115, v115
	v_add_f32_e32 v116, 1.0, v116
	v_add_f32_e32 v112, 1.0, v112
	v_add_f32_e32 v117, 1.0, v117
	v_add_f32_e32 v113, 1.0, v113
	v_add_f32_e32 v118, 1.0, v118
	v_add_f32_e32 v114, 1.0, v114
	v_add_f32_e32 v119, 1.0, v119
	v_add_f32_e32 v115, 1.0, v115
	v_rcp_f32_e32 v116, v116
	v_rcp_f32_e32 v120, v112
	v_rcp_f32_e32 v112, v117
	v_rcp_f32_e32 v117, v113
	v_rcp_f32_e32 v113, v118
	v_rcp_f32_e32 v118, v119
	v_rcp_f32_e32 v119, v114
	v_rcp_f32_e32 v115, v115
	v_cvt_pk_bf16_f32 v112, v116, v112
	v_cvt_pk_bf16_f32 v113, v113, v118
	v_cvt_pk_bf16_f32 v114, v120, v117
	v_cvt_pk_bf16_f32 v115, v119, v115
	global_store_dwordx4 v[146:147], v[112:115], off offset:256
	global_load_dwordx4 v[112:115], v[144:145], off
	s_nop 0
	global_load_dwordx4 v[116:119], v[144:145], off offset:16
	v_or_b32_e32 v120, 16, v148
	v_ashrrev_i32_e32 v121, 31, v120
	v_lshlrev_b64 v[120:121], 12, v[120:121]
	v_lshl_add_u64 v[120:121], s[6:7], 0, v[120:121]
	v_lshl_add_u64 v[120:121], v[120:121], 0, v[150:151]
	s_waitcnt vmcnt(0)
	v_add_f32_e32 v108, v108, v112
	v_add_f32_e32 v104, v104, v116
	v_add_f32_e32 v109, v109, v113
	v_add_f32_e32 v105, v105, v117
	v_add_f32_e32 v110, v110, v114
	v_add_f32_e32 v106, v106, v118
	v_add_f32_e32 v111, v111, v115
	v_add_f32_e32 v107, v107, v119
	v_mul_f32_e32 v108, 0xbfb8aa3b, v108
	v_mul_f32_e32 v104, 0xbfb8aa3b, v104
	v_mul_f32_e32 v109, 0xbfb8aa3b, v109
	v_mul_f32_e32 v105, 0xbfb8aa3b, v105
	v_mul_f32_e32 v110, 0xbfb8aa3b, v110
	v_mul_f32_e32 v106, 0xbfb8aa3b, v106
	v_mul_f32_e32 v111, 0xbfb8aa3b, v111
	v_mul_f32_e32 v107, 0xbfb8aa3b, v107
	v_exp_f32_e32 v108, v108
	v_exp_f32_e32 v104, v104
	v_exp_f32_e32 v109, v109
	v_exp_f32_e32 v105, v105
	v_exp_f32_e32 v110, v110
	v_exp_f32_e32 v106, v106
	v_exp_f32_e32 v111, v111
	v_exp_f32_e32 v107, v107
	v_add_f32_e32 v108, 1.0, v108
	v_add_f32_e32 v104, 1.0, v104
	v_add_f32_e32 v109, 1.0, v109
	v_add_f32_e32 v105, 1.0, v105
	v_add_f32_e32 v110, 1.0, v110
	v_add_f32_e32 v106, 1.0, v106
	v_add_f32_e32 v111, 1.0, v111
	v_add_f32_e32 v107, 1.0, v107
	v_rcp_f32_e32 v108, v108
	v_rcp_f32_e32 v112, v104
	v_rcp_f32_e32 v104, v109
	v_rcp_f32_e32 v109, v105
	v_rcp_f32_e32 v105, v110
	v_rcp_f32_e32 v110, v111
	v_rcp_f32_e32 v111, v106
	v_rcp_f32_e32 v107, v107
	v_cvt_pk_bf16_f32 v104, v108, v104
	v_cvt_pk_bf16_f32 v105, v105, v110
	v_cvt_pk_bf16_f32 v106, v112, v109
	v_cvt_pk_bf16_f32 v107, v111, v107
	global_store_dwordx4 v[120:121], v[104:107], off
	global_load_dwordx4 v[104:107], v[144:145], off offset:512
	s_nop 0
	global_load_dwordx4 v[108:111], v[144:145], off offset:528
	s_waitcnt vmcnt(0)
	v_add_f32_e32 v100, v100, v104
	v_add_f32_e32 v96, v96, v108
	v_add_f32_e32 v101, v101, v105
	v_add_f32_e32 v97, v97, v109
	v_add_f32_e32 v102, v102, v106
	v_add_f32_e32 v98, v98, v110
	v_add_f32_e32 v103, v103, v107
	v_add_f32_e32 v99, v99, v111
	v_mul_f32_e32 v100, 0xbfb8aa3b, v100
	v_mul_f32_e32 v96, 0xbfb8aa3b, v96
	v_mul_f32_e32 v101, 0xbfb8aa3b, v101
	v_mul_f32_e32 v97, 0xbfb8aa3b, v97
	v_mul_f32_e32 v102, 0xbfb8aa3b, v102
	v_mul_f32_e32 v98, 0xbfb8aa3b, v98
	v_mul_f32_e32 v103, 0xbfb8aa3b, v103
	v_mul_f32_e32 v99, 0xbfb8aa3b, v99
	v_exp_f32_e32 v100, v100
	v_exp_f32_e32 v96, v96
	v_exp_f32_e32 v101, v101
	v_exp_f32_e32 v97, v97
	v_exp_f32_e32 v102, v102
	v_exp_f32_e32 v98, v98
	v_exp_f32_e32 v103, v103
	v_exp_f32_e32 v99, v99
	v_add_f32_e32 v100, 1.0, v100
	v_add_f32_e32 v96, 1.0, v96
	v_add_f32_e32 v101, 1.0, v101
	v_add_f32_e32 v97, 1.0, v97
	v_add_f32_e32 v102, 1.0, v102
	v_add_f32_e32 v98, 1.0, v98
	v_add_f32_e32 v103, 1.0, v103
	v_add_f32_e32 v99, 1.0, v99
	v_rcp_f32_e32 v100, v100
	v_rcp_f32_e32 v104, v96
	v_rcp_f32_e32 v96, v101
	v_rcp_f32_e32 v101, v97
	v_rcp_f32_e32 v97, v102
	v_rcp_f32_e32 v102, v103
	v_rcp_f32_e32 v103, v98
	v_rcp_f32_e32 v99, v99
	v_cvt_pk_bf16_f32 v96, v100, v96
	v_cvt_pk_bf16_f32 v97, v97, v102
	v_cvt_pk_bf16_f32 v98, v104, v101
	v_cvt_pk_bf16_f32 v99, v103, v99
	global_store_dwordx4 v[120:121], v[96:99], off offset:256
	global_load_dwordx4 v[96:99], v[144:145], off
	s_nop 0
	global_load_dwordx4 v[100:103], v[144:145], off offset:16
	v_or_b32_e32 v104, 32, v148
	v_ashrrev_i32_e32 v105, 31, v104
	v_lshlrev_b64 v[104:105], 12, v[104:105]
	v_lshl_add_u64 v[104:105], s[6:7], 0, v[104:105]
	v_lshl_add_u64 v[104:105], v[104:105], 0, v[150:151]
	s_waitcnt vmcnt(0)
	v_add_f32_e32 v92, v92, v96
	v_add_f32_e32 v88, v88, v100
	v_add_f32_e32 v93, v93, v97
	v_add_f32_e32 v89, v89, v101
	v_add_f32_e32 v94, v94, v98
	v_add_f32_e32 v90, v90, v102
	v_add_f32_e32 v95, v95, v99
	v_add_f32_e32 v91, v91, v103
	v_mul_f32_e32 v92, 0xbfb8aa3b, v92
	v_mul_f32_e32 v88, 0xbfb8aa3b, v88
	v_mul_f32_e32 v93, 0xbfb8aa3b, v93
	v_mul_f32_e32 v89, 0xbfb8aa3b, v89
	v_mul_f32_e32 v94, 0xbfb8aa3b, v94
	v_mul_f32_e32 v90, 0xbfb8aa3b, v90
	v_mul_f32_e32 v95, 0xbfb8aa3b, v95
	v_mul_f32_e32 v91, 0xbfb8aa3b, v91
	v_exp_f32_e32 v92, v92
	v_exp_f32_e32 v88, v88
	v_exp_f32_e32 v93, v93
	v_exp_f32_e32 v89, v89
	v_exp_f32_e32 v94, v94
	v_exp_f32_e32 v90, v90
	v_exp_f32_e32 v95, v95
	v_exp_f32_e32 v91, v91
	v_add_f32_e32 v92, 1.0, v92
	v_add_f32_e32 v88, 1.0, v88
	v_add_f32_e32 v93, 1.0, v93
	v_add_f32_e32 v89, 1.0, v89
	v_add_f32_e32 v94, 1.0, v94
	v_add_f32_e32 v90, 1.0, v90
	v_add_f32_e32 v95, 1.0, v95
	v_add_f32_e32 v91, 1.0, v91
	v_rcp_f32_e32 v92, v92
	v_rcp_f32_e32 v96, v88
	v_rcp_f32_e32 v88, v93
	v_rcp_f32_e32 v93, v89
	v_rcp_f32_e32 v89, v94
	v_rcp_f32_e32 v94, v95
	v_rcp_f32_e32 v95, v90
	v_rcp_f32_e32 v91, v91
	v_cvt_pk_bf16_f32 v88, v92, v88
	v_cvt_pk_bf16_f32 v89, v89, v94
	v_cvt_pk_bf16_f32 v90, v96, v93
	v_cvt_pk_bf16_f32 v91, v95, v91
	global_store_dwordx4 v[104:105], v[88:91], off
	global_load_dwordx4 v[88:91], v[144:145], off offset:512
	s_nop 0
	global_load_dwordx4 v[92:95], v[144:145], off offset:528
	s_waitcnt vmcnt(0)
	v_add_f32_e32 v84, v84, v88
	v_add_f32_e32 v80, v80, v92
	v_add_f32_e32 v85, v85, v89
	v_add_f32_e32 v81, v81, v93
	v_add_f32_e32 v86, v86, v90
	v_add_f32_e32 v82, v82, v94
	v_add_f32_e32 v87, v87, v91
	v_add_f32_e32 v83, v83, v95
	v_mul_f32_e32 v84, 0xbfb8aa3b, v84
	v_mul_f32_e32 v80, 0xbfb8aa3b, v80
	v_mul_f32_e32 v85, 0xbfb8aa3b, v85
	v_mul_f32_e32 v81, 0xbfb8aa3b, v81
	v_mul_f32_e32 v86, 0xbfb8aa3b, v86
	v_mul_f32_e32 v82, 0xbfb8aa3b, v82
	v_mul_f32_e32 v87, 0xbfb8aa3b, v87
	v_mul_f32_e32 v83, 0xbfb8aa3b, v83
	v_exp_f32_e32 v84, v84
	v_exp_f32_e32 v80, v80
	v_exp_f32_e32 v85, v85
	v_exp_f32_e32 v81, v81
	v_exp_f32_e32 v86, v86
	v_exp_f32_e32 v82, v82
	v_exp_f32_e32 v87, v87
	v_exp_f32_e32 v83, v83
	v_add_f32_e32 v84, 1.0, v84
	v_add_f32_e32 v80, 1.0, v80
	v_add_f32_e32 v85, 1.0, v85
	v_add_f32_e32 v81, 1.0, v81
	v_add_f32_e32 v86, 1.0, v86
	v_add_f32_e32 v82, 1.0, v82
	v_add_f32_e32 v87, 1.0, v87
	v_add_f32_e32 v83, 1.0, v83
	v_rcp_f32_e32 v84, v84
	v_rcp_f32_e32 v88, v80
	v_rcp_f32_e32 v80, v85
	v_rcp_f32_e32 v85, v81
	v_rcp_f32_e32 v81, v86
	v_rcp_f32_e32 v86, v87
	v_rcp_f32_e32 v87, v82
	v_rcp_f32_e32 v83, v83
	v_cvt_pk_bf16_f32 v80, v84, v80
	v_cvt_pk_bf16_f32 v81, v81, v86
	v_cvt_pk_bf16_f32 v82, v88, v85
	v_cvt_pk_bf16_f32 v83, v87, v83
	global_store_dwordx4 v[104:105], v[80:83], off offset:256
	global_load_dwordx4 v[80:83], v[144:145], off
	s_nop 0
	global_load_dwordx4 v[84:87], v[144:145], off offset:16
	v_or_b32_e32 v88, 48, v148
	v_ashrrev_i32_e32 v89, 31, v88
	v_lshlrev_b64 v[88:89], 12, v[88:89]
	v_lshl_add_u64 v[88:89], s[6:7], 0, v[88:89]
	v_lshl_add_u64 v[88:89], v[88:89], 0, v[150:151]
	s_waitcnt vmcnt(0)
	v_add_f32_e32 v76, v76, v80
	v_add_f32_e32 v72, v72, v84
	v_add_f32_e32 v77, v77, v81
	v_add_f32_e32 v73, v73, v85
	v_add_f32_e32 v78, v78, v82
	v_add_f32_e32 v74, v74, v86
	v_add_f32_e32 v79, v79, v83
	v_add_f32_e32 v75, v75, v87
	v_mul_f32_e32 v76, 0xbfb8aa3b, v76
	v_mul_f32_e32 v72, 0xbfb8aa3b, v72
	v_mul_f32_e32 v77, 0xbfb8aa3b, v77
	v_mul_f32_e32 v73, 0xbfb8aa3b, v73
	v_mul_f32_e32 v78, 0xbfb8aa3b, v78
	v_mul_f32_e32 v74, 0xbfb8aa3b, v74
	v_mul_f32_e32 v79, 0xbfb8aa3b, v79
	v_mul_f32_e32 v75, 0xbfb8aa3b, v75
	v_exp_f32_e32 v76, v76
	v_exp_f32_e32 v72, v72
	v_exp_f32_e32 v77, v77
	v_exp_f32_e32 v73, v73
	v_exp_f32_e32 v78, v78
	v_exp_f32_e32 v74, v74
	v_exp_f32_e32 v79, v79
	v_exp_f32_e32 v75, v75
	v_add_f32_e32 v76, 1.0, v76
	v_add_f32_e32 v72, 1.0, v72
	v_add_f32_e32 v77, 1.0, v77
	v_add_f32_e32 v73, 1.0, v73
	v_add_f32_e32 v78, 1.0, v78
	v_add_f32_e32 v74, 1.0, v74
	v_add_f32_e32 v79, 1.0, v79
	v_add_f32_e32 v75, 1.0, v75
	v_rcp_f32_e32 v76, v76
	v_rcp_f32_e32 v80, v72
	v_rcp_f32_e32 v72, v77
	v_rcp_f32_e32 v77, v73
	v_rcp_f32_e32 v73, v78
	v_rcp_f32_e32 v78, v79
	v_rcp_f32_e32 v79, v74
	v_rcp_f32_e32 v75, v75
	v_cvt_pk_bf16_f32 v72, v76, v72
	v_cvt_pk_bf16_f32 v73, v73, v78
	v_cvt_pk_bf16_f32 v74, v80, v77
	v_cvt_pk_bf16_f32 v75, v79, v75
	global_store_dwordx4 v[88:89], v[72:75], off
	global_load_dwordx4 v[72:75], v[144:145], off offset:512
	s_nop 0
	global_load_dwordx4 v[76:79], v[144:145], off offset:528
	s_waitcnt vmcnt(0)
	v_add_f32_e32 v68, v68, v72
	v_add_f32_e32 v64, v64, v76
	v_add_f32_e32 v69, v69, v73
	v_add_f32_e32 v65, v65, v77
	v_add_f32_e32 v70, v70, v74
	v_add_f32_e32 v66, v66, v78
	v_add_f32_e32 v71, v71, v75
	v_add_f32_e32 v67, v67, v79
	v_mul_f32_e32 v68, 0xbfb8aa3b, v68
	v_mul_f32_e32 v64, 0xbfb8aa3b, v64
	v_mul_f32_e32 v69, 0xbfb8aa3b, v69
	v_mul_f32_e32 v65, 0xbfb8aa3b, v65
	v_mul_f32_e32 v70, 0xbfb8aa3b, v70
	v_mul_f32_e32 v66, 0xbfb8aa3b, v66
	v_mul_f32_e32 v71, 0xbfb8aa3b, v71
	v_mul_f32_e32 v67, 0xbfb8aa3b, v67
	v_exp_f32_e32 v68, v68
	v_exp_f32_e32 v64, v64
	v_exp_f32_e32 v69, v69
	v_exp_f32_e32 v65, v65
	v_exp_f32_e32 v70, v70
	v_exp_f32_e32 v66, v66
	v_exp_f32_e32 v71, v71
	v_exp_f32_e32 v67, v67
	v_add_f32_e32 v68, 1.0, v68
	v_add_f32_e32 v64, 1.0, v64
	v_add_f32_e32 v69, 1.0, v69
	v_add_f32_e32 v65, 1.0, v65
	v_add_f32_e32 v70, 1.0, v70
	v_add_f32_e32 v66, 1.0, v66
	v_add_f32_e32 v71, 1.0, v71
	v_add_f32_e32 v67, 1.0, v67
	v_rcp_f32_e32 v68, v68
	v_rcp_f32_e32 v72, v64
	v_rcp_f32_e32 v64, v69
	v_rcp_f32_e32 v69, v65
	v_rcp_f32_e32 v65, v70
	v_rcp_f32_e32 v70, v71
	v_rcp_f32_e32 v71, v66
	v_rcp_f32_e32 v67, v67
	v_cvt_pk_bf16_f32 v64, v68, v64
	v_cvt_pk_bf16_f32 v65, v65, v70
	v_cvt_pk_bf16_f32 v66, v72, v69
	v_cvt_pk_bf16_f32 v67, v71, v67
	global_store_dwordx4 v[88:89], v[64:67], off offset:256
	global_load_dwordx4 v[64:67], v[144:145], off
	s_nop 0
	global_load_dwordx4 v[68:71], v[144:145], off offset:16
	v_add_co_u32_e32 v72, vcc, s74, v146
	s_waitcnt vmcnt(0)
	v_add_f32_e32 v60, v60, v64
	v_add_f32_e32 v56, v56, v68
	v_add_f32_e32 v61, v61, v65
	v_add_f32_e32 v57, v57, v69
	v_add_f32_e32 v62, v62, v66
	v_add_f32_e32 v58, v58, v70
	v_add_f32_e32 v63, v63, v67
	v_add_f32_e32 v59, v59, v71
	v_mul_f32_e32 v60, 0xbfb8aa3b, v60
	v_mul_f32_e32 v56, 0xbfb8aa3b, v56
	v_mul_f32_e32 v61, 0xbfb8aa3b, v61
	v_mul_f32_e32 v57, 0xbfb8aa3b, v57
	v_mul_f32_e32 v62, 0xbfb8aa3b, v62
	v_mul_f32_e32 v58, 0xbfb8aa3b, v58
	v_mul_f32_e32 v63, 0xbfb8aa3b, v63
	v_mul_f32_e32 v59, 0xbfb8aa3b, v59
	v_exp_f32_e32 v60, v60
	v_exp_f32_e32 v56, v56
	v_exp_f32_e32 v61, v61
	v_exp_f32_e32 v57, v57
	v_exp_f32_e32 v62, v62
	v_exp_f32_e32 v58, v58
	v_exp_f32_e32 v63, v63
	v_exp_f32_e32 v59, v59
	v_add_f32_e32 v60, 1.0, v60
	v_add_f32_e32 v56, 1.0, v56
	v_add_f32_e32 v61, 1.0, v61
	v_add_f32_e32 v57, 1.0, v57
	v_add_f32_e32 v62, 1.0, v62
	v_add_f32_e32 v58, 1.0, v58
	v_add_f32_e32 v63, 1.0, v63
	v_add_f32_e32 v59, 1.0, v59
	v_rcp_f32_e32 v60, v60
	v_rcp_f32_e32 v64, v56
	v_rcp_f32_e32 v56, v61
	v_rcp_f32_e32 v61, v57
	v_rcp_f32_e32 v57, v62
	v_rcp_f32_e32 v62, v63
	v_rcp_f32_e32 v63, v58
	v_rcp_f32_e32 v59, v59
	v_addc_co_u32_e32 v73, vcc, 0, v147, vcc
	v_cvt_pk_bf16_f32 v56, v60, v56
	v_cvt_pk_bf16_f32 v57, v57, v62
	v_cvt_pk_bf16_f32 v58, v64, v61
	v_cvt_pk_bf16_f32 v59, v63, v59
	global_store_dwordx4 v[72:73], v[56:59], off
	global_load_dwordx4 v[56:59], v[144:145], off offset:512
	s_nop 0
	global_load_dwordx4 v[60:63], v[144:145], off offset:528
	v_lshl_add_u64 v[64:65], v[146:147], 0, s[14:15]
	s_waitcnt vmcnt(0)
	v_add_f32_e32 v52, v52, v56
	v_add_f32_e32 v48, v48, v60
	v_add_f32_e32 v53, v53, v57
	v_add_f32_e32 v49, v49, v61
	v_add_f32_e32 v54, v54, v58
	v_add_f32_e32 v50, v50, v62
	v_add_f32_e32 v55, v55, v59
	v_add_f32_e32 v51, v51, v63
	v_mul_f32_e32 v52, 0xbfb8aa3b, v52
	v_mul_f32_e32 v48, 0xbfb8aa3b, v48
	v_mul_f32_e32 v53, 0xbfb8aa3b, v53
	v_mul_f32_e32 v49, 0xbfb8aa3b, v49
	v_mul_f32_e32 v54, 0xbfb8aa3b, v54
	v_mul_f32_e32 v50, 0xbfb8aa3b, v50
	v_mul_f32_e32 v55, 0xbfb8aa3b, v55
	v_mul_f32_e32 v51, 0xbfb8aa3b, v51
	v_exp_f32_e32 v52, v52
	v_exp_f32_e32 v48, v48
	v_exp_f32_e32 v53, v53
	v_exp_f32_e32 v49, v49
	v_exp_f32_e32 v54, v54
	v_exp_f32_e32 v50, v50
	v_exp_f32_e32 v55, v55
	v_exp_f32_e32 v51, v51
	v_add_f32_e32 v52, 1.0, v52
	v_add_f32_e32 v48, 1.0, v48
	v_add_f32_e32 v53, 1.0, v53
	v_add_f32_e32 v49, 1.0, v49
	v_add_f32_e32 v54, 1.0, v54
	v_add_f32_e32 v50, 1.0, v50
	v_add_f32_e32 v55, 1.0, v55
	v_add_f32_e32 v51, 1.0, v51
	v_rcp_f32_e32 v52, v52
	v_rcp_f32_e32 v56, v48
	v_rcp_f32_e32 v48, v53
	v_rcp_f32_e32 v53, v49
	v_rcp_f32_e32 v49, v54
	v_rcp_f32_e32 v54, v55
	v_rcp_f32_e32 v55, v50
	v_rcp_f32_e32 v51, v51
	v_cvt_pk_bf16_f32 v48, v52, v48
	v_cvt_pk_bf16_f32 v49, v49, v54
	v_cvt_pk_bf16_f32 v50, v56, v53
	v_cvt_pk_bf16_f32 v51, v55, v51
	global_store_dwordx4 v[64:65], v[48:51], off offset:256
	global_load_dwordx4 v[48:51], v[144:145], off
	s_nop 0
	global_load_dwordx4 v[52:55], v[144:145], off offset:16
	v_add_co_u32_e32 v56, vcc, s75, v146
	s_waitcnt vmcnt(0)
	v_add_f32_e32 v44, v44, v48
	v_add_f32_e32 v40, v40, v52
	v_add_f32_e32 v45, v45, v49
	v_add_f32_e32 v41, v41, v53
	v_add_f32_e32 v46, v46, v50
	v_add_f32_e32 v42, v42, v54
	v_add_f32_e32 v47, v47, v51
	v_add_f32_e32 v43, v43, v55
	v_mul_f32_e32 v44, 0xbfb8aa3b, v44
	v_mul_f32_e32 v40, 0xbfb8aa3b, v40
	v_mul_f32_e32 v45, 0xbfb8aa3b, v45
	v_mul_f32_e32 v41, 0xbfb8aa3b, v41
	v_mul_f32_e32 v46, 0xbfb8aa3b, v46
	v_mul_f32_e32 v42, 0xbfb8aa3b, v42
	v_mul_f32_e32 v47, 0xbfb8aa3b, v47
	v_mul_f32_e32 v43, 0xbfb8aa3b, v43
	v_exp_f32_e32 v44, v44
	v_exp_f32_e32 v40, v40
	v_exp_f32_e32 v45, v45
	v_exp_f32_e32 v41, v41
	v_exp_f32_e32 v46, v46
	v_exp_f32_e32 v42, v42
	v_exp_f32_e32 v47, v47
	v_exp_f32_e32 v43, v43
	v_add_f32_e32 v44, 1.0, v44
	v_add_f32_e32 v40, 1.0, v40
	v_add_f32_e32 v45, 1.0, v45
	v_add_f32_e32 v41, 1.0, v41
	v_add_f32_e32 v46, 1.0, v46
	v_add_f32_e32 v42, 1.0, v42
	v_add_f32_e32 v47, 1.0, v47
	v_add_f32_e32 v43, 1.0, v43
	v_rcp_f32_e32 v44, v44
	v_rcp_f32_e32 v48, v40
	v_rcp_f32_e32 v40, v45
	v_rcp_f32_e32 v45, v41
	v_rcp_f32_e32 v41, v46
	v_rcp_f32_e32 v46, v47
	v_rcp_f32_e32 v47, v42
	v_rcp_f32_e32 v43, v43
	v_addc_co_u32_e32 v57, vcc, 0, v147, vcc
	v_cvt_pk_bf16_f32 v40, v44, v40
	v_cvt_pk_bf16_f32 v41, v41, v46
	v_cvt_pk_bf16_f32 v42, v48, v45
	v_cvt_pk_bf16_f32 v43, v47, v43
	global_store_dwordx4 v[56:57], v[40:43], off
	global_load_dwordx4 v[40:43], v[144:145], off offset:512
	s_nop 0
	global_load_dwordx4 v[44:47], v[144:145], off offset:528
	v_lshl_add_u64 v[48:49], v[146:147], 0, s[24:25]
	s_waitcnt vmcnt(0)
	v_add_f32_e32 v36, v36, v40
	v_add_f32_e32 v32, v32, v44
	v_add_f32_e32 v37, v37, v41
	v_add_f32_e32 v33, v33, v45
	v_add_f32_e32 v38, v38, v42
	v_add_f32_e32 v34, v34, v46
	v_add_f32_e32 v39, v39, v43
	v_add_f32_e32 v35, v35, v47
	v_mul_f32_e32 v36, 0xbfb8aa3b, v36
	v_mul_f32_e32 v32, 0xbfb8aa3b, v32
	v_mul_f32_e32 v37, 0xbfb8aa3b, v37
	v_mul_f32_e32 v33, 0xbfb8aa3b, v33
	v_mul_f32_e32 v38, 0xbfb8aa3b, v38
	v_mul_f32_e32 v34, 0xbfb8aa3b, v34
	v_mul_f32_e32 v39, 0xbfb8aa3b, v39
	v_mul_f32_e32 v35, 0xbfb8aa3b, v35
	v_exp_f32_e32 v36, v36
	v_exp_f32_e32 v32, v32
	v_exp_f32_e32 v37, v37
	v_exp_f32_e32 v33, v33
	v_exp_f32_e32 v38, v38
	v_exp_f32_e32 v34, v34
	v_exp_f32_e32 v39, v39
	v_exp_f32_e32 v35, v35
	v_add_f32_e32 v36, 1.0, v36
	v_add_f32_e32 v32, 1.0, v32
	v_add_f32_e32 v37, 1.0, v37
	v_add_f32_e32 v33, 1.0, v33
	v_add_f32_e32 v38, 1.0, v38
	v_add_f32_e32 v34, 1.0, v34
	v_add_f32_e32 v39, 1.0, v39
	v_add_f32_e32 v35, 1.0, v35
	v_rcp_f32_e32 v36, v36
	v_rcp_f32_e32 v40, v32
	v_rcp_f32_e32 v32, v37
	v_rcp_f32_e32 v37, v33
	v_rcp_f32_e32 v33, v38
	v_rcp_f32_e32 v38, v39
	v_rcp_f32_e32 v39, v34
	v_rcp_f32_e32 v35, v35
	v_cvt_pk_bf16_f32 v32, v36, v32
	v_cvt_pk_bf16_f32 v33, v33, v38
	v_cvt_pk_bf16_f32 v34, v40, v37
	v_cvt_pk_bf16_f32 v35, v39, v35
	global_store_dwordx4 v[48:49], v[32:35], off offset:256
	global_load_dwordx4 v[32:35], v[144:145], off
	s_nop 0
	global_load_dwordx4 v[36:39], v[144:145], off offset:16
	v_add_co_u32_e32 v40, vcc, s76, v146
	s_waitcnt vmcnt(0)
	v_add_f32_e32 v28, v28, v32
	v_add_f32_e32 v24, v24, v36
	v_add_f32_e32 v29, v29, v33
	v_add_f32_e32 v25, v25, v37
	v_add_f32_e32 v30, v30, v34
	v_add_f32_e32 v26, v26, v38
	v_add_f32_e32 v31, v31, v35
	v_add_f32_e32 v27, v27, v39
	v_mul_f32_e32 v28, 0xbfb8aa3b, v28
	v_mul_f32_e32 v24, 0xbfb8aa3b, v24
	v_mul_f32_e32 v29, 0xbfb8aa3b, v29
	v_mul_f32_e32 v25, 0xbfb8aa3b, v25
	v_mul_f32_e32 v30, 0xbfb8aa3b, v30
	v_mul_f32_e32 v26, 0xbfb8aa3b, v26
	v_mul_f32_e32 v31, 0xbfb8aa3b, v31
	v_mul_f32_e32 v27, 0xbfb8aa3b, v27
	v_exp_f32_e32 v28, v28
	v_exp_f32_e32 v24, v24
	v_exp_f32_e32 v29, v29
	v_exp_f32_e32 v25, v25
	v_exp_f32_e32 v30, v30
	v_exp_f32_e32 v26, v26
	v_exp_f32_e32 v31, v31
	v_exp_f32_e32 v27, v27
	v_add_f32_e32 v28, 1.0, v28
	v_add_f32_e32 v24, 1.0, v24
	v_add_f32_e32 v29, 1.0, v29
	v_add_f32_e32 v25, 1.0, v25
	v_add_f32_e32 v30, 1.0, v30
	v_add_f32_e32 v26, 1.0, v26
	v_add_f32_e32 v31, 1.0, v31
	v_add_f32_e32 v27, 1.0, v27
	v_rcp_f32_e32 v28, v28
	v_rcp_f32_e32 v32, v24
	v_rcp_f32_e32 v24, v29
	v_rcp_f32_e32 v29, v25
	v_rcp_f32_e32 v25, v30
	v_rcp_f32_e32 v30, v31
	v_rcp_f32_e32 v31, v26
	v_rcp_f32_e32 v27, v27
	v_addc_co_u32_e32 v41, vcc, 0, v147, vcc
	v_cvt_pk_bf16_f32 v24, v28, v24
	v_cvt_pk_bf16_f32 v25, v25, v30
	v_cvt_pk_bf16_f32 v26, v32, v29
	v_cvt_pk_bf16_f32 v27, v31, v27
	global_store_dwordx4 v[40:41], v[24:27], off
	global_load_dwordx4 v[24:27], v[144:145], off offset:512
	s_nop 0
	global_load_dwordx4 v[28:31], v[144:145], off offset:528
	v_lshl_add_u64 v[32:33], v[146:147], 0, s[40:41]
	s_waitcnt vmcnt(0)
	v_add_f32_e32 v20, v20, v24
	v_add_f32_e32 v16, v16, v28
	v_add_f32_e32 v21, v21, v25
	v_add_f32_e32 v17, v17, v29
	v_add_f32_e32 v22, v22, v26
	v_add_f32_e32 v18, v18, v30
	v_add_f32_e32 v23, v23, v27
	v_add_f32_e32 v19, v19, v31
	v_mul_f32_e32 v20, 0xbfb8aa3b, v20
	v_mul_f32_e32 v16, 0xbfb8aa3b, v16
	v_mul_f32_e32 v21, 0xbfb8aa3b, v21
	v_mul_f32_e32 v17, 0xbfb8aa3b, v17
	v_mul_f32_e32 v22, 0xbfb8aa3b, v22
	v_mul_f32_e32 v18, 0xbfb8aa3b, v18
	v_mul_f32_e32 v23, 0xbfb8aa3b, v23
	v_mul_f32_e32 v19, 0xbfb8aa3b, v19
	v_exp_f32_e32 v20, v20
	v_exp_f32_e32 v16, v16
	v_exp_f32_e32 v21, v21
	v_exp_f32_e32 v17, v17
	v_exp_f32_e32 v22, v22
	v_exp_f32_e32 v18, v18
	v_exp_f32_e32 v23, v23
	v_exp_f32_e32 v19, v19
	v_add_f32_e32 v20, 1.0, v20
	v_add_f32_e32 v16, 1.0, v16
	v_add_f32_e32 v21, 1.0, v21
	v_add_f32_e32 v17, 1.0, v17
	v_add_f32_e32 v22, 1.0, v22
	v_add_f32_e32 v18, 1.0, v18
	v_add_f32_e32 v23, 1.0, v23
	v_add_f32_e32 v19, 1.0, v19
	v_rcp_f32_e32 v20, v20
	v_rcp_f32_e32 v24, v16
	v_rcp_f32_e32 v16, v21
	v_rcp_f32_e32 v21, v17
	v_rcp_f32_e32 v17, v22
	v_rcp_f32_e32 v22, v23
	v_rcp_f32_e32 v23, v18
	v_rcp_f32_e32 v19, v19
	v_cvt_pk_bf16_f32 v16, v20, v16
	v_cvt_pk_bf16_f32 v17, v17, v22
	v_cvt_pk_bf16_f32 v18, v24, v21
	v_cvt_pk_bf16_f32 v19, v23, v19
	global_store_dwordx4 v[32:33], v[16:19], off offset:256
	global_load_dwordx4 v[16:19], v[144:145], off
	s_nop 0
	global_load_dwordx4 v[20:23], v[144:145], off offset:16
	v_add_co_u32_e32 v24, vcc, s77, v146
	s_waitcnt vmcnt(0)
	v_add_f32_e32 v12, v12, v16
	v_add_f32_e32 v8, v8, v20
	v_add_f32_e32 v13, v13, v17
	v_add_f32_e32 v9, v9, v21
	v_add_f32_e32 v14, v14, v18
	v_add_f32_e32 v10, v10, v22
	v_add_f32_e32 v15, v15, v19
	v_add_f32_e32 v11, v11, v23
	v_mul_f32_e32 v12, 0xbfb8aa3b, v12
	v_mul_f32_e32 v8, 0xbfb8aa3b, v8
	v_mul_f32_e32 v13, 0xbfb8aa3b, v13
	v_mul_f32_e32 v9, 0xbfb8aa3b, v9
	v_mul_f32_e32 v14, 0xbfb8aa3b, v14
	v_mul_f32_e32 v10, 0xbfb8aa3b, v10
	v_mul_f32_e32 v15, 0xbfb8aa3b, v15
	v_mul_f32_e32 v11, 0xbfb8aa3b, v11
	v_exp_f32_e32 v12, v12
	v_exp_f32_e32 v8, v8
	v_exp_f32_e32 v13, v13
	v_exp_f32_e32 v9, v9
	v_exp_f32_e32 v14, v14
	v_exp_f32_e32 v10, v10
	v_exp_f32_e32 v15, v15
	v_exp_f32_e32 v11, v11
	v_add_f32_e32 v12, 1.0, v12
	v_add_f32_e32 v8, 1.0, v8
	v_add_f32_e32 v13, 1.0, v13
	v_add_f32_e32 v9, 1.0, v9
	v_add_f32_e32 v14, 1.0, v14
	v_add_f32_e32 v10, 1.0, v10
	v_add_f32_e32 v15, 1.0, v15
	v_add_f32_e32 v11, 1.0, v11
	v_rcp_f32_e32 v12, v12
	v_rcp_f32_e32 v16, v8
	v_rcp_f32_e32 v8, v13
	v_rcp_f32_e32 v13, v9
	v_rcp_f32_e32 v9, v14
	v_rcp_f32_e32 v14, v15
	v_rcp_f32_e32 v15, v10
	v_rcp_f32_e32 v11, v11
	v_addc_co_u32_e32 v25, vcc, 0, v147, vcc
	v_cvt_pk_bf16_f32 v8, v12, v8
	v_cvt_pk_bf16_f32 v9, v9, v14
	v_cvt_pk_bf16_f32 v10, v16, v13
	v_cvt_pk_bf16_f32 v11, v15, v11
	global_store_dwordx4 v[24:25], v[8:11], off
	global_load_dwordx4 v[8:11], v[144:145], off offset:512
	s_nop 0
	global_load_dwordx4 v[12:15], v[144:145], off offset:528
	s_and_b64 vcc, exec, s[4:5]
	v_lshl_add_u64 v[16:17], v[146:147], 0, s[46:47]
	s_waitcnt vmcnt(0)
	v_add_f32_e32 v4, v4, v8
	v_add_f32_e32 v0, v0, v12
	v_add_f32_e32 v5, v5, v9
	v_add_f32_e32 v1, v1, v13
	v_add_f32_e32 v6, v6, v10
	v_add_f32_e32 v2, v2, v14
	v_add_f32_e32 v7, v7, v11
	v_add_f32_e32 v3, v3, v15
	v_mul_f32_e32 v4, 0xbfb8aa3b, v4
	v_mul_f32_e32 v0, 0xbfb8aa3b, v0
	v_mul_f32_e32 v5, 0xbfb8aa3b, v5
	v_mul_f32_e32 v1, 0xbfb8aa3b, v1
	v_mul_f32_e32 v6, 0xbfb8aa3b, v6
	v_mul_f32_e32 v2, 0xbfb8aa3b, v2
	v_mul_f32_e32 v7, 0xbfb8aa3b, v7
	v_mul_f32_e32 v3, 0xbfb8aa3b, v3
	v_exp_f32_e32 v4, v4
	v_exp_f32_e32 v0, v0
	v_exp_f32_e32 v5, v5
	v_exp_f32_e32 v1, v1
	v_exp_f32_e32 v6, v6
	v_exp_f32_e32 v2, v2
	v_exp_f32_e32 v7, v7
	v_exp_f32_e32 v3, v3
	v_add_f32_e32 v4, 1.0, v4
	v_add_f32_e32 v0, 1.0, v0
	v_add_f32_e32 v5, 1.0, v5
	v_add_f32_e32 v1, 1.0, v1
	v_add_f32_e32 v6, 1.0, v6
	v_add_f32_e32 v2, 1.0, v2
	v_add_f32_e32 v7, 1.0, v7
	v_add_f32_e32 v3, 1.0, v3
	v_rcp_f32_e32 v4, v4
	v_rcp_f32_e32 v8, v0
	v_rcp_f32_e32 v0, v5
	v_rcp_f32_e32 v5, v1
	v_rcp_f32_e32 v1, v6
	v_rcp_f32_e32 v6, v7
	v_rcp_f32_e32 v7, v2
	v_rcp_f32_e32 v3, v3
	v_cvt_pk_bf16_f32 v0, v4, v0
	v_cvt_pk_bf16_f32 v1, v1, v6
	v_cvt_pk_bf16_f32 v2, v8, v5
	v_cvt_pk_bf16_f32 v3, v7, v3
	global_store_dwordx4 v[16:17], v[0:3], off offset:256
	s_cbranch_vccz .LBB0_566
	s_waitcnt vmcnt(0)
	v_readlane_b32 s78, v228, 33
	s_cmpk_gt_u32 s0, 0xff
	v_readlane_b32 s76, v228, 32
	v_readlane_b32 s79, v228, 34
	v_readlane_b32 s77, v228, 35
	s_cbranch_scc1 .LBB0_573
	s_barrier

.LBB0_574:
	s_waitcnt lgkmcnt(0)
	s_barrier
	s_setprio 0
	s_and_saveexec_b64 s[4:5], s[80:81]
	s_cbranch_execz .LBB0_584
	buffer_wbl2 sc1
	s_waitcnt vmcnt(0)
	s_load_dwordx2 s[8:9], s[78:79], -0x8
	s_load_dword s0, s[78:79], 0x0
	v_mov_b32_e32 v0, 0
	v_mov_b32_e32 v1, 1
	v_mov_b32_e32 v3, 0
	s_mov_b64 s[14:15], 0
	s_waitcnt lgkmcnt(0)
	s_add_u32 s8, s8, 0x2300080
	s_addc_u32 s9, s9, 0
	s_mul_i32 s0, s0, 5
	global_atomic_add v0, v1, s[8:9]

.LBB0_587:
	s_lshl_b32 s20, s20, 5
	s_and_b32 s41, s20, 0x60
	s_mov_b64 s[20:21], 0x80
	s_add_i32 m0, s35, 0x18000
	v_lshl_add_u64 v[6:7], v[6:7], 0, s[20:21]
	s_lshl_b32 s40, s5, 13
	s_lshl_b32 s44, s41, 7
	s_waitcnt vmcnt(4)
	s_barrier
	global_load_lds_dwordx4 v[6:7], off
	v_lshl_add_u64 v[4:5], v[4:5], 0, s[20:21]
	s_add_i32 m0, s35, 0x1a000
	s_add_i32 s59, s35, 0x8000
	s_add_i32 s60, s35, 0xa000
	global_load_lds_dwordx4 v[4:5], off
	v_lshl_add_u64 v[2:3], v[2:3], 0, s[20:21]
	s_mov_b32 m0, s59
	s_add_u32 s24, s52, 0x20080
	global_load_lds_dwordx4 v[2:3], off
	v_lshl_add_u64 v[0:1], v[0:1], 0, s[20:21]
	s_mov_b32 m0, s60
	s_addc_u32 s25, s53, 0
	global_load_lds_dwordx4 v[0:1], off
	s_add_i32 m0, s35, 0x1c000
	v_lshl_add_u64 v[0:1], s[24:25], 0, v[132:133]
	global_load_lds_dwordx4 v[0:1], off
	v_lshl_add_u64 v[0:1], s[24:25], 0, v[128:129]
	s_add_i32 m0, s35, 0x1e000
	s_add_i32 s62, 0, 0x10000
	global_load_lds_dwordx4 v[0:1], off
	v_lshrrev_b32_e32 v1, 1, v9
	v_and_b32_e32 v1, 24, v1
	v_and_b32_e32 v0, 15, v9
	v_lshlrev_b32_e32 v2, 1, v1
	v_lshl_or_b32 v148, s5, 6, v0
	v_lshl_or_b32 v0, v0, 6, v2
	v_lshlrev_b32_e32 v2, 2, v9
	v_and_b32_e32 v2, 32, v2
	v_bitop3_b32 v3, v0, s40, v2 bitop3:0xde
	v_bitop3_b32 v149, v0, s44, v2 bitop3:0xde
	v_lshlrev_b32_e32 v0, 13, v13
	v_and_b32_e32 v0, 0xffffc000, v0
	v_or_b32_e32 v150, s41, v1
	v_lshl_add_u32 v0, v12, 10, v0
	v_and_b32_e32 v1, 1, v13
	v_lshl_or_b32 v0, v1, 6, v0
	v_lshl_add_u32 v136, v14, 1, v0
	v_lshlrev_b32_e32 v0, 13, v8
	v_and_b32_e32 v0, 0xffffc000, v0
	s_waitcnt vmcnt(6)
	v_lshl_add_u32 v0, v10, 10, v0
	v_and_b32_e32 v1, 1, v8
	v_lshl_or_b32 v0, v1, 6, v0
	s_sext_i32_i8 s63, s4
	s_ashr_i32 s61, s3, 31
	v_mov_b32_e32 v137, v133
	v_lshl_add_u32 v138, v11, 1, v0
	v_mov_b32_e32 v139, v133
	v_mov_b64_e32 v[140:141], 0x600
	v_mov_b64_e32 v[142:143], 0x5ff
	v_add_u32_e32 v151, s62, v149
	v_add_u32_e32 v152, 0, v3
	v_add_u32_e32 v153, s72, v149
	s_barrier
	v_readfirstlane_b32 s4, v154
	s_bitcmp1_b32 s4, 8
	s_cbranch_scc0 .Lprio_588
	s_setprio 1
.Lprio_588:
.LBB0_588:
	s_add_i32 s58, s58, 1
	s_mul_i32 s4, s58, s61
	s_mul_hi_u32 s5, s58, s3
	s_add_i32 s5, s5, s4
	s_mul_i32 s4, s58, s3
	s_add_u32 s44, s4, s2
	s_addc_u32 s45, s5, s33
	v_cmp_gt_i64_e64 s[4:5], s[44:45], v[142:143]
	s_and_b64 vcc, exec, s[4:5]
	s_cbranch_vccnz .LBB0_590
	s_ashr_i32 s24, s44, 31
	s_lshr_b32 s24, s24, 29
	s_add_i32 s24, s44, s24
	s_ashr_i32 s25, s24, 3
	s_and_b32 s24, s24, -8
	s_sub_i32 s24, s44, s24
	s_cmp_lt_i32 s24, 0
	s_cselect_b32 s40, s34, 0xc0
	s_mul_i32 s24, s40, s24
	s_add_i32 s24, s24, s25
	s_ashr_i32 s25, s24, 31
	s_lshr_b32 s25, s25, 27
	s_add_i32 s25, s24, s25
	s_ashr_i32 s40, s25, 5
	s_lshl_b32 s40, s40, 3
	s_sub_i32 s41, 0x180, s40
	s_min_i32 s41, s41, 8
	s_abs_i32 s46, s41
	v_cvt_f32_u32_e32 v0, s46
	s_sub_i32 s54, 0, s46
	s_andn2_b32 s25, s25, 31
	s_sub_i32 s25, s24, s25
	v_rcp_iflag_f32_e32 v0, v0
	s_abs_i32 s24, s25
	s_xor_b32 s47, s25, s41
	s_ashr_i32 s47, s47, 31
	v_mul_f32_e32 v0, 0x4f7ffffe, v0
	v_cvt_u32_f32_e32 v0, v0
	s_nop 0
	v_readfirstlane_b32 s55, v0
	s_mul_i32 s54, s54, s55
	s_mul_hi_u32 s54, s55, s54
	s_add_i32 s55, s55, s54
	s_mul_hi_u32 s54, s24, s55
	s_mul_i32 s55, s54, s46
	s_sub_i32 s24, s24, s55
	s_add_i32 s64, s54, 1
	s_sub_i32 s55, s24, s46
	s_cmp_ge_u32 s24, s46
	s_cselect_b32 s54, s64, s54
	s_cselect_b32 s24, s55, s24
	s_add_i32 s55, s54, 1
	s_cmp_ge_u32 s24, s46
	s_cselect_b32 s24, s55, s54
	s_xor_b32 s24, s24, s47
	s_sub_i32 s24, s24, s47
	s_mul_i32 s41, s24, s41
	s_sub_i32 s25, s25, s41
	s_add_i32 s40, s25, s40

.LBB0_591:
	ds_read_b128 v[144:147], v151
	ds_read_b128 v[156:159], v151 offset:1024
	ds_read_b128 v[160:163], v151 offset:2048
	ds_read_b128 v[164:167], v151 offset:3072
	s_add_u32 s52, s50, 0xfffe0080
	s_addc_u32 s53, s51, -1
	s_cmp_eq_u32 s68, 4
	s_cselect_b32 s55, s41, s53
	s_cselect_b32 s54, s64, s52
	s_cselect_b32 s53, s25, s67
	s_cselect_b32 s52, s65, s66
	v_lshl_add_u64 v[200:201], s[50:51], 0, v[136:137]
	s_add_i32 m0, s35, 0xc000
	ds_read_b128 v[168:171], v152
	ds_read_b128 v[172:175], v152 offset:1024
	ds_read_b128 v[176:179], v152 offset:2048
	ds_read_b128 v[180:183], v152 offset:3072
	ds_read_b128 v[184:187], v152 offset:4096
	ds_read_b128 v[188:191], v152 offset:5120
	ds_read_b128 v[192:195], v152 offset:6144
	ds_read_b128 v[196:199], v152 offset:7168
	global_load_lds_dwordx4 v[200:201], off
	v_lshl_add_u64 v[200:201], s[50:51], 0, v[138:139]
	s_add_i32 m0, s35, 0xe000
	s_nop 0
	global_load_lds_dwordx4 v[200:201], off
	s_waitcnt lgkmcnt(8)
	s_barrier
	s_waitcnt lgkmcnt(0)
	s_waitcnt lgkmcnt(0)
	v_mfma_f32_16x16x32_bf16 v[124:127], v[144:147], v[168:171], v[124:127]
	v_mfma_f32_16x16x32_bf16 v[120:123], v[160:163], v[168:171], v[120:123]
	v_mfma_f32_16x16x32_bf16 v[108:111], v[144:147], v[176:179], v[108:111]
	v_mfma_f32_16x16x32_bf16 v[104:107], v[160:163], v[176:179], v[104:107]
	v_mfma_f32_16x16x32_bf16 v[92:95], v[144:147], v[184:187], v[92:95]
	v_mfma_f32_16x16x32_bf16 v[88:91], v[160:163], v[184:187], v[88:91]
	v_mfma_f32_16x16x32_bf16 v[76:79], v[144:147], v[192:195], v[76:79]
	v_mfma_f32_16x16x32_bf16 v[72:75], v[160:163], v[192:195], v[72:75]
	v_mfma_f32_16x16x32_bf16 v[124:127], v[156:159], v[172:175], v[124:127]
	v_mfma_f32_16x16x32_bf16 v[120:123], v[164:167], v[172:175], v[120:123]
	v_mfma_f32_16x16x32_bf16 v[108:111], v[156:159], v[180:183], v[108:111]
	v_mfma_f32_16x16x32_bf16 v[104:107], v[164:167], v[180:183], v[104:107]
	v_mfma_f32_16x16x32_bf16 v[92:95], v[156:159], v[188:191], v[92:95]
	v_mfma_f32_16x16x32_bf16 v[88:91], v[164:167], v[188:191], v[88:91]
	v_mfma_f32_16x16x32_bf16 v[76:79], v[156:159], v[196:199], v[76:79]
	v_mfma_f32_16x16x32_bf16 v[72:75], v[164:167], v[196:199], v[72:75]
	s_barrier
	s_add_i32 s69, s62, s1
	v_lshl_add_u64 v[216:217], s[52:53], 0, v[132:133]
	s_mov_b32 m0, s69
	ds_read_b128 v[200:203], v153
	ds_read_b128 v[204:207], v153 offset:1024
	ds_read_b128 v[208:211], v153 offset:2048
	ds_read_b128 v[212:215], v153 offset:3072
	global_load_lds_dwordx4 v[216:217], off
	v_lshl_add_u64 v[218:219], s[52:53], 0, v[128:129]
	s_add_i32 m0, s69, 0x2000
	s_nop 0
	global_load_lds_dwordx4 v[218:219], off
	s_barrier
	s_waitcnt lgkmcnt(0)
	s_waitcnt lgkmcnt(0)
	v_mfma_f32_16x16x32_bf16 v[116:119], v[200:203], v[168:171], v[116:119]
	v_mfma_f32_16x16x32_bf16 v[112:115], v[208:211], v[168:171], v[112:115]
	v_mfma_f32_16x16x32_bf16 v[100:103], v[200:203], v[176:179], v[100:103]
	v_mfma_f32_16x16x32_bf16 v[96:99], v[208:211], v[176:179], v[96:99]
	v_mfma_f32_16x16x32_bf16 v[84:87], v[200:203], v[184:187], v[84:87]
	v_mfma_f32_16x16x32_bf16 v[80:83], v[208:211], v[184:187], v[80:83]
	v_mfma_f32_16x16x32_bf16 v[68:71], v[200:203], v[192:195], v[68:71]
	v_mfma_f32_16x16x32_bf16 v[64:67], v[208:211], v[192:195], v[64:67]
	v_mfma_f32_16x16x32_bf16 v[116:119], v[204:207], v[172:175], v[116:119]
	v_mfma_f32_16x16x32_bf16 v[112:115], v[212:215], v[172:175], v[112:115]
	v_mfma_f32_16x16x32_bf16 v[100:103], v[204:207], v[180:183], v[100:103]
	v_mfma_f32_16x16x32_bf16 v[96:99], v[212:215], v[180:183], v[96:99]
	v_mfma_f32_16x16x32_bf16 v[84:87], v[204:207], v[188:191], v[84:87]
	v_mfma_f32_16x16x32_bf16 v[80:83], v[212:215], v[188:191], v[80:83]
	v_mfma_f32_16x16x32_bf16 v[68:71], v[204:207], v[196:199], v[68:71]
	v_mfma_f32_16x16x32_bf16 v[64:67], v[212:215], v[196:199], v[64:67]
	s_mov_b32 m0, s35
	v_lshl_add_u64 v[220:221], s[54:55], 0, v[134:135]
	s_barrier
	ds_read_b128 v[168:171], v152 offset:16384
	ds_read_b128 v[172:175], v152 offset:17408
	ds_read_b128 v[176:179], v152 offset:18432
	ds_read_b128 v[180:183], v152 offset:19456
	ds_read_b128 v[184:187], v152 offset:20480
	ds_read_b128 v[188:191], v152 offset:21504
	ds_read_b128 v[192:195], v152 offset:22528
	ds_read_b128 v[196:199], v152 offset:23552
	global_load_lds_dwordx4 v[220:221], off
	v_lshl_add_u64 v[222:223], s[54:55], 0, v[130:131]
	s_mov_b32 m0, s49
	s_nop 0
	global_load_lds_dwordx4 v[222:223], off
	s_barrier
	s_waitcnt lgkmcnt(0)
	s_waitcnt lgkmcnt(0)
	v_mfma_f32_16x16x32_bf16 v[60:63], v[144:147], v[168:171], v[60:63]
	v_mfma_f32_16x16x32_bf16 v[56:59], v[160:163], v[168:171], v[56:59]
	v_mfma_f32_16x16x32_bf16 v[44:47], v[144:147], v[176:179], v[44:47]
	v_mfma_f32_16x16x32_bf16 v[40:43], v[160:163], v[176:179], v[40:43]
	v_mfma_f32_16x16x32_bf16 v[28:31], v[144:147], v[184:187], v[28:31]
	v_mfma_f32_16x16x32_bf16 v[24:27], v[160:163], v[184:187], v[24:27]
	v_mfma_f32_16x16x32_bf16 v[12:15], v[144:147], v[192:195], v[12:15]
	v_mfma_f32_16x16x32_bf16 v[8:11], v[160:163], v[192:195], v[8:11]
	v_mfma_f32_16x16x32_bf16 v[60:63], v[156:159], v[172:175], v[60:63]
	v_mfma_f32_16x16x32_bf16 v[56:59], v[164:167], v[172:175], v[56:59]
	v_mfma_f32_16x16x32_bf16 v[44:47], v[156:159], v[180:183], v[44:47]
	v_mfma_f32_16x16x32_bf16 v[40:43], v[164:167], v[180:183], v[40:43]
	v_mfma_f32_16x16x32_bf16 v[28:31], v[156:159], v[188:191], v[28:31]
	v_mfma_f32_16x16x32_bf16 v[24:27], v[164:167], v[188:191], v[24:27]
	v_mfma_f32_16x16x32_bf16 v[12:15], v[156:159], v[196:199], v[12:15]
	v_mfma_f32_16x16x32_bf16 v[8:11], v[164:167], v[196:199], v[8:11]
	s_barrier
	s_add_u32 s70, s52, 0x20000
	s_addc_u32 s71, s53, 0
	s_add_i32 s69, s72, s1
	v_lshl_add_u64 v[144:145], s[70:71], 0, v[132:133]
	s_mov_b32 m0, s69
	s_nop 0
	global_load_lds_dwordx4 v[144:145], off
	v_lshl_add_u64 v[144:145], s[70:71], 0, v[128:129]
	s_add_i32 m0, s69, 0x2000
	s_nop 0
	global_load_lds_dwordx4 v[144:145], off
	s_waitcnt vmcnt(6)
	s_barrier
	v_mfma_f32_16x16x32_bf16 v[52:55], v[200:203], v[168:171], v[52:55]
	v_mfma_f32_16x16x32_bf16 v[48:51], v[208:211], v[168:171], v[48:51]
	v_mfma_f32_16x16x32_bf16 v[36:39], v[200:203], v[176:179], v[36:39]
	v_mfma_f32_16x16x32_bf16 v[32:35], v[208:211], v[176:179], v[32:35]
	v_mfma_f32_16x16x32_bf16 v[20:23], v[200:203], v[184:187], v[20:23]
	v_mfma_f32_16x16x32_bf16 v[16:19], v[208:211], v[184:187], v[16:19]
	v_mfma_f32_16x16x32_bf16 v[4:7], v[200:203], v[192:195], v[4:7]
	v_mfma_f32_16x16x32_bf16 v[0:3], v[208:211], v[192:195], v[0:3]
	v_mfma_f32_16x16x32_bf16 v[52:55], v[204:207], v[172:175], v[52:55]
	v_mfma_f32_16x16x32_bf16 v[48:51], v[212:215], v[172:175], v[48:51]
	v_mfma_f32_16x16x32_bf16 v[36:39], v[204:207], v[180:183], v[36:39]
	v_mfma_f32_16x16x32_bf16 v[32:35], v[212:215], v[180:183], v[32:35]
	v_mfma_f32_16x16x32_bf16 v[20:23], v[204:207], v[188:191], v[20:23]
	v_mfma_f32_16x16x32_bf16 v[16:19], v[212:215], v[188:191], v[16:19]
	v_mfma_f32_16x16x32_bf16 v[4:7], v[204:207], v[196:199], v[4:7]
	v_mfma_f32_16x16x32_bf16 v[0:3], v[212:215], v[196:199], v[0:3]
	s_add_i32 s69, 0, 0x18000
	v_add_u32_e32 v164, s69, v149
	s_barrier
	ds_read_b128 v[144:147], v164
	ds_read_b128 v[156:159], v164 offset:1024
	ds_read_b128 v[160:163], v164 offset:2048
	ds_read_b128 v[164:167], v164 offset:3072
	s_add_u32 s54, s54, 0x20000
	s_addc_u32 s55, s55, 0
	s_mov_b32 m0, s56
	v_lshl_add_u64 v[200:201], s[54:55], 0, v[134:135]
	ds_read_b128 v[168:171], v152 offset:32768
	ds_read_b128 v[172:175], v152 offset:33792
	ds_read_b128 v[176:179], v152 offset:34816
	ds_read_b128 v[180:183], v152 offset:35840
	ds_read_b128 v[184:187], v152 offset:36864
	ds_read_b128 v[188:191], v152 offset:37888
	ds_read_b128 v[192:195], v152 offset:38912
	ds_read_b128 v[196:199], v152 offset:39936
	global_load_lds_dwordx4 v[200:201], off
	v_lshl_add_u64 v[200:201], s[54:55], 0, v[130:131]
	s_mov_b32 m0, s57
	s_nop 0
	global_load_lds_dwordx4 v[200:201], off
	s_waitcnt lgkmcnt(8)
	s_barrier
	s_waitcnt lgkmcnt(0)
	s_waitcnt lgkmcnt(0)
	v_mfma_f32_16x16x32_bf16 v[124:127], v[144:147], v[168:171], v[124:127]
	v_mfma_f32_16x16x32_bf16 v[120:123], v[160:163], v[168:171], v[120:123]
	v_mfma_f32_16x16x32_bf16 v[108:111], v[144:147], v[176:179], v[108:111]
	v_mfma_f32_16x16x32_bf16 v[104:107], v[160:163], v[176:179], v[104:107]
	v_mfma_f32_16x16x32_bf16 v[92:95], v[144:147], v[184:187], v[92:95]
	v_mfma_f32_16x16x32_bf16 v[88:91], v[160:163], v[184:187], v[88:91]
	v_mfma_f32_16x16x32_bf16 v[76:79], v[144:147], v[192:195], v[76:79]
	v_mfma_f32_16x16x32_bf16 v[72:75], v[160:163], v[192:195], v[72:75]
	v_mfma_f32_16x16x32_bf16 v[124:127], v[156:159], v[172:175], v[124:127]
	v_mfma_f32_16x16x32_bf16 v[120:123], v[164:167], v[172:175], v[120:123]
	v_mfma_f32_16x16x32_bf16 v[108:111], v[156:159], v[180:183], v[108:111]
	v_mfma_f32_16x16x32_bf16 v[104:107], v[164:167], v[180:183], v[104:107]
	v_mfma_f32_16x16x32_bf16 v[92:95], v[156:159], v[188:191], v[92:95]
	v_mfma_f32_16x16x32_bf16 v[88:91], v[164:167], v[188:191], v[88:91]
	v_mfma_f32_16x16x32_bf16 v[76:79], v[156:159], v[196:199], v[76:79]
	v_mfma_f32_16x16x32_bf16 v[72:75], v[164:167], v[196:199], v[72:75]
	s_barrier
	s_add_i32 s54, s69, s1
	v_add_u32_e32 v212, s97, v149
	v_lshl_add_u64 v[216:217], v[216:217], 0, s[20:21]
	s_mov_b32 m0, s54
	ds_read_b128 v[200:203], v212
	ds_read_b128 v[204:207], v212 offset:1024
	ds_read_b128 v[208:211], v212 offset:2048
	ds_read_b128 v[212:215], v212 offset:3072
	global_load_lds_dwordx4 v[216:217], off
	v_lshl_add_u64 v[216:217], v[218:219], 0, s[20:21]
	s_add_i32 m0, s54, 0x2000
	s_nop 0
	global_load_lds_dwordx4 v[216:217], off
	s_barrier
	s_waitcnt lgkmcnt(0)
	s_waitcnt lgkmcnt(0)
	v_mfma_f32_16x16x32_bf16 v[116:119], v[200:203], v[168:171], v[116:119]
	v_mfma_f32_16x16x32_bf16 v[112:115], v[208:211], v[168:171], v[112:115]
	v_mfma_f32_16x16x32_bf16 v[100:103], v[200:203], v[176:179], v[100:103]
	v_mfma_f32_16x16x32_bf16 v[96:99], v[208:211], v[176:179], v[96:99]
	v_mfma_f32_16x16x32_bf16 v[84:87], v[200:203], v[184:187], v[84:87]
	v_mfma_f32_16x16x32_bf16 v[80:83], v[208:211], v[184:187], v[80:83]
	v_mfma_f32_16x16x32_bf16 v[68:71], v[200:203], v[192:195], v[68:71]
	v_mfma_f32_16x16x32_bf16 v[64:67], v[208:211], v[192:195], v[64:67]
	v_mfma_f32_16x16x32_bf16 v[116:119], v[204:207], v[172:175], v[116:119]
	v_mfma_f32_16x16x32_bf16 v[112:115], v[212:215], v[172:175], v[112:115]
	v_mfma_f32_16x16x32_bf16 v[100:103], v[204:207], v[180:183], v[100:103]
	v_mfma_f32_16x16x32_bf16 v[96:99], v[212:215], v[180:183], v[96:99]
	v_mfma_f32_16x16x32_bf16 v[84:87], v[204:207], v[188:191], v[84:87]
	v_mfma_f32_16x16x32_bf16 v[80:83], v[212:215], v[188:191], v[80:83]
	v_mfma_f32_16x16x32_bf16 v[68:71], v[204:207], v[196:199], v[68:71]
	v_mfma_f32_16x16x32_bf16 v[64:67], v[212:215], v[196:199], v[64:67]
	s_mov_b32 m0, s59
	v_lshl_add_u64 v[216:217], v[220:221], 0, s[20:21]
	s_barrier
	ds_read_b128 v[168:171], v152 offset:49152
	ds_read_b128 v[172:175], v152 offset:50176
	ds_read_b128 v[176:179], v152 offset:51200
	ds_read_b128 v[180:183], v152 offset:52224
	ds_read_b128 v[184:187], v152 offset:53248
	ds_read_b128 v[188:191], v152 offset:54272
	ds_read_b128 v[192:195], v152 offset:55296
	ds_read_b128 v[196:199], v152 offset:56320
	global_load_lds_dwordx4 v[216:217], off
	v_lshl_add_u64 v[216:217], v[222:223], 0, s[20:21]
	s_mov_b32 m0, s60
	s_nop 0
	global_load_lds_dwordx4 v[216:217], off
	s_barrier
	s_waitcnt lgkmcnt(0)
	s_waitcnt lgkmcnt(0)
	v_mfma_f32_16x16x32_bf16 v[60:63], v[144:147], v[168:171], v[60:63]
	v_mfma_f32_16x16x32_bf16 v[56:59], v[160:163], v[168:171], v[56:59]
	v_mfma_f32_16x16x32_bf16 v[44:47], v[144:147], v[176:179], v[44:47]
	v_mfma_f32_16x16x32_bf16 v[40:43], v[160:163], v[176:179], v[40:43]
	v_mfma_f32_16x16x32_bf16 v[28:31], v[144:147], v[184:187], v[28:31]
	v_mfma_f32_16x16x32_bf16 v[24:27], v[160:163], v[184:187], v[24:27]
	v_mfma_f32_16x16x32_bf16 v[12:15], v[144:147], v[192:195], v[12:15]
	v_mfma_f32_16x16x32_bf16 v[8:11], v[160:163], v[192:195], v[8:11]
	v_mfma_f32_16x16x32_bf16 v[60:63], v[156:159], v[172:175], v[60:63]
	v_mfma_f32_16x16x32_bf16 v[56:59], v[164:167], v[172:175], v[56:59]
	v_mfma_f32_16x16x32_bf16 v[44:47], v[156:159], v[180:183], v[44:47]
	v_mfma_f32_16x16x32_bf16 v[40:43], v[164:167], v[180:183], v[40:43]
	v_mfma_f32_16x16x32_bf16 v[28:31], v[156:159], v[188:191], v[28:31]
	v_mfma_f32_16x16x32_bf16 v[24:27], v[164:167], v[188:191], v[24:27]
	v_mfma_f32_16x16x32_bf16 v[12:15], v[156:159], v[196:199], v[12:15]
	v_mfma_f32_16x16x32_bf16 v[8:11], v[164:167], v[196:199], v[8:11]
	s_barrier
	s_add_u32 s52, s52, 0x20080
	s_addc_u32 s53, s53, 0
	s_add_i32 s54, s97, s1
	v_lshl_add_u64 v[144:145], s[52:53], 0, v[132:133]
	s_mov_b32 m0, s54
	s_nop 0
	global_load_lds_dwordx4 v[144:145], off
	v_lshl_add_u64 v[144:145], s[52:53], 0, v[128:129]
	s_add_i32 m0, s54, 0x2000
	s_nop 0
	global_load_lds_dwordx4 v[144:145], off
	s_waitcnt vmcnt(6)
	s_barrier
	v_mfma_f32_16x16x32_bf16 v[52:55], v[200:203], v[168:171], v[52:55]
	v_mfma_f32_16x16x32_bf16 v[48:51], v[208:211], v[168:171], v[48:51]
	v_mfma_f32_16x16x32_bf16 v[36:39], v[200:203], v[176:179], v[36:39]
	v_mfma_f32_16x16x32_bf16 v[32:35], v[208:211], v[176:179], v[32:35]
	v_mfma_f32_16x16x32_bf16 v[20:23], v[200:203], v[184:187], v[20:23]
	v_mfma_f32_16x16x32_bf16 v[16:19], v[208:211], v[184:187], v[16:19]
	v_mfma_f32_16x16x32_bf16 v[4:7], v[200:203], v[192:195], v[4:7]
	v_mfma_f32_16x16x32_bf16 v[0:3], v[208:211], v[192:195], v[0:3]
	v_mfma_f32_16x16x32_bf16 v[52:55], v[204:207], v[172:175], v[52:55]
	v_mfma_f32_16x16x32_bf16 v[48:51], v[212:215], v[172:175], v[48:51]
	v_mfma_f32_16x16x32_bf16 v[36:39], v[204:207], v[180:183], v[36:39]
	v_mfma_f32_16x16x32_bf16 v[32:35], v[212:215], v[180:183], v[32:35]
	v_mfma_f32_16x16x32_bf16 v[20:23], v[204:207], v[188:191], v[20:23]
	v_mfma_f32_16x16x32_bf16 v[16:19], v[212:215], v[188:191], v[16:19]
	v_mfma_f32_16x16x32_bf16 v[4:7], v[204:207], v[196:199], v[4:7]
	v_mfma_f32_16x16x32_bf16 v[0:3], v[212:215], v[196:199], v[0:3]
	s_add_i32 s68, s68, 2
	s_add_u32 s50, s50, 0x100
	s_addc_u32 s51, s51, 0
	s_add_u32 s66, s66, 0x100
	s_addc_u32 s67, s67, 0
	s_cmp_gt_u32 s68, 5
	s_barrier
	s_cbranch_scc0 .LBB0_591
	v_lshl_add_u32 v146, s48, 8, v148
	v_lshl_or_b32 v144, s63, 8, v150
	v_ashrrev_i32_e32 v147, 31, v146
	v_lshlrev_b64 v[156:157], 12, v[146:147]
	v_ashrrev_i32_e32 v145, 31, v144
	v_lshl_add_u64 v[156:157], s[6:7], 0, v[156:157]
	v_lshlrev_b64 v[144:145], 1, v[144:145]
	v_lshl_add_u64 v[160:161], v[156:157], 0, v[144:145]
	global_load_dwordx4 v[156:159], v[160:161], off
	s_nop 0
	global_load_dwordx4 v[160:163], v[160:161], off offset:256
	v_or_b32_e32 v164, 16, v146
	v_lshlrev_b64 v[166:167], 11, v[146:147]
	v_ashrrev_i32_e32 v165, 31, v164
	v_lshl_add_u64 v[166:167], s[14:15], 0, v[166:167]
	v_lshlrev_b64 v[168:169], 12, v[164:165]
	v_lshl_add_u64 v[166:167], v[166:167], 0, v[144:145]
	v_lshl_add_u64 v[168:169], s[6:7], 0, v[168:169]
	v_lshl_add_u64 v[168:169], v[168:169], 0, v[144:145]
	s_and_b64 vcc, exec, s[4:5]
	s_mov_b32 s63, s24
	s_mov_b32 s48, s40
	s_mov_b64 s[52:53], s[46:47]
	s_mov_b64 s[50:51], s[44:45]
	s_waitcnt vmcnt(0)
	v_lshlrev_b32_e32 v170, 16, v156
	v_and_b32_e32 v171, 0xffff0000, v156
	v_lshlrev_b32_e32 v156, 16, v157
	v_and_b32_e32 v157, 0xffff0000, v157
	v_lshlrev_b32_e32 v172, 16, v158
	v_and_b32_e32 v173, 0xffff0000, v158
	v_lshlrev_b32_e32 v158, 16, v159
	v_and_b32_e32 v159, 0xffff0000, v159
	v_lshlrev_b32_e32 v174, 16, v160
	v_and_b32_e32 v175, 0xffff0000, v160
	v_lshlrev_b32_e32 v160, 16, v161
	v_and_b32_e32 v161, 0xffff0000, v161
	v_lshlrev_b32_e32 v176, 16, v162
	v_and_b32_e32 v177, 0xffff0000, v162
	v_lshlrev_b32_e32 v162, 16, v163
	v_and_b32_e32 v163, 0xffff0000, v163
	v_pk_mul_f32 v[126:127], v[126:127], v[156:157]
	v_pk_mul_f32 v[124:125], v[124:125], v[170:171]
	v_pk_mul_f32 v[122:123], v[122:123], v[158:159]
	v_pk_mul_f32 v[120:121], v[120:121], v[172:173]
	v_pk_mul_f32 v[156:157], v[118:119], v[160:161]
	v_pk_mul_f32 v[158:159], v[116:117], v[174:175]
	v_cvt_pk_bf16_f32 v116, v124, v125
	v_cvt_pk_bf16_f32 v117, v126, v127
	v_cvt_pk_bf16_f32 v118, v120, v121
	v_cvt_pk_bf16_f32 v119, v122, v123
	v_pk_mul_f32 v[120:121], v[114:115], v[162:163]
	v_pk_mul_f32 v[114:115], v[112:113], v[176:177]
	global_store_dwordx4 v[166:167], v[116:119], off
	v_cvt_pk_bf16_f32 v112, v158, v159
	v_cvt_pk_bf16_f32 v113, v156, v157
	v_cvt_pk_bf16_f32 v114, v114, v115
	v_cvt_pk_bf16_f32 v115, v120, v121
	global_load_dwordx4 v[116:119], v[168:169], off
	v_or_b32_e32 v120, 32, v146
	global_store_dwordx4 v[166:167], v[112:115], off offset:256
	global_load_dwordx4 v[112:115], v[168:169], off offset:256
	v_ashrrev_i32_e32 v121, 31, v120
	v_lshlrev_b64 v[122:123], 11, v[164:165]
	v_lshlrev_b64 v[124:125], 12, v[120:121]
	v_lshl_add_u64 v[122:123], s[14:15], 0, v[122:123]
	v_lshl_add_u64 v[124:125], s[6:7], 0, v[124:125]
	v_lshl_add_u64 v[122:123], v[122:123], 0, v[144:145]
	v_lshl_add_u64 v[124:125], v[124:125], 0, v[144:145]
	s_waitcnt vmcnt(0)
	v_lshlrev_b32_e32 v126, 16, v116
	v_and_b32_e32 v127, 0xffff0000, v116
	v_lshlrev_b32_e32 v116, 16, v117
	v_and_b32_e32 v117, 0xffff0000, v117
	v_lshlrev_b32_e32 v156, 16, v118
	v_and_b32_e32 v157, 0xffff0000, v118
	v_lshlrev_b32_e32 v118, 16, v119
	v_and_b32_e32 v119, 0xffff0000, v119
	v_lshlrev_b32_e32 v158, 16, v112
	v_and_b32_e32 v159, 0xffff0000, v112
	v_lshlrev_b32_e32 v112, 16, v113
	v_and_b32_e32 v113, 0xffff0000, v113
	v_lshlrev_b32_e32 v160, 16, v114
	v_and_b32_e32 v161, 0xffff0000, v114
	v_lshlrev_b32_e32 v114, 16, v115
	v_and_b32_e32 v115, 0xffff0000, v115
	v_pk_mul_f32 v[110:111], v[110:111], v[116:117]
	v_pk_mul_f32 v[108:109], v[108:109], v[126:127]
	v_pk_mul_f32 v[106:107], v[106:107], v[118:119]
	v_pk_mul_f32 v[104:105], v[104:105], v[156:157]
	v_pk_mul_f32 v[112:113], v[102:103], v[112:113]
	v_pk_mul_f32 v[116:117], v[100:101], v[158:159]
	v_cvt_pk_bf16_f32 v100, v108, v109
	v_cvt_pk_bf16_f32 v101, v110, v111
	v_cvt_pk_bf16_f32 v102, v104, v105
	v_cvt_pk_bf16_f32 v103, v106, v107
	v_pk_mul_f32 v[104:105], v[98:99], v[114:115]
	v_pk_mul_f32 v[98:99], v[96:97], v[160:161]
	global_store_dwordx4 v[122:123], v[100:103], off
	v_cvt_pk_bf16_f32 v96, v116, v117
	v_cvt_pk_bf16_f32 v97, v112, v113
	v_cvt_pk_bf16_f32 v98, v98, v99
	v_cvt_pk_bf16_f32 v99, v104, v105
	global_load_dwordx4 v[100:103], v[124:125], off
	v_or_b32_e32 v104, 48, v146
	global_store_dwordx4 v[122:123], v[96:99], off offset:256
	global_load_dwordx4 v[96:99], v[124:125], off offset:256
	v_ashrrev_i32_e32 v105, 31, v104
	v_lshlrev_b64 v[106:107], 11, v[120:121]
	v_lshlrev_b64 v[108:109], 12, v[104:105]
	v_lshl_add_u64 v[106:107], s[14:15], 0, v[106:107]
	v_lshl_add_u64 v[108:109], s[6:7], 0, v[108:109]
	v_lshl_add_u64 v[106:107], v[106:107], 0, v[144:145]
	v_lshl_add_u64 v[108:109], v[108:109], 0, v[144:145]
	s_waitcnt vmcnt(0)
	v_lshlrev_b32_e32 v110, 16, v100
	v_and_b32_e32 v111, 0xffff0000, v100
	v_lshlrev_b32_e32 v100, 16, v101
	v_and_b32_e32 v101, 0xffff0000, v101
	v_lshlrev_b32_e32 v112, 16, v102
	v_and_b32_e32 v113, 0xffff0000, v102
	v_lshlrev_b32_e32 v102, 16, v103
	v_and_b32_e32 v103, 0xffff0000, v103
	v_lshlrev_b32_e32 v114, 16, v96
	v_and_b32_e32 v115, 0xffff0000, v96
	v_lshlrev_b32_e32 v96, 16, v97
	v_and_b32_e32 v97, 0xffff0000, v97
	v_lshlrev_b32_e32 v116, 16, v98
	v_and_b32_e32 v117, 0xffff0000, v98
	v_lshlrev_b32_e32 v98, 16, v99
	v_and_b32_e32 v99, 0xffff0000, v99
	v_pk_mul_f32 v[94:95], v[94:95], v[100:101]
	v_pk_mul_f32 v[92:93], v[92:93], v[110:111]
	v_pk_mul_f32 v[90:91], v[90:91], v[102:103]
	v_pk_mul_f32 v[88:89], v[88:89], v[112:113]
	v_pk_mul_f32 v[96:97], v[86:87], v[96:97]
	v_pk_mul_f32 v[100:101], v[84:85], v[114:115]
	v_cvt_pk_bf16_f32 v84, v92, v93
	v_cvt_pk_bf16_f32 v85, v94, v95
	v_cvt_pk_bf16_f32 v86, v88, v89
	v_cvt_pk_bf16_f32 v87, v90, v91
	v_pk_mul_f32 v[88:89], v[82:83], v[98:99]
	v_pk_mul_f32 v[82:83], v[80:81], v[116:117]
	global_store_dwordx4 v[106:107], v[84:87], off
	v_cvt_pk_bf16_f32 v80, v100, v101
	v_cvt_pk_bf16_f32 v81, v96, v97
	v_cvt_pk_bf16_f32 v82, v82, v83
	v_cvt_pk_bf16_f32 v83, v88, v89
	global_load_dwordx4 v[84:87], v[108:109], off
	v_add_u32_e32 v88, 0x80, v146
	global_store_dwordx4 v[106:107], v[80:83], off offset:256
	global_load_dwordx4 v[80:83], v[108:109], off offset:256
	v_ashrrev_i32_e32 v89, 31, v88
	v_lshlrev_b64 v[90:91], 11, v[104:105]
	v_lshlrev_b64 v[92:93], 12, v[88:89]
	v_lshl_add_u64 v[90:91], s[14:15], 0, v[90:91]
	v_lshl_add_u64 v[92:93], s[6:7], 0, v[92:93]
	v_lshl_add_u64 v[90:91], v[90:91], 0, v[144:145]
	v_lshl_add_u64 v[92:93], v[92:93], 0, v[144:145]
	s_waitcnt vmcnt(0)
	v_lshlrev_b32_e32 v94, 16, v84
	v_and_b32_e32 v95, 0xffff0000, v84
	v_lshlrev_b32_e32 v84, 16, v85
	v_and_b32_e32 v85, 0xffff0000, v85
	v_lshlrev_b32_e32 v96, 16, v86
	v_and_b32_e32 v97, 0xffff0000, v86
	v_lshlrev_b32_e32 v86, 16, v87
	v_and_b32_e32 v87, 0xffff0000, v87
	v_lshlrev_b32_e32 v98, 16, v80
	v_and_b32_e32 v99, 0xffff0000, v80
	v_lshlrev_b32_e32 v80, 16, v81
	v_and_b32_e32 v81, 0xffff0000, v81
	v_lshlrev_b32_e32 v100, 16, v82
	v_and_b32_e32 v101, 0xffff0000, v82
	v_lshlrev_b32_e32 v82, 16, v83
	v_and_b32_e32 v83, 0xffff0000, v83
	v_pk_mul_f32 v[78:79], v[78:79], v[84:85]
	v_pk_mul_f32 v[76:77], v[76:77], v[94:95]
	v_pk_mul_f32 v[74:75], v[74:75], v[86:87]
	v_pk_mul_f32 v[72:73], v[72:73], v[96:97]
	v_pk_mul_f32 v[80:81], v[70:71], v[80:81]
	v_pk_mul_f32 v[84:85], v[68:69], v[98:99]
	v_cvt_pk_bf16_f32 v68, v76, v77
	v_cvt_pk_bf16_f32 v69, v78, v79
	v_cvt_pk_bf16_f32 v70, v72, v73
	v_cvt_pk_bf16_f32 v71, v74, v75
	v_pk_mul_f32 v[72:73], v[66:67], v[82:83]
	v_pk_mul_f32 v[66:67], v[64:65], v[100:101]
	global_store_dwordx4 v[90:91], v[68:71], off
	v_cvt_pk_bf16_f32 v64, v84, v85
	v_cvt_pk_bf16_f32 v65, v80, v81
	v_cvt_pk_bf16_f32 v66, v66, v67
	v_cvt_pk_bf16_f32 v67, v72, v73
	global_load_dwordx4 v[68:71], v[92:93], off
	v_add_u32_e32 v72, 0x90, v146
	global_store_dwordx4 v[90:91], v[64:67], off offset:256
	global_load_dwordx4 v[64:67], v[92:93], off offset:256
	v_ashrrev_i32_e32 v73, 31, v72
	v_lshlrev_b64 v[74:75], 11, v[88:89]
	v_lshlrev_b64 v[76:77], 12, v[72:73]
	v_lshl_add_u64 v[74:75], s[14:15], 0, v[74:75]
	v_lshl_add_u64 v[76:77], s[6:7], 0, v[76:77]
	v_lshl_add_u64 v[74:75], v[74:75], 0, v[144:145]
	v_lshl_add_u64 v[76:77], v[76:77], 0, v[144:145]
	s_waitcnt vmcnt(0)
	v_lshlrev_b32_e32 v78, 16, v68
	v_and_b32_e32 v79, 0xffff0000, v68
	v_lshlrev_b32_e32 v68, 16, v69
	v_and_b32_e32 v69, 0xffff0000, v69
	v_lshlrev_b32_e32 v80, 16, v70
	v_and_b32_e32 v81, 0xffff0000, v70
	v_lshlrev_b32_e32 v70, 16, v71
	v_and_b32_e32 v71, 0xffff0000, v71
	v_lshlrev_b32_e32 v82, 16, v64
	v_and_b32_e32 v83, 0xffff0000, v64
	v_lshlrev_b32_e32 v64, 16, v65
	v_and_b32_e32 v65, 0xffff0000, v65
	v_lshlrev_b32_e32 v84, 16, v66
	v_and_b32_e32 v85, 0xffff0000, v66
	v_lshlrev_b32_e32 v66, 16, v67
	v_and_b32_e32 v67, 0xffff0000, v67
	v_pk_mul_f32 v[62:63], v[62:63], v[68:69]
	v_pk_mul_f32 v[60:61], v[60:61], v[78:79]
	v_pk_mul_f32 v[58:59], v[58:59], v[70:71]
	v_pk_mul_f32 v[56:57], v[56:57], v[80:81]
	v_pk_mul_f32 v[64:65], v[54:55], v[64:65]
	v_pk_mul_f32 v[68:69], v[52:53], v[82:83]
	v_cvt_pk_bf16_f32 v52, v60, v61
	v_cvt_pk_bf16_f32 v53, v62, v63
	v_cvt_pk_bf16_f32 v54, v56, v57
	v_cvt_pk_bf16_f32 v55, v58, v59
	v_pk_mul_f32 v[56:57], v[50:51], v[66:67]
	v_pk_mul_f32 v[50:51], v[48:49], v[84:85]
	global_store_dwordx4 v[74:75], v[52:55], off
	v_cvt_pk_bf16_f32 v48, v68, v69
	v_cvt_pk_bf16_f32 v49, v64, v65
	v_cvt_pk_bf16_f32 v50, v50, v51
	v_cvt_pk_bf16_f32 v51, v56, v57
	global_load_dwordx4 v[52:55], v[76:77], off
	v_add_u32_e32 v56, 0xa0, v146
	global_store_dwordx4 v[74:75], v[48:51], off offset:256
	global_load_dwordx4 v[48:51], v[76:77], off offset:256
	v_ashrrev_i32_e32 v57, 31, v56
	v_lshlrev_b64 v[58:59], 11, v[72:73]
	v_lshlrev_b64 v[60:61], 12, v[56:57]
	v_lshl_add_u64 v[58:59], s[14:15], 0, v[58:59]
	v_lshl_add_u64 v[60:61], s[6:7], 0, v[60:61]
	v_lshl_add_u64 v[58:59], v[58:59], 0, v[144:145]
	v_lshl_add_u64 v[60:61], v[60:61], 0, v[144:145]
	s_waitcnt vmcnt(0)
	v_lshlrev_b32_e32 v62, 16, v52
	v_and_b32_e32 v63, 0xffff0000, v52
	v_lshlrev_b32_e32 v52, 16, v53
	v_and_b32_e32 v53, 0xffff0000, v53
	v_lshlrev_b32_e32 v64, 16, v54
	v_and_b32_e32 v65, 0xffff0000, v54
	v_lshlrev_b32_e32 v54, 16, v55
	v_and_b32_e32 v55, 0xffff0000, v55
	v_lshlrev_b32_e32 v66, 16, v48
	v_and_b32_e32 v67, 0xffff0000, v48
	v_lshlrev_b32_e32 v48, 16, v49
	v_and_b32_e32 v49, 0xffff0000, v49
	v_lshlrev_b32_e32 v68, 16, v50
	v_and_b32_e32 v69, 0xffff0000, v50
	v_lshlrev_b32_e32 v50, 16, v51
	v_and_b32_e32 v51, 0xffff0000, v51
	v_pk_mul_f32 v[46:47], v[46:47], v[52:53]
	v_pk_mul_f32 v[44:45], v[44:45], v[62:63]
	v_pk_mul_f32 v[42:43], v[42:43], v[54:55]
	v_pk_mul_f32 v[40:41], v[40:41], v[64:65]
	v_pk_mul_f32 v[48:49], v[38:39], v[48:49]
	v_pk_mul_f32 v[52:53], v[36:37], v[66:67]
	v_cvt_pk_bf16_f32 v36, v44, v45
	v_cvt_pk_bf16_f32 v37, v46, v47
	v_cvt_pk_bf16_f32 v38, v40, v41
	v_cvt_pk_bf16_f32 v39, v42, v43
	v_pk_mul_f32 v[40:41], v[34:35], v[50:51]
	v_pk_mul_f32 v[34:35], v[32:33], v[68:69]
	global_store_dwordx4 v[58:59], v[36:39], off
	v_cvt_pk_bf16_f32 v32, v52, v53
	v_cvt_pk_bf16_f32 v33, v48, v49
	v_cvt_pk_bf16_f32 v34, v34, v35
	v_cvt_pk_bf16_f32 v35, v40, v41
	global_load_dwordx4 v[36:39], v[60:61], off
	v_add_u32_e32 v40, 0xb0, v146
	global_store_dwordx4 v[58:59], v[32:35], off offset:256
	global_load_dwordx4 v[32:35], v[60:61], off offset:256
	v_ashrrev_i32_e32 v41, 31, v40
	v_lshlrev_b64 v[42:43], 11, v[56:57]
	v_lshlrev_b64 v[44:45], 12, v[40:41]
	v_lshl_add_u64 v[42:43], s[14:15], 0, v[42:43]
	v_lshl_add_u64 v[44:45], s[6:7], 0, v[44:45]
	v_lshl_add_u64 v[42:43], v[42:43], 0, v[144:145]
	v_lshl_add_u64 v[44:45], v[44:45], 0, v[144:145]
	s_waitcnt vmcnt(0)
	v_lshlrev_b32_e32 v46, 16, v36
	v_and_b32_e32 v47, 0xffff0000, v36
	v_lshlrev_b32_e32 v36, 16, v37
	v_and_b32_e32 v37, 0xffff0000, v37
	v_lshlrev_b32_e32 v48, 16, v38
	v_and_b32_e32 v49, 0xffff0000, v38
	v_lshlrev_b32_e32 v38, 16, v39
	v_and_b32_e32 v39, 0xffff0000, v39
	v_lshlrev_b32_e32 v50, 16, v32
	v_and_b32_e32 v51, 0xffff0000, v32
	v_lshlrev_b32_e32 v32, 16, v33
	v_and_b32_e32 v33, 0xffff0000, v33
	v_lshlrev_b32_e32 v52, 16, v34
	v_and_b32_e32 v53, 0xffff0000, v34
	v_lshlrev_b32_e32 v34, 16, v35
	v_and_b32_e32 v35, 0xffff0000, v35
	v_pk_mul_f32 v[30:31], v[30:31], v[36:37]
	v_pk_mul_f32 v[28:29], v[28:29], v[46:47]
	v_pk_mul_f32 v[26:27], v[26:27], v[38:39]
	v_pk_mul_f32 v[24:25], v[24:25], v[48:49]
	v_pk_mul_f32 v[32:33], v[22:23], v[32:33]
	v_pk_mul_f32 v[36:37], v[20:21], v[50:51]
	v_cvt_pk_bf16_f32 v20, v28, v29
	v_cvt_pk_bf16_f32 v21, v30, v31
	v_cvt_pk_bf16_f32 v22, v24, v25
	v_cvt_pk_bf16_f32 v23, v26, v27
	v_pk_mul_f32 v[24:25], v[18:19], v[34:35]
	v_pk_mul_f32 v[18:19], v[16:17], v[52:53]
	global_store_dwordx4 v[42:43], v[20:23], off
	v_cvt_pk_bf16_f32 v16, v36, v37
	v_cvt_pk_bf16_f32 v17, v32, v33
	v_cvt_pk_bf16_f32 v18, v18, v19
	v_cvt_pk_bf16_f32 v19, v24, v25
	global_load_dwordx4 v[20:23], v[44:45], off
	v_lshlrev_b64 v[24:25], 11, v[40:41]
	global_store_dwordx4 v[42:43], v[16:19], off offset:256
	global_load_dwordx4 v[16:19], v[44:45], off offset:256
	v_lshl_add_u64 v[24:25], s[14:15], 0, v[24:25]
	v_lshl_add_u64 v[24:25], v[24:25], 0, v[144:145]
	s_waitcnt vmcnt(0)
	v_lshlrev_b32_e32 v26, 16, v20
	v_and_b32_e32 v27, 0xffff0000, v20
	v_lshlrev_b32_e32 v20, 16, v21
	v_and_b32_e32 v21, 0xffff0000, v21
	v_lshlrev_b32_e32 v28, 16, v22
	v_and_b32_e32 v29, 0xffff0000, v22
	v_lshlrev_b32_e32 v22, 16, v23
	v_and_b32_e32 v23, 0xffff0000, v23
	v_lshlrev_b32_e32 v30, 16, v16
	v_and_b32_e32 v31, 0xffff0000, v16
	v_lshlrev_b32_e32 v16, 16, v17
	v_and_b32_e32 v17, 0xffff0000, v17
	v_lshlrev_b32_e32 v32, 16, v18
	v_and_b32_e32 v33, 0xffff0000, v18
	v_lshlrev_b32_e32 v18, 16, v19
	v_and_b32_e32 v19, 0xffff0000, v19
	v_pk_mul_f32 v[14:15], v[14:15], v[20:21]
	v_pk_mul_f32 v[12:13], v[12:13], v[26:27]
	v_pk_mul_f32 v[10:11], v[10:11], v[22:23]
	v_pk_mul_f32 v[8:9], v[8:9], v[28:29]
	v_pk_mul_f32 v[6:7], v[6:7], v[16:17]
	v_pk_mul_f32 v[4:5], v[4:5], v[30:31]
	v_pk_mul_f32 v[16:17], v[2:3], v[18:19]
	v_pk_mul_f32 v[18:19], v[0:1], v[32:33]
	v_cvt_pk_bf16_f32 v0, v12, v13
	v_cvt_pk_bf16_f32 v1, v14, v15
	v_cvt_pk_bf16_f32 v2, v8, v9
	v_cvt_pk_bf16_f32 v3, v10, v11
	v_cvt_pk_bf16_f32 v4, v4, v5
	v_cvt_pk_bf16_f32 v5, v6, v7
	v_cvt_pk_bf16_f32 v6, v18, v19
	v_cvt_pk_bf16_f32 v7, v16, v17
	global_store_dwordx4 v[24:25], v[0:3], off
	global_store_dwordx4 v[24:25], v[4:7], off offset:256
	s_cbranch_vccz .LBB0_588
	s_waitcnt vmcnt(0)
	s_cmpk_gt_u32 s0, 0xff
	s_cbranch_scc1 .LBB0_595
	s_barrier

.LBB0_599:
	s_lshl_b32 s20, s20, 5
	s_and_b32 s25, s20, 0x60
	s_mov_b64 s[20:21], 0x80
	s_add_i32 m0, s35, 0x18000
	v_lshl_add_u64 v[6:7], v[6:7], 0, s[20:21]
	s_lshl_b32 s24, s5, 13
	s_lshl_b32 s40, s25, 7
	s_waitcnt vmcnt(4)
	s_barrier
	global_load_lds_dwordx4 v[6:7], off
	v_lshl_add_u64 v[4:5], v[4:5], 0, s[20:21]
	s_add_i32 m0, s35, 0x1a000
	s_add_i32 s57, s35, 0x8000
	s_add_i32 s58, s35, 0xa000
	global_load_lds_dwordx4 v[4:5], off
	v_lshl_add_u64 v[2:3], v[2:3], 0, s[20:21]
	s_mov_b32 m0, s57
	s_add_u32 s22, s50, 0x40080
	global_load_lds_dwordx4 v[2:3], off
	v_lshl_add_u64 v[0:1], v[0:1], 0, s[20:21]
	s_mov_b32 m0, s58
	s_addc_u32 s23, s51, 0
	global_load_lds_dwordx4 v[0:1], off
	s_add_i32 m0, s35, 0x1c000
	v_lshl_add_u64 v[0:1], s[22:23], 0, v[132:133]
	global_load_lds_dwordx4 v[0:1], off
	v_lshl_add_u64 v[0:1], s[22:23], 0, v[128:129]
	s_add_i32 m0, s35, 0x1e000
	s_add_i32 s60, 0, 0x10000
	global_load_lds_dwordx4 v[0:1], off
	v_lshrrev_b32_e32 v1, 1, v9
	v_and_b32_e32 v1, 24, v1
	v_and_b32_e32 v0, 15, v9
	v_lshlrev_b32_e32 v2, 1, v1
	v_lshl_or_b32 v150, s5, 6, v0
	v_lshl_or_b32 v0, v0, 6, v2
	v_lshlrev_b32_e32 v2, 2, v9
	v_and_b32_e32 v2, 32, v2
	v_bitop3_b32 v3, v0, s24, v2 bitop3:0xde
	v_bitop3_b32 v151, v0, s40, v2 bitop3:0xde
	v_lshlrev_b32_e32 v0, 14, v13
	v_and_b32_e32 v0, 0xffff8000, v0
	v_or_b32_e32 v152, s25, v1
	v_lshl_add_u32 v0, v12, 11, v0
	v_and_b32_e32 v1, 1, v13
	v_lshl_or_b32 v0, v1, 6, v0
	v_lshl_add_u32 v136, v14, 1, v0
	v_lshlrev_b32_e32 v0, 14, v8
	v_and_b32_e32 v0, 0xffff8000, v0
	s_waitcnt vmcnt(6)
	v_lshl_add_u32 v0, v10, 11, v0
	v_and_b32_e32 v1, 1, v8
	v_lshl_or_b32 v0, v1, 6, v0
	s_sext_i32_i8 s61, s4
	s_ashr_i32 s59, s3, 31
	v_mov_b32_e32 v137, v133
	v_lshl_add_u32 v138, v11, 1, v0
	v_mov_b32_e32 v139, v133
	v_mov_b64_e32 v[140:141], 0x600
	v_mov_b64_e32 v[142:143], 0x5ff
	v_add_u32_e32 v153, s60, v151
	v_add_u32_e32 v156, 0, v3
	v_add_u32_e32 v157, s72, v151
	s_barrier
	v_readfirstlane_b32 s4, v154
	s_bitcmp1_b32 s4, 8
	s_cbranch_scc0 .Lprio_600
	s_setprio 1
.Lprio_600:
.LBB0_600:
	s_add_i32 s56, s56, 1
	s_mul_i32 s4, s56, s59
	s_mul_hi_u32 s5, s56, s3
	s_add_i32 s5, s5, s4
	s_mul_i32 s4, s56, s3
	s_add_u32 s40, s4, s2
	s_addc_u32 s41, s5, s33
	v_cmp_gt_i64_e64 s[4:5], s[40:41], v[142:143]
	s_and_b64 vcc, exec, s[4:5]
	s_cbranch_vccnz .LBB0_602
	s_ashr_i32 s22, s40, 31
	s_lshr_b32 s22, s22, 29
	s_add_i32 s22, s40, s22
	s_ashr_i32 s23, s22, 3
	s_and_b32 s22, s22, -8
	s_sub_i32 s22, s40, s22
	s_cmp_lt_i32 s22, 0
	s_cselect_b32 s24, s34, 0xc0
	s_mul_i32 s22, s24, s22
	s_add_i32 s22, s22, s23
	s_ashr_i32 s23, s22, 31
	s_lshr_b32 s23, s23, 27
	s_add_i32 s23, s22, s23
	s_ashr_i32 s24, s23, 5
	s_lshl_b32 s24, s24, 3
	s_sub_i32 s25, 0x180, s24
	s_min_i32 s25, s25, 8
	s_abs_i32 s44, s25
	v_cvt_f32_u32_e32 v0, s44
	s_sub_i32 s52, 0, s44
	s_andn2_b32 s23, s23, 31
	s_sub_i32 s23, s22, s23
	v_rcp_iflag_f32_e32 v0, v0
	s_abs_i32 s22, s23
	s_xor_b32 s45, s23, s25
	s_ashr_i32 s45, s45, 31
	v_mul_f32_e32 v0, 0x4f7ffffe, v0
	v_cvt_u32_f32_e32 v0, v0
	s_nop 0
	v_readfirstlane_b32 s53, v0
	s_mul_i32 s52, s52, s53
	s_mul_hi_u32 s52, s53, s52
	s_add_i32 s53, s53, s52
	s_mul_hi_u32 s52, s22, s53
	s_mul_i32 s53, s52, s44
	s_sub_i32 s22, s22, s53
	s_add_i32 s62, s52, 1
	s_sub_i32 s53, s22, s44
	s_cmp_ge_u32 s22, s44
	s_cselect_b32 s52, s62, s52
	s_cselect_b32 s22, s53, s22
	s_add_i32 s53, s52, 1
	s_cmp_ge_u32 s22, s44
	s_cselect_b32 s22, s53, s52
	s_xor_b32 s22, s22, s45
	s_sub_i32 s22, s22, s45
	s_mul_i32 s25, s22, s25
	s_sub_i32 s23, s23, s25
	s_add_i32 s24, s23, s24

.LBB0_603:
	ds_read_b128 v[144:147], v153
	ds_read_b128 v[158:161], v153 offset:1024
	ds_read_b128 v[162:165], v153 offset:2048
	ds_read_b128 v[166:169], v153 offset:3072
	s_add_u32 s50, s48, 0xfffc0080
	s_addc_u32 s51, s49, -1
	s_cmp_eq_u32 s66, 12
	s_cselect_b32 s53, s25, s51
	s_cselect_b32 s52, s62, s50
	s_cselect_b32 s51, s23, s65
	s_cselect_b32 s50, s63, s64
	v_lshl_add_u64 v[148:149], s[48:49], 0, v[136:137]
	s_add_i32 m0, s35, 0xc000
	ds_read_b128 v[170:173], v156
	ds_read_b128 v[174:177], v156 offset:1024
	ds_read_b128 v[178:181], v156 offset:2048
	ds_read_b128 v[182:185], v156 offset:3072
	ds_read_b128 v[186:189], v156 offset:4096
	ds_read_b128 v[190:193], v156 offset:5120
	ds_read_b128 v[194:197], v156 offset:6144
	ds_read_b128 v[198:201], v156 offset:7168
	global_load_lds_dwordx4 v[148:149], off
	v_lshl_add_u64 v[148:149], s[48:49], 0, v[138:139]
	s_add_i32 m0, s35, 0xe000
	s_nop 0
	global_load_lds_dwordx4 v[148:149], off
	s_waitcnt lgkmcnt(8)
	s_barrier
	s_waitcnt lgkmcnt(0)
	s_waitcnt lgkmcnt(0)
	v_mfma_f32_16x16x32_bf16 v[124:127], v[144:147], v[170:173], v[124:127]
	v_mfma_f32_16x16x32_bf16 v[120:123], v[162:165], v[170:173], v[120:123]
	v_mfma_f32_16x16x32_bf16 v[108:111], v[144:147], v[178:181], v[108:111]
	v_mfma_f32_16x16x32_bf16 v[104:107], v[162:165], v[178:181], v[104:107]
	v_mfma_f32_16x16x32_bf16 v[92:95], v[144:147], v[186:189], v[92:95]
	v_mfma_f32_16x16x32_bf16 v[88:91], v[162:165], v[186:189], v[88:91]
	v_mfma_f32_16x16x32_bf16 v[76:79], v[144:147], v[194:197], v[76:79]
	v_mfma_f32_16x16x32_bf16 v[72:75], v[162:165], v[194:197], v[72:75]
	v_mfma_f32_16x16x32_bf16 v[124:127], v[158:161], v[174:177], v[124:127]
	v_mfma_f32_16x16x32_bf16 v[120:123], v[166:169], v[174:177], v[120:123]
	v_mfma_f32_16x16x32_bf16 v[108:111], v[158:161], v[182:185], v[108:111]
	v_mfma_f32_16x16x32_bf16 v[104:107], v[166:169], v[182:185], v[104:107]
	v_mfma_f32_16x16x32_bf16 v[92:95], v[158:161], v[190:193], v[92:95]
	v_mfma_f32_16x16x32_bf16 v[88:91], v[166:169], v[190:193], v[88:91]
	v_mfma_f32_16x16x32_bf16 v[76:79], v[158:161], v[198:201], v[76:79]
	v_mfma_f32_16x16x32_bf16 v[72:75], v[166:169], v[198:201], v[72:75]
	s_barrier
	s_add_i32 s67, s60, s1
	v_lshl_add_u64 v[148:149], s[50:51], 0, v[132:133]
	s_mov_b32 m0, s67
	ds_read_b128 v[202:205], v157
	ds_read_b128 v[206:209], v157 offset:1024
	ds_read_b128 v[210:213], v157 offset:2048
	ds_read_b128 v[214:217], v157 offset:3072
	global_load_lds_dwordx4 v[148:149], off
	v_lshl_add_u64 v[218:219], s[50:51], 0, v[128:129]
	s_add_i32 m0, s67, 0x2000
	s_nop 0
	global_load_lds_dwordx4 v[218:219], off
	s_barrier
	s_waitcnt lgkmcnt(0)
	s_waitcnt lgkmcnt(0)
	v_mfma_f32_16x16x32_bf16 v[116:119], v[202:205], v[170:173], v[116:119]
	v_mfma_f32_16x16x32_bf16 v[112:115], v[210:213], v[170:173], v[112:115]
	v_mfma_f32_16x16x32_bf16 v[100:103], v[202:205], v[178:181], v[100:103]
	v_mfma_f32_16x16x32_bf16 v[96:99], v[210:213], v[178:181], v[96:99]
	v_mfma_f32_16x16x32_bf16 v[84:87], v[202:205], v[186:189], v[84:87]
	v_mfma_f32_16x16x32_bf16 v[80:83], v[210:213], v[186:189], v[80:83]
	v_mfma_f32_16x16x32_bf16 v[68:71], v[202:205], v[194:197], v[68:71]
	v_mfma_f32_16x16x32_bf16 v[64:67], v[210:213], v[194:197], v[64:67]
	v_mfma_f32_16x16x32_bf16 v[116:119], v[206:209], v[174:177], v[116:119]
	v_mfma_f32_16x16x32_bf16 v[112:115], v[214:217], v[174:177], v[112:115]
	v_mfma_f32_16x16x32_bf16 v[100:103], v[206:209], v[182:185], v[100:103]
	v_mfma_f32_16x16x32_bf16 v[96:99], v[214:217], v[182:185], v[96:99]
	v_mfma_f32_16x16x32_bf16 v[84:87], v[206:209], v[190:193], v[84:87]
	v_mfma_f32_16x16x32_bf16 v[80:83], v[214:217], v[190:193], v[80:83]
	v_mfma_f32_16x16x32_bf16 v[68:71], v[206:209], v[198:201], v[68:71]
	v_mfma_f32_16x16x32_bf16 v[64:67], v[214:217], v[198:201], v[64:67]
	s_mov_b32 m0, s35
	v_lshl_add_u64 v[220:221], s[52:53], 0, v[134:135]
	s_barrier
	ds_read_b128 v[170:173], v156 offset:16384
	ds_read_b128 v[174:177], v156 offset:17408
	ds_read_b128 v[178:181], v156 offset:18432
	ds_read_b128 v[182:185], v156 offset:19456
	ds_read_b128 v[186:189], v156 offset:20480
	ds_read_b128 v[190:193], v156 offset:21504
	ds_read_b128 v[194:197], v156 offset:22528
	ds_read_b128 v[198:201], v156 offset:23552
	global_load_lds_dwordx4 v[220:221], off
	v_lshl_add_u64 v[222:223], s[52:53], 0, v[130:131]
	s_mov_b32 m0, s47
	s_nop 0
	global_load_lds_dwordx4 v[222:223], off
	s_barrier
	s_waitcnt lgkmcnt(0)
	s_waitcnt lgkmcnt(0)
	v_mfma_f32_16x16x32_bf16 v[60:63], v[144:147], v[170:173], v[60:63]
	v_mfma_f32_16x16x32_bf16 v[56:59], v[162:165], v[170:173], v[56:59]
	v_mfma_f32_16x16x32_bf16 v[44:47], v[144:147], v[178:181], v[44:47]
	v_mfma_f32_16x16x32_bf16 v[40:43], v[162:165], v[178:181], v[40:43]
	v_mfma_f32_16x16x32_bf16 v[28:31], v[144:147], v[186:189], v[28:31]
	v_mfma_f32_16x16x32_bf16 v[24:27], v[162:165], v[186:189], v[24:27]
	v_mfma_f32_16x16x32_bf16 v[12:15], v[144:147], v[194:197], v[12:15]
	v_mfma_f32_16x16x32_bf16 v[8:11], v[162:165], v[194:197], v[8:11]
	v_mfma_f32_16x16x32_bf16 v[60:63], v[158:161], v[174:177], v[60:63]
	v_mfma_f32_16x16x32_bf16 v[56:59], v[166:169], v[174:177], v[56:59]
	v_mfma_f32_16x16x32_bf16 v[44:47], v[158:161], v[182:185], v[44:47]
	v_mfma_f32_16x16x32_bf16 v[40:43], v[166:169], v[182:185], v[40:43]
	v_mfma_f32_16x16x32_bf16 v[28:31], v[158:161], v[190:193], v[28:31]
	v_mfma_f32_16x16x32_bf16 v[24:27], v[166:169], v[190:193], v[24:27]
	v_mfma_f32_16x16x32_bf16 v[12:15], v[158:161], v[198:201], v[12:15]
	v_mfma_f32_16x16x32_bf16 v[8:11], v[166:169], v[198:201], v[8:11]
	s_barrier
	s_add_u32 s68, s50, 0x40000
	s_addc_u32 s69, s51, 0
	s_add_i32 s67, s72, s1
	v_lshl_add_u64 v[144:145], s[68:69], 0, v[132:133]
	s_mov_b32 m0, s67
	s_nop 0
	global_load_lds_dwordx4 v[144:145], off
	v_lshl_add_u64 v[144:145], s[68:69], 0, v[128:129]
	s_add_i32 m0, s67, 0x2000
	s_nop 0
	global_load_lds_dwordx4 v[144:145], off
	s_waitcnt vmcnt(6)
	s_barrier
	v_mfma_f32_16x16x32_bf16 v[52:55], v[202:205], v[170:173], v[52:55]
	v_mfma_f32_16x16x32_bf16 v[48:51], v[210:213], v[170:173], v[48:51]
	v_mfma_f32_16x16x32_bf16 v[36:39], v[202:205], v[178:181], v[36:39]
	v_mfma_f32_16x16x32_bf16 v[32:35], v[210:213], v[178:181], v[32:35]
	v_mfma_f32_16x16x32_bf16 v[20:23], v[202:205], v[186:189], v[20:23]
	v_mfma_f32_16x16x32_bf16 v[16:19], v[210:213], v[186:189], v[16:19]
	v_mfma_f32_16x16x32_bf16 v[4:7], v[202:205], v[194:197], v[4:7]
	v_mfma_f32_16x16x32_bf16 v[0:3], v[210:213], v[194:197], v[0:3]
	v_mfma_f32_16x16x32_bf16 v[52:55], v[206:209], v[174:177], v[52:55]
	v_mfma_f32_16x16x32_bf16 v[48:51], v[214:217], v[174:177], v[48:51]
	v_mfma_f32_16x16x32_bf16 v[36:39], v[206:209], v[182:185], v[36:39]
	v_mfma_f32_16x16x32_bf16 v[32:35], v[214:217], v[182:185], v[32:35]
	v_mfma_f32_16x16x32_bf16 v[20:23], v[206:209], v[190:193], v[20:23]
	v_mfma_f32_16x16x32_bf16 v[16:19], v[214:217], v[190:193], v[16:19]
	v_mfma_f32_16x16x32_bf16 v[4:7], v[206:209], v[198:201], v[4:7]
	v_mfma_f32_16x16x32_bf16 v[0:3], v[214:217], v[198:201], v[0:3]
	s_add_i32 s67, 0, 0x18000
	v_add_u32_e32 v166, s67, v151
	s_barrier
	ds_read_b128 v[144:147], v166
	ds_read_b128 v[158:161], v166 offset:1024
	ds_read_b128 v[162:165], v166 offset:2048
	ds_read_b128 v[166:169], v166 offset:3072
	s_add_u32 s52, s52, 0x40000
	s_addc_u32 s53, s53, 0
	s_mov_b32 m0, s54
	v_lshl_add_u64 v[202:203], s[52:53], 0, v[134:135]
	ds_read_b128 v[170:173], v156 offset:32768
	ds_read_b128 v[174:177], v156 offset:33792
	ds_read_b128 v[178:181], v156 offset:34816
	ds_read_b128 v[182:185], v156 offset:35840
	ds_read_b128 v[186:189], v156 offset:36864
	ds_read_b128 v[190:193], v156 offset:37888
	ds_read_b128 v[194:197], v156 offset:38912
	ds_read_b128 v[198:201], v156 offset:39936
	global_load_lds_dwordx4 v[202:203], off
	v_lshl_add_u64 v[202:203], s[52:53], 0, v[130:131]
	s_mov_b32 m0, s55
	s_nop 0
	global_load_lds_dwordx4 v[202:203], off
	s_waitcnt lgkmcnt(8)
	s_barrier
	s_waitcnt lgkmcnt(0)
	s_waitcnt lgkmcnt(0)
	v_mfma_f32_16x16x32_bf16 v[124:127], v[144:147], v[170:173], v[124:127]
	v_mfma_f32_16x16x32_bf16 v[120:123], v[162:165], v[170:173], v[120:123]
	v_mfma_f32_16x16x32_bf16 v[108:111], v[144:147], v[178:181], v[108:111]
	v_mfma_f32_16x16x32_bf16 v[104:107], v[162:165], v[178:181], v[104:107]
	v_mfma_f32_16x16x32_bf16 v[92:95], v[144:147], v[186:189], v[92:95]
	v_mfma_f32_16x16x32_bf16 v[88:91], v[162:165], v[186:189], v[88:91]
	v_mfma_f32_16x16x32_bf16 v[76:79], v[144:147], v[194:197], v[76:79]
	v_mfma_f32_16x16x32_bf16 v[72:75], v[162:165], v[194:197], v[72:75]
	v_mfma_f32_16x16x32_bf16 v[124:127], v[158:161], v[174:177], v[124:127]
	v_mfma_f32_16x16x32_bf16 v[120:123], v[166:169], v[174:177], v[120:123]
	v_mfma_f32_16x16x32_bf16 v[108:111], v[158:161], v[182:185], v[108:111]
	v_mfma_f32_16x16x32_bf16 v[104:107], v[166:169], v[182:185], v[104:107]
	v_mfma_f32_16x16x32_bf16 v[92:95], v[158:161], v[190:193], v[92:95]
	v_mfma_f32_16x16x32_bf16 v[88:91], v[166:169], v[190:193], v[88:91]
	v_mfma_f32_16x16x32_bf16 v[76:79], v[158:161], v[198:201], v[76:79]
	v_mfma_f32_16x16x32_bf16 v[72:75], v[166:169], v[198:201], v[72:75]
	s_barrier
	s_add_i32 s52, s67, s1
	v_add_u32_e32 v214, s97, v151
	v_lshl_add_u64 v[148:149], v[148:149], 0, s[20:21]
	s_mov_b32 m0, s52
	ds_read_b128 v[202:205], v214
	ds_read_b128 v[206:209], v214 offset:1024
	ds_read_b128 v[210:213], v214 offset:2048
	ds_read_b128 v[214:217], v214 offset:3072
	global_load_lds_dwordx4 v[148:149], off
	v_lshl_add_u64 v[148:149], v[218:219], 0, s[20:21]
	s_add_i32 m0, s52, 0x2000
	s_nop 0
	global_load_lds_dwordx4 v[148:149], off
	s_barrier
	s_waitcnt lgkmcnt(0)
	s_waitcnt lgkmcnt(0)
	v_mfma_f32_16x16x32_bf16 v[116:119], v[202:205], v[170:173], v[116:119]
	v_mfma_f32_16x16x32_bf16 v[112:115], v[210:213], v[170:173], v[112:115]
	v_mfma_f32_16x16x32_bf16 v[100:103], v[202:205], v[178:181], v[100:103]
	v_mfma_f32_16x16x32_bf16 v[96:99], v[210:213], v[178:181], v[96:99]
	v_mfma_f32_16x16x32_bf16 v[84:87], v[202:205], v[186:189], v[84:87]
	v_mfma_f32_16x16x32_bf16 v[80:83], v[210:213], v[186:189], v[80:83]
	v_mfma_f32_16x16x32_bf16 v[68:71], v[202:205], v[194:197], v[68:71]
	v_mfma_f32_16x16x32_bf16 v[64:67], v[210:213], v[194:197], v[64:67]
	v_mfma_f32_16x16x32_bf16 v[116:119], v[206:209], v[174:177], v[116:119]
	v_mfma_f32_16x16x32_bf16 v[112:115], v[214:217], v[174:177], v[112:115]
	v_mfma_f32_16x16x32_bf16 v[100:103], v[206:209], v[182:185], v[100:103]
	v_mfma_f32_16x16x32_bf16 v[96:99], v[214:217], v[182:185], v[96:99]
	v_mfma_f32_16x16x32_bf16 v[84:87], v[206:209], v[190:193], v[84:87]
	v_mfma_f32_16x16x32_bf16 v[80:83], v[214:217], v[190:193], v[80:83]
	v_mfma_f32_16x16x32_bf16 v[68:71], v[206:209], v[198:201], v[68:71]
	v_mfma_f32_16x16x32_bf16 v[64:67], v[214:217], v[198:201], v[64:67]
	s_mov_b32 m0, s57
	v_lshl_add_u64 v[148:149], v[220:221], 0, s[20:21]
	s_barrier
	ds_read_b128 v[170:173], v156 offset:49152
	ds_read_b128 v[174:177], v156 offset:50176
	ds_read_b128 v[178:181], v156 offset:51200
	ds_read_b128 v[182:185], v156 offset:52224
	ds_read_b128 v[186:189], v156 offset:53248
	ds_read_b128 v[190:193], v156 offset:54272
	ds_read_b128 v[194:197], v156 offset:55296
	ds_read_b128 v[198:201], v156 offset:56320
	global_load_lds_dwordx4 v[148:149], off
	v_lshl_add_u64 v[148:149], v[222:223], 0, s[20:21]
	s_mov_b32 m0, s58
	s_nop 0
	global_load_lds_dwordx4 v[148:149], off
	s_barrier
	s_waitcnt lgkmcnt(0)
	s_waitcnt lgkmcnt(0)
	v_mfma_f32_16x16x32_bf16 v[60:63], v[144:147], v[170:173], v[60:63]
	v_mfma_f32_16x16x32_bf16 v[56:59], v[162:165], v[170:173], v[56:59]
	v_mfma_f32_16x16x32_bf16 v[44:47], v[144:147], v[178:181], v[44:47]
	v_mfma_f32_16x16x32_bf16 v[40:43], v[162:165], v[178:181], v[40:43]
	v_mfma_f32_16x16x32_bf16 v[28:31], v[144:147], v[186:189], v[28:31]
	v_mfma_f32_16x16x32_bf16 v[24:27], v[162:165], v[186:189], v[24:27]
	v_mfma_f32_16x16x32_bf16 v[12:15], v[144:147], v[194:197], v[12:15]
	v_mfma_f32_16x16x32_bf16 v[8:11], v[162:165], v[194:197], v[8:11]
	v_mfma_f32_16x16x32_bf16 v[60:63], v[158:161], v[174:177], v[60:63]
	v_mfma_f32_16x16x32_bf16 v[56:59], v[166:169], v[174:177], v[56:59]
	v_mfma_f32_16x16x32_bf16 v[44:47], v[158:161], v[182:185], v[44:47]
	v_mfma_f32_16x16x32_bf16 v[40:43], v[166:169], v[182:185], v[40:43]
	v_mfma_f32_16x16x32_bf16 v[28:31], v[158:161], v[190:193], v[28:31]
	v_mfma_f32_16x16x32_bf16 v[24:27], v[166:169], v[190:193], v[24:27]
	v_mfma_f32_16x16x32_bf16 v[12:15], v[158:161], v[198:201], v[12:15]
	v_mfma_f32_16x16x32_bf16 v[8:11], v[166:169], v[198:201], v[8:11]
	s_barrier
	s_add_u32 s50, s50, 0x40080
	s_addc_u32 s51, s51, 0
	s_add_i32 s52, s97, s1
	v_lshl_add_u64 v[144:145], s[50:51], 0, v[132:133]
	s_mov_b32 m0, s52
	s_nop 0
	global_load_lds_dwordx4 v[144:145], off
	v_lshl_add_u64 v[144:145], s[50:51], 0, v[128:129]
	s_add_i32 m0, s52, 0x2000
	s_nop 0
	global_load_lds_dwordx4 v[144:145], off
	s_waitcnt vmcnt(6)
	s_barrier
	v_mfma_f32_16x16x32_bf16 v[52:55], v[202:205], v[170:173], v[52:55]
	v_mfma_f32_16x16x32_bf16 v[48:51], v[210:213], v[170:173], v[48:51]
	v_mfma_f32_16x16x32_bf16 v[36:39], v[202:205], v[178:181], v[36:39]
	v_mfma_f32_16x16x32_bf16 v[32:35], v[210:213], v[178:181], v[32:35]
	v_mfma_f32_16x16x32_bf16 v[20:23], v[202:205], v[186:189], v[20:23]
	v_mfma_f32_16x16x32_bf16 v[16:19], v[210:213], v[186:189], v[16:19]
	v_mfma_f32_16x16x32_bf16 v[4:7], v[202:205], v[194:197], v[4:7]
	v_mfma_f32_16x16x32_bf16 v[0:3], v[210:213], v[194:197], v[0:3]
	v_mfma_f32_16x16x32_bf16 v[52:55], v[206:209], v[174:177], v[52:55]
	v_mfma_f32_16x16x32_bf16 v[48:51], v[214:217], v[174:177], v[48:51]
	v_mfma_f32_16x16x32_bf16 v[36:39], v[206:209], v[182:185], v[36:39]
	v_mfma_f32_16x16x32_bf16 v[32:35], v[214:217], v[182:185], v[32:35]
	v_mfma_f32_16x16x32_bf16 v[20:23], v[206:209], v[190:193], v[20:23]
	v_mfma_f32_16x16x32_bf16 v[16:19], v[214:217], v[190:193], v[16:19]
	v_mfma_f32_16x16x32_bf16 v[4:7], v[206:209], v[198:201], v[4:7]
	v_mfma_f32_16x16x32_bf16 v[0:3], v[214:217], v[198:201], v[0:3]
	s_add_i32 s66, s66, 2
	s_add_u32 s48, s48, 0x100
	s_addc_u32 s49, s49, 0
	s_add_u32 s64, s64, 0x100
	s_addc_u32 s65, s65, 0
	s_cmp_gt_u32 s66, 13
	s_barrier
	s_cbranch_scc0 .LBB0_603
	v_lshl_add_u32 v146, s46, 8, v150
	v_lshl_or_b32 v144, s61, 8, v152
	v_ashrrev_i32_e32 v147, 31, v146
	v_lshlrev_b64 v[148:149], 12, v[146:147]
	v_ashrrev_i32_e32 v145, 31, v144
	v_lshl_add_u64 v[148:149], s[6:7], 0, v[148:149]
	v_lshlrev_b64 v[144:145], 1, v[144:145]
	v_lshlrev_b64 v[162:163], 11, v[146:147]
	v_lshl_add_u64 v[148:149], v[148:149], 0, v[144:145]
	v_lshl_add_u64 v[162:163], s[14:15], 0, v[162:163]
	global_load_dwordx4 v[158:161], v[148:149], off offset:2048
	v_lshl_add_u64 v[182:183], v[162:163], 0, v[144:145]
	global_load_dwordx4 v[162:165], v[182:183], off
	global_load_dwordx4 v[166:169], v[148:149], off offset:2304
	global_load_dwordx4 v[170:173], v[182:183], off offset:256
	v_or_b32_e32 v148, 16, v146
	v_ashrrev_i32_e32 v149, 31, v148
	v_lshlrev_b64 v[174:175], 12, v[148:149]
	v_lshlrev_b64 v[148:149], 11, v[148:149]
	v_lshl_add_u64 v[148:149], s[14:15], 0, v[148:149]
	v_lshl_add_u64 v[174:175], s[6:7], 0, v[174:175]
	v_lshl_add_u64 v[148:149], v[148:149], 0, v[144:145]
	v_lshl_add_u64 v[184:185], v[174:175], 0, v[144:145]
	global_load_dwordx4 v[174:177], v[148:149], off
	global_load_dwordx4 v[178:181], v[148:149], off offset:256
	s_and_b64 vcc, exec, s[4:5]
	s_mov_b32 s61, s22
	s_mov_b32 s46, s24
	s_mov_b64 s[50:51], s[44:45]
	s_mov_b64 s[48:49], s[40:41]
	s_waitcnt vmcnt(0)
	v_lshlrev_b32_e32 v190, 16, v162
	v_lshlrev_b32_e32 v186, 16, v158
	v_and_b32_e32 v187, 0xffff0000, v158
	v_lshlrev_b32_e32 v158, 16, v159
	v_and_b32_e32 v159, 0xffff0000, v159
	v_lshlrev_b32_e32 v188, 16, v160
	v_and_b32_e32 v189, 0xffff0000, v160
	v_lshlrev_b32_e32 v160, 16, v161
	v_and_b32_e32 v161, 0xffff0000, v161
	v_and_b32_e32 v191, 0xffff0000, v162
	v_lshlrev_b32_e32 v162, 16, v163
	v_and_b32_e32 v163, 0xffff0000, v163
	v_lshlrev_b32_e32 v192, 16, v164
	v_and_b32_e32 v193, 0xffff0000, v164
	v_lshlrev_b32_e32 v164, 16, v165
	v_and_b32_e32 v165, 0xffff0000, v165
	v_lshlrev_b32_e32 v194, 16, v166
	v_and_b32_e32 v195, 0xffff0000, v166
	v_lshlrev_b32_e32 v166, 16, v167
	v_and_b32_e32 v167, 0xffff0000, v167
	v_lshlrev_b32_e32 v196, 16, v168
	v_and_b32_e32 v197, 0xffff0000, v168
	v_lshlrev_b32_e32 v168, 16, v169
	v_and_b32_e32 v169, 0xffff0000, v169
	v_lshlrev_b32_e32 v198, 16, v170
	v_and_b32_e32 v199, 0xffff0000, v170
	v_lshlrev_b32_e32 v170, 16, v171
	v_and_b32_e32 v171, 0xffff0000, v171
	v_lshlrev_b32_e32 v200, 16, v172
	v_and_b32_e32 v201, 0xffff0000, v172
	v_lshlrev_b32_e32 v172, 16, v173
	v_and_b32_e32 v173, 0xffff0000, v173
	v_pk_fma_f32 v[126:127], v[126:127], v[158:159], v[162:163]
	v_pk_fma_f32 v[124:125], v[124:125], v[186:187], v[190:191]
	v_pk_fma_f32 v[122:123], v[122:123], v[160:161], v[164:165]
	v_pk_fma_f32 v[120:121], v[120:121], v[188:189], v[192:193]
	v_pk_fma_f32 v[158:159], v[118:119], v[166:167], v[170:171]
	v_pk_fma_f32 v[160:161], v[116:117], v[194:195], v[198:199]
	v_cvt_pk_bf16_f32 v116, v124, v125
	v_cvt_pk_bf16_f32 v117, v126, v127
	v_cvt_pk_bf16_f32 v118, v120, v121
	v_cvt_pk_bf16_f32 v119, v122, v123
	v_pk_fma_f32 v[120:121], v[114:115], v[168:169], v[172:173]
	v_pk_fma_f32 v[114:115], v[112:113], v[196:197], v[200:201]
	global_store_dwordx4 v[182:183], v[116:119], off
	v_cvt_pk_bf16_f32 v112, v160, v161
	v_cvt_pk_bf16_f32 v113, v158, v159
	v_cvt_pk_bf16_f32 v114, v114, v115
	v_cvt_pk_bf16_f32 v115, v120, v121
	global_load_dwordx4 v[116:119], v[184:185], off offset:2048
	v_lshlrev_b32_e32 v162, 16, v174
	global_store_dwordx4 v[182:183], v[112:115], off offset:256
	global_load_dwordx4 v[120:123], v[184:185], off offset:2304
	v_and_b32_e32 v163, 0xffff0000, v174
	v_or_b32_e32 v112, 32, v146
	v_ashrrev_i32_e32 v113, 31, v112
	v_lshlrev_b64 v[114:115], 12, v[112:113]
	v_lshlrev_b64 v[112:113], 11, v[112:113]
	v_lshlrev_b32_e32 v164, 16, v175
	v_and_b32_e32 v165, 0xffff0000, v175
	v_lshlrev_b32_e32 v166, 16, v176
	v_and_b32_e32 v167, 0xffff0000, v176
	v_lshlrev_b32_e32 v168, 16, v177
	v_and_b32_e32 v169, 0xffff0000, v177
	v_lshlrev_b32_e32 v170, 16, v178
	v_and_b32_e32 v171, 0xffff0000, v178
	v_lshlrev_b32_e32 v172, 16, v179
	v_and_b32_e32 v173, 0xffff0000, v179
	v_lshlrev_b32_e32 v174, 16, v180
	v_and_b32_e32 v175, 0xffff0000, v180
	v_lshlrev_b32_e32 v176, 16, v181
	v_and_b32_e32 v177, 0xffff0000, v181
	v_lshl_add_u64 v[112:113], s[14:15], 0, v[112:113]
	v_lshl_add_u64 v[114:115], s[6:7], 0, v[114:115]
	v_lshl_add_u64 v[112:113], v[112:113], 0, v[144:145]
	v_lshl_add_u64 v[114:115], v[114:115], 0, v[144:145]
	global_load_dwordx4 v[124:127], v[112:113], off
	global_load_dwordx4 v[158:161], v[112:113], off offset:256
	s_waitcnt vmcnt(0)
	v_lshlrev_b32_e32 v178, 16, v116
	v_and_b32_e32 v179, 0xffff0000, v116
	v_lshlrev_b32_e32 v116, 16, v117
	v_and_b32_e32 v117, 0xffff0000, v117
	v_lshlrev_b32_e32 v180, 16, v118
	v_and_b32_e32 v181, 0xffff0000, v118
	v_lshlrev_b32_e32 v118, 16, v119
	v_and_b32_e32 v119, 0xffff0000, v119
	v_lshlrev_b32_e32 v182, 16, v120
	v_and_b32_e32 v183, 0xffff0000, v120
	v_lshlrev_b32_e32 v120, 16, v121
	v_and_b32_e32 v121, 0xffff0000, v121
	v_lshlrev_b32_e32 v184, 16, v122
	v_and_b32_e32 v185, 0xffff0000, v122
	v_lshlrev_b32_e32 v122, 16, v123
	v_and_b32_e32 v123, 0xffff0000, v123
	v_pk_fma_f32 v[110:111], v[110:111], v[116:117], v[164:165]
	v_pk_fma_f32 v[108:109], v[108:109], v[178:179], v[162:163]
	v_pk_fma_f32 v[106:107], v[106:107], v[118:119], v[168:169]
	v_pk_fma_f32 v[104:105], v[104:105], v[180:181], v[166:167]
	v_pk_fma_f32 v[116:117], v[102:103], v[120:121], v[172:173]
	v_pk_fma_f32 v[118:119], v[100:101], v[182:183], v[170:171]
	v_cvt_pk_bf16_f32 v100, v108, v109
	v_cvt_pk_bf16_f32 v101, v110, v111
	v_cvt_pk_bf16_f32 v102, v104, v105
	v_cvt_pk_bf16_f32 v103, v106, v107
	v_pk_fma_f32 v[104:105], v[98:99], v[122:123], v[176:177]
	v_pk_fma_f32 v[98:99], v[96:97], v[184:185], v[174:175]
	global_store_dwordx4 v[148:149], v[100:103], off
	v_cvt_pk_bf16_f32 v96, v118, v119
	v_cvt_pk_bf16_f32 v97, v116, v117
	v_cvt_pk_bf16_f32 v98, v98, v99
	v_cvt_pk_bf16_f32 v99, v104, v105
	global_load_dwordx4 v[100:103], v[114:115], off offset:2048
	v_lshlrev_b32_e32 v118, 16, v124
	global_store_dwordx4 v[148:149], v[96:99], off offset:256
	global_load_dwordx4 v[104:107], v[114:115], off offset:2304
	v_and_b32_e32 v119, 0xffff0000, v124
	v_or_b32_e32 v96, 48, v146
	v_ashrrev_i32_e32 v97, 31, v96
	v_lshlrev_b64 v[98:99], 12, v[96:97]
	v_lshlrev_b64 v[96:97], 11, v[96:97]
	v_lshlrev_b32_e32 v120, 16, v125
	v_and_b32_e32 v121, 0xffff0000, v125
	v_lshlrev_b32_e32 v122, 16, v126
	v_and_b32_e32 v123, 0xffff0000, v126
	v_lshlrev_b32_e32 v124, 16, v127
	v_and_b32_e32 v125, 0xffff0000, v127
	v_lshl_add_u64 v[96:97], s[14:15], 0, v[96:97]
	v_lshlrev_b32_e32 v126, 16, v158
	v_and_b32_e32 v127, 0xffff0000, v158
	v_lshlrev_b32_e32 v148, 16, v159
	v_and_b32_e32 v149, 0xffff0000, v159
	v_lshlrev_b32_e32 v158, 16, v160
	v_and_b32_e32 v159, 0xffff0000, v160
	v_lshlrev_b32_e32 v160, 16, v161
	v_and_b32_e32 v161, 0xffff0000, v161
	v_lshl_add_u64 v[98:99], s[6:7], 0, v[98:99]
	v_lshl_add_u64 v[96:97], v[96:97], 0, v[144:145]
	v_lshl_add_u64 v[98:99], v[98:99], 0, v[144:145]
	global_load_dwordx4 v[108:111], v[96:97], off
	global_load_dwordx4 v[114:117], v[96:97], off offset:256
	s_waitcnt vmcnt(0)
	v_lshlrev_b32_e32 v162, 16, v100
	v_and_b32_e32 v163, 0xffff0000, v100
	v_lshlrev_b32_e32 v100, 16, v101
	v_and_b32_e32 v101, 0xffff0000, v101
	v_lshlrev_b32_e32 v164, 16, v102
	v_and_b32_e32 v165, 0xffff0000, v102
	v_lshlrev_b32_e32 v102, 16, v103
	v_and_b32_e32 v103, 0xffff0000, v103
	v_lshlrev_b32_e32 v166, 16, v104
	v_and_b32_e32 v167, 0xffff0000, v104
	v_lshlrev_b32_e32 v104, 16, v105
	v_and_b32_e32 v105, 0xffff0000, v105
	v_lshlrev_b32_e32 v168, 16, v106
	v_and_b32_e32 v169, 0xffff0000, v106
	v_lshlrev_b32_e32 v106, 16, v107
	v_and_b32_e32 v107, 0xffff0000, v107
	v_pk_fma_f32 v[94:95], v[94:95], v[100:101], v[120:121]
	v_pk_fma_f32 v[92:93], v[92:93], v[162:163], v[118:119]
	v_pk_fma_f32 v[90:91], v[90:91], v[102:103], v[124:125]
	v_pk_fma_f32 v[88:89], v[88:89], v[164:165], v[122:123]
	v_pk_fma_f32 v[100:101], v[86:87], v[104:105], v[148:149]
	v_pk_fma_f32 v[102:103], v[84:85], v[166:167], v[126:127]
	v_cvt_pk_bf16_f32 v84, v92, v93
	v_cvt_pk_bf16_f32 v85, v94, v95
	v_cvt_pk_bf16_f32 v86, v88, v89
	v_cvt_pk_bf16_f32 v87, v90, v91
	v_pk_fma_f32 v[88:89], v[82:83], v[106:107], v[160:161]
	v_pk_fma_f32 v[82:83], v[80:81], v[168:169], v[158:159]
	global_store_dwordx4 v[112:113], v[84:87], off
	v_cvt_pk_bf16_f32 v80, v102, v103
	v_cvt_pk_bf16_f32 v81, v100, v101
	v_cvt_pk_bf16_f32 v82, v82, v83
	v_cvt_pk_bf16_f32 v83, v88, v89
	global_load_dwordx4 v[84:87], v[98:99], off offset:2048
	v_lshlrev_b32_e32 v102, 16, v108
	global_store_dwordx4 v[112:113], v[80:83], off offset:256
	global_load_dwordx4 v[88:91], v[98:99], off offset:2304
	v_and_b32_e32 v103, 0xffff0000, v108
	v_add_u32_e32 v80, 0x80, v146
	v_ashrrev_i32_e32 v81, 31, v80
	v_lshlrev_b64 v[82:83], 12, v[80:81]
	v_lshlrev_b64 v[80:81], 11, v[80:81]
	v_lshlrev_b32_e32 v104, 16, v109
	v_and_b32_e32 v105, 0xffff0000, v109
	v_lshlrev_b32_e32 v106, 16, v110
	v_and_b32_e32 v107, 0xffff0000, v110
	v_lshlrev_b32_e32 v108, 16, v111
	v_and_b32_e32 v109, 0xffff0000, v111
	v_lshl_add_u64 v[80:81], s[14:15], 0, v[80:81]
	v_lshlrev_b32_e32 v110, 16, v114
	v_and_b32_e32 v111, 0xffff0000, v114
	v_lshlrev_b32_e32 v112, 16, v115
	v_and_b32_e32 v113, 0xffff0000, v115
	v_lshlrev_b32_e32 v114, 16, v116
	v_and_b32_e32 v115, 0xffff0000, v116
	v_lshlrev_b32_e32 v116, 16, v117
	v_and_b32_e32 v117, 0xffff0000, v117
	v_lshl_add_u64 v[82:83], s[6:7], 0, v[82:83]
	v_lshl_add_u64 v[80:81], v[80:81], 0, v[144:145]
	v_lshl_add_u64 v[82:83], v[82:83], 0, v[144:145]
	global_load_dwordx4 v[92:95], v[80:81], off
	global_load_dwordx4 v[98:101], v[80:81], off offset:256
	s_waitcnt vmcnt(0)
	v_lshlrev_b32_e32 v118, 16, v84
	v_and_b32_e32 v119, 0xffff0000, v84
	v_lshlrev_b32_e32 v84, 16, v85
	v_and_b32_e32 v85, 0xffff0000, v85
	v_lshlrev_b32_e32 v120, 16, v86
	v_and_b32_e32 v121, 0xffff0000, v86
	v_lshlrev_b32_e32 v86, 16, v87
	v_and_b32_e32 v87, 0xffff0000, v87
	v_lshlrev_b32_e32 v122, 16, v88
	v_and_b32_e32 v123, 0xffff0000, v88
	v_lshlrev_b32_e32 v88, 16, v89
	v_and_b32_e32 v89, 0xffff0000, v89
	v_lshlrev_b32_e32 v124, 16, v90
	v_and_b32_e32 v125, 0xffff0000, v90
	v_lshlrev_b32_e32 v90, 16, v91
	v_and_b32_e32 v91, 0xffff0000, v91
	v_pk_fma_f32 v[78:79], v[78:79], v[84:85], v[104:105]
	v_pk_fma_f32 v[76:77], v[76:77], v[118:119], v[102:103]
	v_pk_fma_f32 v[74:75], v[74:75], v[86:87], v[108:109]
	v_pk_fma_f32 v[72:73], v[72:73], v[120:121], v[106:107]
	v_pk_fma_f32 v[84:85], v[70:71], v[88:89], v[112:113]
	v_pk_fma_f32 v[86:87], v[68:69], v[122:123], v[110:111]
	v_cvt_pk_bf16_f32 v68, v76, v77
	v_cvt_pk_bf16_f32 v69, v78, v79
	v_cvt_pk_bf16_f32 v70, v72, v73
	v_cvt_pk_bf16_f32 v71, v74, v75
	v_pk_fma_f32 v[72:73], v[66:67], v[90:91], v[116:117]
	v_pk_fma_f32 v[66:67], v[64:65], v[124:125], v[114:115]
	global_store_dwordx4 v[96:97], v[68:71], off
	v_cvt_pk_bf16_f32 v64, v86, v87
	v_cvt_pk_bf16_f32 v65, v84, v85
	v_cvt_pk_bf16_f32 v66, v66, v67
	v_cvt_pk_bf16_f32 v67, v72, v73
	global_load_dwordx4 v[68:71], v[82:83], off offset:2048
	v_lshlrev_b32_e32 v86, 16, v92
	global_store_dwordx4 v[96:97], v[64:67], off offset:256
	global_load_dwordx4 v[72:75], v[82:83], off offset:2304
	v_and_b32_e32 v87, 0xffff0000, v92
	v_add_u32_e32 v64, 0x90, v146
	v_ashrrev_i32_e32 v65, 31, v64
	v_lshlrev_b64 v[66:67], 12, v[64:65]
	v_lshlrev_b64 v[64:65], 11, v[64:65]
	v_lshlrev_b32_e32 v88, 16, v93
	v_and_b32_e32 v89, 0xffff0000, v93
	v_lshlrev_b32_e32 v90, 16, v94
	v_and_b32_e32 v91, 0xffff0000, v94
	v_lshlrev_b32_e32 v92, 16, v95
	v_and_b32_e32 v93, 0xffff0000, v95
	v_lshl_add_u64 v[64:65], s[14:15], 0, v[64:65]
	v_lshlrev_b32_e32 v94, 16, v98
	v_and_b32_e32 v95, 0xffff0000, v98
	v_lshlrev_b32_e32 v96, 16, v99
	v_and_b32_e32 v97, 0xffff0000, v99
	v_lshlrev_b32_e32 v98, 16, v100
	v_and_b32_e32 v99, 0xffff0000, v100
	v_lshlrev_b32_e32 v100, 16, v101
	v_and_b32_e32 v101, 0xffff0000, v101
	v_lshl_add_u64 v[66:67], s[6:7], 0, v[66:67]
	v_lshl_add_u64 v[64:65], v[64:65], 0, v[144:145]
	v_lshl_add_u64 v[66:67], v[66:67], 0, v[144:145]
	global_load_dwordx4 v[76:79], v[64:65], off
	global_load_dwordx4 v[82:85], v[64:65], off offset:256
	s_waitcnt vmcnt(0)
	v_lshlrev_b32_e32 v102, 16, v68
	v_and_b32_e32 v103, 0xffff0000, v68
	v_lshlrev_b32_e32 v68, 16, v69
	v_and_b32_e32 v69, 0xffff0000, v69
	v_lshlrev_b32_e32 v104, 16, v70
	v_and_b32_e32 v105, 0xffff0000, v70
	v_lshlrev_b32_e32 v70, 16, v71
	v_and_b32_e32 v71, 0xffff0000, v71
	v_lshlrev_b32_e32 v106, 16, v72
	v_and_b32_e32 v107, 0xffff0000, v72
	v_lshlrev_b32_e32 v72, 16, v73
	v_and_b32_e32 v73, 0xffff0000, v73
	v_lshlrev_b32_e32 v108, 16, v74
	v_and_b32_e32 v109, 0xffff0000, v74
	v_lshlrev_b32_e32 v74, 16, v75
	v_and_b32_e32 v75, 0xffff0000, v75
	v_pk_fma_f32 v[62:63], v[62:63], v[68:69], v[88:89]
	v_pk_fma_f32 v[60:61], v[60:61], v[102:103], v[86:87]
	v_pk_fma_f32 v[58:59], v[58:59], v[70:71], v[92:93]
	v_pk_fma_f32 v[56:57], v[56:57], v[104:105], v[90:91]
	v_pk_fma_f32 v[68:69], v[54:55], v[72:73], v[96:97]
	v_pk_fma_f32 v[70:71], v[52:53], v[106:107], v[94:95]
	v_cvt_pk_bf16_f32 v52, v60, v61
	v_cvt_pk_bf16_f32 v53, v62, v63
	v_cvt_pk_bf16_f32 v54, v56, v57
	v_cvt_pk_bf16_f32 v55, v58, v59
	v_pk_fma_f32 v[56:57], v[50:51], v[74:75], v[100:101]
	v_pk_fma_f32 v[50:51], v[48:49], v[108:109], v[98:99]
	global_store_dwordx4 v[80:81], v[52:55], off
	v_cvt_pk_bf16_f32 v48, v70, v71
	v_cvt_pk_bf16_f32 v49, v68, v69
	v_cvt_pk_bf16_f32 v50, v50, v51
	v_cvt_pk_bf16_f32 v51, v56, v57
	global_load_dwordx4 v[52:55], v[66:67], off offset:2048
	v_lshlrev_b32_e32 v70, 16, v76
	global_store_dwordx4 v[80:81], v[48:51], off offset:256
	global_load_dwordx4 v[56:59], v[66:67], off offset:2304
	v_and_b32_e32 v71, 0xffff0000, v76
	v_add_u32_e32 v48, 0xa0, v146
	v_ashrrev_i32_e32 v49, 31, v48
	v_lshlrev_b64 v[50:51], 12, v[48:49]
	v_lshlrev_b64 v[48:49], 11, v[48:49]
	v_lshlrev_b32_e32 v72, 16, v77
	v_and_b32_e32 v73, 0xffff0000, v77
	v_lshlrev_b32_e32 v74, 16, v78
	v_and_b32_e32 v75, 0xffff0000, v78
	v_lshlrev_b32_e32 v76, 16, v79
	v_and_b32_e32 v77, 0xffff0000, v79
	v_lshl_add_u64 v[48:49], s[14:15], 0, v[48:49]
	v_lshlrev_b32_e32 v78, 16, v82
	v_and_b32_e32 v79, 0xffff0000, v82
	v_lshlrev_b32_e32 v80, 16, v83
	v_and_b32_e32 v81, 0xffff0000, v83
	v_lshlrev_b32_e32 v82, 16, v84
	v_and_b32_e32 v83, 0xffff0000, v84
	v_lshlrev_b32_e32 v84, 16, v85
	v_and_b32_e32 v85, 0xffff0000, v85
	v_lshl_add_u64 v[50:51], s[6:7], 0, v[50:51]
	v_lshl_add_u64 v[48:49], v[48:49], 0, v[144:145]
	v_lshl_add_u64 v[50:51], v[50:51], 0, v[144:145]
	global_load_dwordx4 v[60:63], v[48:49], off
	global_load_dwordx4 v[66:69], v[48:49], off offset:256
	s_waitcnt vmcnt(0)
	v_lshlrev_b32_e32 v86, 16, v52
	v_and_b32_e32 v87, 0xffff0000, v52
	v_lshlrev_b32_e32 v52, 16, v53
	v_and_b32_e32 v53, 0xffff0000, v53
	v_lshlrev_b32_e32 v88, 16, v54
	v_and_b32_e32 v89, 0xffff0000, v54
	v_lshlrev_b32_e32 v54, 16, v55
	v_and_b32_e32 v55, 0xffff0000, v55
	v_lshlrev_b32_e32 v90, 16, v56
	v_and_b32_e32 v91, 0xffff0000, v56
	v_lshlrev_b32_e32 v56, 16, v57
	v_and_b32_e32 v57, 0xffff0000, v57
	v_lshlrev_b32_e32 v92, 16, v58
	v_and_b32_e32 v93, 0xffff0000, v58
	v_lshlrev_b32_e32 v58, 16, v59
	v_and_b32_e32 v59, 0xffff0000, v59
	v_pk_fma_f32 v[46:47], v[46:47], v[52:53], v[72:73]
	v_pk_fma_f32 v[44:45], v[44:45], v[86:87], v[70:71]
	v_pk_fma_f32 v[42:43], v[42:43], v[54:55], v[76:77]
	v_pk_fma_f32 v[40:41], v[40:41], v[88:89], v[74:75]
	v_pk_fma_f32 v[52:53], v[38:39], v[56:57], v[80:81]
	v_pk_fma_f32 v[54:55], v[36:37], v[90:91], v[78:79]
	v_cvt_pk_bf16_f32 v36, v44, v45
	v_cvt_pk_bf16_f32 v37, v46, v47
	v_cvt_pk_bf16_f32 v38, v40, v41
	v_cvt_pk_bf16_f32 v39, v42, v43
	v_pk_fma_f32 v[40:41], v[34:35], v[58:59], v[84:85]
	v_pk_fma_f32 v[34:35], v[32:33], v[92:93], v[82:83]
	global_store_dwordx4 v[64:65], v[36:39], off
	v_cvt_pk_bf16_f32 v32, v54, v55
	v_cvt_pk_bf16_f32 v33, v52, v53
	v_cvt_pk_bf16_f32 v34, v34, v35
	v_cvt_pk_bf16_f32 v35, v40, v41
	global_load_dwordx4 v[36:39], v[50:51], off offset:2048
	v_add_u32_e32 v40, 0xb0, v146
	global_store_dwordx4 v[64:65], v[32:35], off offset:256
	global_load_dwordx4 v[32:35], v[50:51], off offset:2304
	v_ashrrev_i32_e32 v41, 31, v40
	v_lshlrev_b64 v[42:43], 12, v[40:41]
	v_lshlrev_b64 v[40:41], 11, v[40:41]
	v_lshlrev_b32_e32 v54, 16, v60
	v_and_b32_e32 v55, 0xffff0000, v60
	v_lshlrev_b32_e32 v56, 16, v61
	v_and_b32_e32 v57, 0xffff0000, v61
	v_lshlrev_b32_e32 v58, 16, v62
	v_and_b32_e32 v59, 0xffff0000, v62
	v_lshlrev_b32_e32 v60, 16, v63
	v_and_b32_e32 v61, 0xffff0000, v63
	v_lshl_add_u64 v[40:41], s[14:15], 0, v[40:41]
	v_lshlrev_b32_e32 v62, 16, v66
	v_and_b32_e32 v63, 0xffff0000, v66
	v_lshlrev_b32_e32 v64, 16, v67
	v_and_b32_e32 v65, 0xffff0000, v67
	v_lshlrev_b32_e32 v66, 16, v68
	v_and_b32_e32 v67, 0xffff0000, v68
	v_lshlrev_b32_e32 v68, 16, v69
	v_and_b32_e32 v69, 0xffff0000, v69
	v_lshl_add_u64 v[42:43], s[6:7], 0, v[42:43]
	v_lshl_add_u64 v[52:53], v[40:41], 0, v[144:145]
	v_lshl_add_u64 v[50:51], v[42:43], 0, v[144:145]
	global_load_dwordx4 v[40:43], v[52:53], off
	global_load_dwordx4 v[44:47], v[52:53], off offset:256
	s_waitcnt vmcnt(0)
	v_lshlrev_b32_e32 v70, 16, v36
	v_and_b32_e32 v71, 0xffff0000, v36
	v_lshlrev_b32_e32 v36, 16, v37
	v_and_b32_e32 v37, 0xffff0000, v37
	v_lshlrev_b32_e32 v72, 16, v38
	v_and_b32_e32 v73, 0xffff0000, v38
	v_lshlrev_b32_e32 v38, 16, v39
	v_and_b32_e32 v39, 0xffff0000, v39
	v_lshlrev_b32_e32 v74, 16, v32
	v_and_b32_e32 v75, 0xffff0000, v32
	v_lshlrev_b32_e32 v32, 16, v33
	v_and_b32_e32 v33, 0xffff0000, v33
	v_lshlrev_b32_e32 v76, 16, v34
	v_and_b32_e32 v77, 0xffff0000, v34
	v_lshlrev_b32_e32 v34, 16, v35
	v_and_b32_e32 v35, 0xffff0000, v35
	v_pk_fma_f32 v[30:31], v[30:31], v[36:37], v[56:57]
	v_pk_fma_f32 v[28:29], v[28:29], v[70:71], v[54:55]
	v_pk_fma_f32 v[26:27], v[26:27], v[38:39], v[60:61]
	v_pk_fma_f32 v[24:25], v[24:25], v[72:73], v[58:59]
	v_pk_fma_f32 v[32:33], v[22:23], v[32:33], v[64:65]
	v_pk_fma_f32 v[36:37], v[20:21], v[74:75], v[62:63]
	v_cvt_pk_bf16_f32 v20, v28, v29
	v_cvt_pk_bf16_f32 v21, v30, v31
	v_cvt_pk_bf16_f32 v22, v24, v25
	v_cvt_pk_bf16_f32 v23, v26, v27
	v_pk_fma_f32 v[24:25], v[18:19], v[34:35], v[68:69]
	v_pk_fma_f32 v[18:19], v[16:17], v[76:77], v[66:67]
	global_store_dwordx4 v[48:49], v[20:23], off
	v_cvt_pk_bf16_f32 v16, v36, v37
	v_cvt_pk_bf16_f32 v17, v32, v33
	v_cvt_pk_bf16_f32 v18, v18, v19
	v_cvt_pk_bf16_f32 v19, v24, v25
	global_load_dwordx4 v[20:23], v[50:51], off offset:2048
	v_lshlrev_b32_e32 v24, 16, v40
	global_store_dwordx4 v[48:49], v[16:19], off offset:256
	global_load_dwordx4 v[16:19], v[50:51], off offset:2304
	v_and_b32_e32 v25, 0xffff0000, v40
	v_lshlrev_b32_e32 v26, 16, v41
	v_and_b32_e32 v27, 0xffff0000, v41
	v_lshlrev_b32_e32 v28, 16, v42
	v_and_b32_e32 v29, 0xffff0000, v42
	v_lshlrev_b32_e32 v30, 16, v43
	v_and_b32_e32 v31, 0xffff0000, v43
	v_lshlrev_b32_e32 v32, 16, v44
	v_and_b32_e32 v33, 0xffff0000, v44
	v_lshlrev_b32_e32 v34, 16, v45
	v_and_b32_e32 v35, 0xffff0000, v45
	v_lshlrev_b32_e32 v36, 16, v46
	v_and_b32_e32 v37, 0xffff0000, v46
	v_lshlrev_b32_e32 v38, 16, v47
	v_and_b32_e32 v39, 0xffff0000, v47
	s_waitcnt vmcnt(0)
	v_lshlrev_b32_e32 v40, 16, v20
	v_and_b32_e32 v41, 0xffff0000, v20
	v_lshlrev_b32_e32 v20, 16, v21
	v_and_b32_e32 v21, 0xffff0000, v21
	v_lshlrev_b32_e32 v42, 16, v22
	v_and_b32_e32 v43, 0xffff0000, v22
	v_lshlrev_b32_e32 v22, 16, v23
	v_and_b32_e32 v23, 0xffff0000, v23
	v_lshlrev_b32_e32 v44, 16, v16
	v_and_b32_e32 v45, 0xffff0000, v16
	v_lshlrev_b32_e32 v16, 16, v17
	v_and_b32_e32 v17, 0xffff0000, v17
	v_lshlrev_b32_e32 v46, 16, v18
	v_and_b32_e32 v47, 0xffff0000, v18
	v_lshlrev_b32_e32 v18, 16, v19
	v_and_b32_e32 v19, 0xffff0000, v19
	v_pk_fma_f32 v[14:15], v[14:15], v[20:21], v[26:27]
	v_pk_fma_f32 v[12:13], v[12:13], v[40:41], v[24:25]
	v_pk_fma_f32 v[10:11], v[10:11], v[22:23], v[30:31]
	v_pk_fma_f32 v[8:9], v[8:9], v[42:43], v[28:29]
	v_pk_fma_f32 v[6:7], v[6:7], v[16:17], v[34:35]
	v_pk_fma_f32 v[4:5], v[4:5], v[44:45], v[32:33]
	v_pk_fma_f32 v[16:17], v[2:3], v[18:19], v[38:39]
	v_pk_fma_f32 v[18:19], v[0:1], v[46:47], v[36:37]
	v_cvt_pk_bf16_f32 v0, v12, v13
	v_cvt_pk_bf16_f32 v1, v14, v15
	v_cvt_pk_bf16_f32 v2, v8, v9
	v_cvt_pk_bf16_f32 v3, v10, v11
	v_cvt_pk_bf16_f32 v4, v4, v5
	v_cvt_pk_bf16_f32 v5, v6, v7
	v_cvt_pk_bf16_f32 v6, v18, v19
	v_cvt_pk_bf16_f32 v7, v16, v17
	global_store_dwordx4 v[52:53], v[0:3], off
	global_store_dwordx4 v[52:53], v[4:7], off offset:256
	s_cbranch_vccz .LBB0_600
	s_waitcnt vmcnt(0)
	s_cmpk_gt_u32 s0, 0xff
	s_cbranch_scc1 .LBB0_607
	s_barrier

.LBB0_608:
	s_waitcnt lgkmcnt(0)
	s_barrier
	s_setprio 0
	s_and_saveexec_b64 s[4:5], s[80:81]
	s_cbranch_execz .LBB0_618
	buffer_wbl2 sc1
	s_waitcnt vmcnt(0)
	s_load_dwordx2 s[6:7], s[78:79], -0x8
	s_load_dword s0, s[78:79], 0x0
	v_mov_b32_e32 v0, 0
	v_mov_b32_e32 v1, 1
	v_mov_b32_e32 v3, 0
	s_mov_b64 s[18:19], 0
	s_waitcnt lgkmcnt(0)
	s_add_u32 s6, s6, 0x2300080
	s_addc_u32 s7, s7, 0
	s_mul_i32 s0, s0, 6
	global_atomic_add v0, v1, s[6:7]

.LBB0_624:
	s_or_b64 exec, exec, s[46:47]
	s_and_b64 vcc, exec, s[6:7]
	s_mov_b32 s46, s22
	s_mov_b32 s48, s24
	s_mov_b64 s[52:53], s[44:45]
	s_mov_b64 s[50:51], s[40:41]
	s_cbranch_vccnz .LBB0_677
	v_readfirstlane_b32 s6, v154
	s_bitcmp1_b32 s6, 8
	s_cbranch_scc0 .Lprio_625
	s_setprio 1
.Lprio_625:
.LBB0_625:
	s_add_i32 s57, s57, 1
	s_mul_i32 s6, s57, s60
	s_mul_hi_u32 s7, s57, s3
	s_add_i32 s7, s7, s6
	s_mul_i32 s6, s57, s3
	s_add_u32 s40, s6, s2
	s_addc_u32 s41, s7, s61
	v_cmp_gt_i64_e64 s[6:7], s[40:41], v[144:145]
	s_and_b64 vcc, exec, s[6:7]
	s_cbranch_vccnz .LBB0_627
	s_ashr_i32 s22, s40, 31
	s_lshr_b32 s22, s22, 29
	s_add_i32 s22, s40, s22
	s_ashr_i32 s23, s22, 3
	s_and_b32 s22, s22, -8
	s_sub_i32 s22, s40, s22
	s_cmp_lt_i32 s22, 0
	s_cselect_b32 s24, s62, 0xc0
	s_mul_i32 s22, s24, s22
	s_add_i32 s22, s22, s23
	s_ashr_i32 s23, s22, 31
	s_lshr_b32 s23, s23, 27
	s_add_i32 s23, s22, s23
	s_ashr_i32 s24, s23, 5
	s_lshl_b32 s24, s24, 3
	s_sub_i32 s25, 0x180, s24
	s_min_i32 s25, s25, 8
	s_abs_i32 s44, s25
	v_cvt_f32_u32_e32 v0, s44
	s_sub_i32 s47, 0, s44
	s_andn2_b32 s23, s23, 31
	s_sub_i32 s23, s22, s23
	v_rcp_iflag_f32_e32 v0, v0
	s_abs_i32 s22, s23
	s_xor_b32 s45, s23, s25
	s_ashr_i32 s45, s45, 31
	v_mul_f32_e32 v0, 0x4f7ffffe, v0
	v_cvt_u32_f32_e32 v0, v0
	s_nop 0
	v_readfirstlane_b32 s49, v0
	s_mul_i32 s47, s47, s49
	s_mul_hi_u32 s47, s49, s47
	s_add_i32 s49, s49, s47
	s_mul_hi_u32 s47, s22, s49
	s_mul_i32 s49, s47, s44
	s_sub_i32 s22, s22, s49
	s_add_i32 s54, s47, 1
	s_sub_i32 s49, s22, s44
	s_cmp_ge_u32 s22, s44
	s_cselect_b32 s47, s54, s47
	s_cselect_b32 s22, s49, s22
	s_add_i32 s49, s47, 1
	s_cmp_ge_u32 s22, s44
	s_cselect_b32 s22, s49, s47
	s_xor_b32 s22, s22, s45
	s_sub_i32 s22, s22, s45
	s_mul_i32 s25, s22, s25
	s_sub_i32 s23, s23, s25
	s_add_i32 s24, s23, s24

.LBB0_628:
	ds_read_b128 v[146:149], v159
	ds_read_b128 v[150:153], v159 offset:1024
	ds_read_b128 v[164:167], v159 offset:2048
	ds_read_b128 v[168:171], v159 offset:3072
	s_add_u32 s52, s50, 0xfffc0080
	s_addc_u32 s53, s51, -1
	s_cmp_eq_u32 s71, 12
	s_cselect_b32 s55, s25, s53
	s_cselect_b32 s54, s47, s52
	s_cselect_b32 s53, s23, s70
	s_cselect_b32 s52, s49, s69
	v_lshl_add_u64 v[204:205], s[50:51], 0, v[138:139]
	s_add_i32 m0, s33, 0xc000
	ds_read_b128 v[172:175], v160
	ds_read_b128 v[176:179], v160 offset:1024
	ds_read_b128 v[180:183], v160 offset:2048
	ds_read_b128 v[184:187], v160 offset:3072
	ds_read_b128 v[188:191], v160 offset:4096
	ds_read_b128 v[192:195], v160 offset:5120
	ds_read_b128 v[196:199], v160 offset:6144
	ds_read_b128 v[200:203], v160 offset:7168
	global_load_lds_dwordx4 v[204:205], off
	v_lshl_add_u64 v[204:205], s[50:51], 0, v[140:141]
	s_add_i32 m0, s33, 0xe000
	s_nop 0
	global_load_lds_dwordx4 v[204:205], off
	s_waitcnt lgkmcnt(8)
	s_barrier
	s_waitcnt lgkmcnt(0)
	s_waitcnt lgkmcnt(0)
	v_mfma_f32_16x16x32_bf16 v[124:127], v[146:149], v[172:175], v[124:127]
	v_mfma_f32_16x16x32_bf16 v[120:123], v[164:167], v[172:175], v[120:123]
	v_mfma_f32_16x16x32_bf16 v[108:111], v[146:149], v[180:183], v[108:111]
	v_mfma_f32_16x16x32_bf16 v[104:107], v[164:167], v[180:183], v[104:107]
	v_mfma_f32_16x16x32_bf16 v[92:95], v[146:149], v[188:191], v[92:95]
	v_mfma_f32_16x16x32_bf16 v[88:91], v[164:167], v[188:191], v[88:91]
	v_mfma_f32_16x16x32_bf16 v[76:79], v[146:149], v[196:199], v[76:79]
	v_mfma_f32_16x16x32_bf16 v[72:75], v[164:167], v[196:199], v[72:75]
	v_mfma_f32_16x16x32_bf16 v[124:127], v[150:153], v[176:179], v[124:127]
	v_mfma_f32_16x16x32_bf16 v[120:123], v[168:171], v[176:179], v[120:123]
	v_mfma_f32_16x16x32_bf16 v[108:111], v[150:153], v[184:187], v[108:111]
	v_mfma_f32_16x16x32_bf16 v[104:107], v[168:171], v[184:187], v[104:107]
	v_mfma_f32_16x16x32_bf16 v[92:95], v[150:153], v[192:195], v[92:95]
	v_mfma_f32_16x16x32_bf16 v[88:91], v[168:171], v[192:195], v[88:91]
	v_mfma_f32_16x16x32_bf16 v[76:79], v[150:153], v[200:203], v[76:79]
	v_mfma_f32_16x16x32_bf16 v[72:75], v[168:171], v[200:203], v[72:75]
	s_barrier
	s_add_i32 s73, s63, s1
	v_lshl_add_u64 v[220:221], s[52:53], 0, v[130:131]
	s_mov_b32 m0, s73
	ds_read_b128 v[204:207], v161
	ds_read_b128 v[208:211], v161 offset:1024
	ds_read_b128 v[212:215], v161 offset:2048
	ds_read_b128 v[216:219], v161 offset:3072
	global_load_lds_dwordx4 v[220:221], off
	v_lshl_add_u64 v[222:223], s[52:53], 0, v[134:135]
	s_add_i32 m0, s73, 0x2000
	s_nop 0
	global_load_lds_dwordx4 v[222:223], off
	s_barrier
	s_waitcnt lgkmcnt(0)
	s_waitcnt lgkmcnt(0)
	v_mfma_f32_16x16x32_bf16 v[116:119], v[204:207], v[172:175], v[116:119]
	v_mfma_f32_16x16x32_bf16 v[112:115], v[212:215], v[172:175], v[112:115]
	v_mfma_f32_16x16x32_bf16 v[100:103], v[204:207], v[180:183], v[100:103]
	v_mfma_f32_16x16x32_bf16 v[96:99], v[212:215], v[180:183], v[96:99]
	v_mfma_f32_16x16x32_bf16 v[84:87], v[204:207], v[188:191], v[84:87]
	v_mfma_f32_16x16x32_bf16 v[80:83], v[212:215], v[188:191], v[80:83]
	v_mfma_f32_16x16x32_bf16 v[68:71], v[204:207], v[196:199], v[68:71]
	v_mfma_f32_16x16x32_bf16 v[64:67], v[212:215], v[196:199], v[64:67]
	v_mfma_f32_16x16x32_bf16 v[116:119], v[208:211], v[176:179], v[116:119]
	v_mfma_f32_16x16x32_bf16 v[112:115], v[216:219], v[176:179], v[112:115]
	v_mfma_f32_16x16x32_bf16 v[100:103], v[208:211], v[184:187], v[100:103]
	v_mfma_f32_16x16x32_bf16 v[96:99], v[216:219], v[184:187], v[96:99]
	v_mfma_f32_16x16x32_bf16 v[84:87], v[208:211], v[192:195], v[84:87]
	v_mfma_f32_16x16x32_bf16 v[80:83], v[216:219], v[192:195], v[80:83]
	v_mfma_f32_16x16x32_bf16 v[68:71], v[208:211], v[200:203], v[68:71]
	v_mfma_f32_16x16x32_bf16 v[64:67], v[216:219], v[200:203], v[64:67]
	s_mov_b32 m0, s33
	v_lshl_add_u64 v[224:225], s[54:55], 0, v[128:129]
	s_barrier
	ds_read_b128 v[172:175], v160 offset:16384
	ds_read_b128 v[176:179], v160 offset:17408
	ds_read_b128 v[180:183], v160 offset:18432
	ds_read_b128 v[184:187], v160 offset:19456
	ds_read_b128 v[188:191], v160 offset:20480
	ds_read_b128 v[192:195], v160 offset:21504
	ds_read_b128 v[196:199], v160 offset:22528
	ds_read_b128 v[200:203], v160 offset:23552
	global_load_lds_dwordx4 v[224:225], off
	v_lshl_add_u64 v[226:227], s[54:55], 0, v[132:133]
	s_mov_b32 m0, s34
	s_nop 0
	global_load_lds_dwordx4 v[226:227], off
	s_barrier
	s_waitcnt lgkmcnt(0)
	s_waitcnt lgkmcnt(0)
	v_mfma_f32_16x16x32_bf16 v[60:63], v[146:149], v[172:175], v[60:63]
	v_mfma_f32_16x16x32_bf16 v[56:59], v[164:167], v[172:175], v[56:59]
	v_mfma_f32_16x16x32_bf16 v[44:47], v[146:149], v[180:183], v[44:47]
	v_mfma_f32_16x16x32_bf16 v[40:43], v[164:167], v[180:183], v[40:43]
	v_mfma_f32_16x16x32_bf16 v[28:31], v[146:149], v[188:191], v[28:31]
	v_mfma_f32_16x16x32_bf16 v[24:27], v[164:167], v[188:191], v[24:27]
	v_mfma_f32_16x16x32_bf16 v[12:15], v[146:149], v[196:199], v[12:15]
	v_mfma_f32_16x16x32_bf16 v[8:11], v[164:167], v[196:199], v[8:11]
	v_mfma_f32_16x16x32_bf16 v[60:63], v[150:153], v[176:179], v[60:63]
	v_mfma_f32_16x16x32_bf16 v[56:59], v[168:171], v[176:179], v[56:59]
	v_mfma_f32_16x16x32_bf16 v[44:47], v[150:153], v[184:187], v[44:47]
	v_mfma_f32_16x16x32_bf16 v[40:43], v[168:171], v[184:187], v[40:43]
	v_mfma_f32_16x16x32_bf16 v[28:31], v[150:153], v[192:195], v[28:31]
	v_mfma_f32_16x16x32_bf16 v[24:27], v[168:171], v[192:195], v[24:27]
	v_mfma_f32_16x16x32_bf16 v[12:15], v[150:153], v[200:203], v[12:15]
	v_mfma_f32_16x16x32_bf16 v[8:11], v[168:171], v[200:203], v[8:11]
	s_barrier
	s_add_u32 s74, s52, 0x40000
	s_addc_u32 s75, s53, 0
	s_add_i32 s73, s72, s1
	v_lshl_add_u64 v[146:147], s[74:75], 0, v[130:131]
	s_mov_b32 m0, s73
	s_nop 0
	global_load_lds_dwordx4 v[146:147], off
	v_lshl_add_u64 v[146:147], s[74:75], 0, v[134:135]
	s_add_i32 m0, s73, 0x2000
	s_nop 0
	global_load_lds_dwordx4 v[146:147], off
	s_waitcnt vmcnt(6)
	s_barrier
	v_mfma_f32_16x16x32_bf16 v[52:55], v[204:207], v[172:175], v[52:55]
	v_mfma_f32_16x16x32_bf16 v[48:51], v[212:215], v[172:175], v[48:51]
	v_mfma_f32_16x16x32_bf16 v[36:39], v[204:207], v[180:183], v[36:39]
	v_mfma_f32_16x16x32_bf16 v[32:35], v[212:215], v[180:183], v[32:35]
	v_mfma_f32_16x16x32_bf16 v[20:23], v[204:207], v[188:191], v[20:23]
	v_mfma_f32_16x16x32_bf16 v[16:19], v[212:215], v[188:191], v[16:19]
	v_mfma_f32_16x16x32_bf16 v[4:7], v[204:207], v[196:199], v[4:7]
	v_mfma_f32_16x16x32_bf16 v[0:3], v[212:215], v[196:199], v[0:3]
	v_mfma_f32_16x16x32_bf16 v[52:55], v[208:211], v[176:179], v[52:55]
	v_mfma_f32_16x16x32_bf16 v[48:51], v[216:219], v[176:179], v[48:51]
	v_mfma_f32_16x16x32_bf16 v[36:39], v[208:211], v[184:187], v[36:39]
	v_mfma_f32_16x16x32_bf16 v[32:35], v[216:219], v[184:187], v[32:35]
	v_mfma_f32_16x16x32_bf16 v[20:23], v[208:211], v[192:195], v[20:23]
	v_mfma_f32_16x16x32_bf16 v[16:19], v[216:219], v[192:195], v[16:19]
	v_mfma_f32_16x16x32_bf16 v[4:7], v[208:211], v[200:203], v[4:7]
	v_mfma_f32_16x16x32_bf16 v[0:3], v[216:219], v[200:203], v[0:3]
	s_add_i32 s73, 0, 0x18000
	v_add_u32_e32 v136, s73, v157
	s_barrier
	ds_read_b128 v[146:149], v136
	ds_read_b128 v[150:153], v136 offset:1024
	ds_read_b128 v[164:167], v136 offset:2048
	ds_read_b128 v[168:171], v136 offset:3072
	s_add_u32 s54, s54, 0x40000
	s_addc_u32 s55, s55, 0
	s_mov_b32 m0, s35
	v_lshl_add_u64 v[204:205], s[54:55], 0, v[128:129]
	ds_read_b128 v[172:175], v160 offset:32768
	ds_read_b128 v[176:179], v160 offset:33792
	ds_read_b128 v[180:183], v160 offset:34816
	ds_read_b128 v[184:187], v160 offset:35840
	ds_read_b128 v[188:191], v160 offset:36864
	ds_read_b128 v[192:195], v160 offset:37888
	ds_read_b128 v[196:199], v160 offset:38912
	ds_read_b128 v[200:203], v160 offset:39936
	global_load_lds_dwordx4 v[204:205], off
	v_lshl_add_u64 v[204:205], s[54:55], 0, v[132:133]
	s_mov_b32 m0, s56
	s_nop 0
	global_load_lds_dwordx4 v[204:205], off
	s_waitcnt lgkmcnt(8)
	s_barrier
	s_waitcnt lgkmcnt(0)
	s_waitcnt lgkmcnt(0)
	v_mfma_f32_16x16x32_bf16 v[124:127], v[146:149], v[172:175], v[124:127]
	v_mfma_f32_16x16x32_bf16 v[120:123], v[164:167], v[172:175], v[120:123]
	v_mfma_f32_16x16x32_bf16 v[108:111], v[146:149], v[180:183], v[108:111]
	v_mfma_f32_16x16x32_bf16 v[104:107], v[164:167], v[180:183], v[104:107]
	v_mfma_f32_16x16x32_bf16 v[92:95], v[146:149], v[188:191], v[92:95]
	v_mfma_f32_16x16x32_bf16 v[88:91], v[164:167], v[188:191], v[88:91]
	v_mfma_f32_16x16x32_bf16 v[76:79], v[146:149], v[196:199], v[76:79]
	v_mfma_f32_16x16x32_bf16 v[72:75], v[164:167], v[196:199], v[72:75]
	v_mfma_f32_16x16x32_bf16 v[124:127], v[150:153], v[176:179], v[124:127]
	v_mfma_f32_16x16x32_bf16 v[120:123], v[168:171], v[176:179], v[120:123]
	v_mfma_f32_16x16x32_bf16 v[108:111], v[150:153], v[184:187], v[108:111]
	v_mfma_f32_16x16x32_bf16 v[104:107], v[168:171], v[184:187], v[104:107]
	v_mfma_f32_16x16x32_bf16 v[92:95], v[150:153], v[192:195], v[92:95]
	v_mfma_f32_16x16x32_bf16 v[88:91], v[168:171], v[192:195], v[88:91]
	v_mfma_f32_16x16x32_bf16 v[76:79], v[150:153], v[200:203], v[76:79]
	v_mfma_f32_16x16x32_bf16 v[72:75], v[168:171], v[200:203], v[72:75]
	s_barrier
	s_add_i32 s54, s73, s1
	v_add_u32_e32 v136, s97, v157
	v_lshl_add_u64 v[220:221], v[220:221], 0, s[20:21]
	s_mov_b32 m0, s54
	ds_read_b128 v[204:207], v136
	ds_read_b128 v[208:211], v136 offset:1024
	ds_read_b128 v[212:215], v136 offset:2048
	ds_read_b128 v[216:219], v136 offset:3072
	global_load_lds_dwordx4 v[220:221], off
	v_lshl_add_u64 v[220:221], v[222:223], 0, s[20:21]
	s_add_i32 m0, s54, 0x2000
	s_nop 0
	global_load_lds_dwordx4 v[220:221], off
	s_barrier
	s_waitcnt lgkmcnt(0)
	s_waitcnt lgkmcnt(0)
	v_mfma_f32_16x16x32_bf16 v[116:119], v[204:207], v[172:175], v[116:119]
	v_mfma_f32_16x16x32_bf16 v[112:115], v[212:215], v[172:175], v[112:115]
	v_mfma_f32_16x16x32_bf16 v[100:103], v[204:207], v[180:183], v[100:103]
	v_mfma_f32_16x16x32_bf16 v[96:99], v[212:215], v[180:183], v[96:99]
	v_mfma_f32_16x16x32_bf16 v[84:87], v[204:207], v[188:191], v[84:87]
	v_mfma_f32_16x16x32_bf16 v[80:83], v[212:215], v[188:191], v[80:83]
	v_mfma_f32_16x16x32_bf16 v[68:71], v[204:207], v[196:199], v[68:71]
	v_mfma_f32_16x16x32_bf16 v[64:67], v[212:215], v[196:199], v[64:67]
	v_mfma_f32_16x16x32_bf16 v[116:119], v[208:211], v[176:179], v[116:119]
	v_mfma_f32_16x16x32_bf16 v[112:115], v[216:219], v[176:179], v[112:115]
	v_mfma_f32_16x16x32_bf16 v[100:103], v[208:211], v[184:187], v[100:103]
	v_mfma_f32_16x16x32_bf16 v[96:99], v[216:219], v[184:187], v[96:99]
	v_mfma_f32_16x16x32_bf16 v[84:87], v[208:211], v[192:195], v[84:87]
	v_mfma_f32_16x16x32_bf16 v[80:83], v[216:219], v[192:195], v[80:83]
	v_mfma_f32_16x16x32_bf16 v[68:71], v[208:211], v[200:203], v[68:71]
	v_mfma_f32_16x16x32_bf16 v[64:67], v[216:219], v[200:203], v[64:67]
	s_mov_b32 m0, s58
	v_lshl_add_u64 v[220:221], v[224:225], 0, s[20:21]
	s_barrier
	ds_read_b128 v[172:175], v160 offset:49152
	ds_read_b128 v[176:179], v160 offset:50176
	ds_read_b128 v[180:183], v160 offset:51200
	ds_read_b128 v[184:187], v160 offset:52224
	ds_read_b128 v[188:191], v160 offset:53248
	ds_read_b128 v[192:195], v160 offset:54272
	ds_read_b128 v[196:199], v160 offset:55296
	ds_read_b128 v[200:203], v160 offset:56320
	global_load_lds_dwordx4 v[220:221], off
	v_lshl_add_u64 v[220:221], v[226:227], 0, s[20:21]
	s_mov_b32 m0, s59
	s_nop 0
	global_load_lds_dwordx4 v[220:221], off
	s_barrier
	s_waitcnt lgkmcnt(0)
	s_waitcnt lgkmcnt(0)
	v_mfma_f32_16x16x32_bf16 v[60:63], v[146:149], v[172:175], v[60:63]
	v_mfma_f32_16x16x32_bf16 v[56:59], v[164:167], v[172:175], v[56:59]
	v_mfma_f32_16x16x32_bf16 v[44:47], v[146:149], v[180:183], v[44:47]
	v_mfma_f32_16x16x32_bf16 v[40:43], v[164:167], v[180:183], v[40:43]
	v_mfma_f32_16x16x32_bf16 v[28:31], v[146:149], v[188:191], v[28:31]
	v_mfma_f32_16x16x32_bf16 v[24:27], v[164:167], v[188:191], v[24:27]
	v_mfma_f32_16x16x32_bf16 v[12:15], v[146:149], v[196:199], v[12:15]
	v_mfma_f32_16x16x32_bf16 v[8:11], v[164:167], v[196:199], v[8:11]
	v_mfma_f32_16x16x32_bf16 v[60:63], v[150:153], v[176:179], v[60:63]
	v_mfma_f32_16x16x32_bf16 v[56:59], v[168:171], v[176:179], v[56:59]
	v_mfma_f32_16x16x32_bf16 v[44:47], v[150:153], v[184:187], v[44:47]
	v_mfma_f32_16x16x32_bf16 v[40:43], v[168:171], v[184:187], v[40:43]
	v_mfma_f32_16x16x32_bf16 v[28:31], v[150:153], v[192:195], v[28:31]
	v_mfma_f32_16x16x32_bf16 v[24:27], v[168:171], v[192:195], v[24:27]
	v_mfma_f32_16x16x32_bf16 v[12:15], v[150:153], v[200:203], v[12:15]
	v_mfma_f32_16x16x32_bf16 v[8:11], v[168:171], v[200:203], v[8:11]
	s_barrier
	s_add_u32 s52, s52, 0x40080
	s_addc_u32 s53, s53, 0
	s_add_i32 s54, s97, s1
	v_lshl_add_u64 v[146:147], s[52:53], 0, v[130:131]
	s_mov_b32 m0, s54
	s_nop 0
	global_load_lds_dwordx4 v[146:147], off
	v_lshl_add_u64 v[146:147], s[52:53], 0, v[134:135]
	s_add_i32 m0, s54, 0x2000
	s_nop 0
	global_load_lds_dwordx4 v[146:147], off
	s_waitcnt vmcnt(6)
	s_barrier
	v_mfma_f32_16x16x32_bf16 v[52:55], v[204:207], v[172:175], v[52:55]
	v_mfma_f32_16x16x32_bf16 v[48:51], v[212:215], v[172:175], v[48:51]
	v_mfma_f32_16x16x32_bf16 v[36:39], v[204:207], v[180:183], v[36:39]
	v_mfma_f32_16x16x32_bf16 v[32:35], v[212:215], v[180:183], v[32:35]
	v_mfma_f32_16x16x32_bf16 v[20:23], v[204:207], v[188:191], v[20:23]
	v_mfma_f32_16x16x32_bf16 v[16:19], v[212:215], v[188:191], v[16:19]
	v_mfma_f32_16x16x32_bf16 v[4:7], v[204:207], v[196:199], v[4:7]
	v_mfma_f32_16x16x32_bf16 v[0:3], v[212:215], v[196:199], v[0:3]
	v_mfma_f32_16x16x32_bf16 v[52:55], v[208:211], v[176:179], v[52:55]
	v_mfma_f32_16x16x32_bf16 v[48:51], v[216:219], v[176:179], v[48:51]
	v_mfma_f32_16x16x32_bf16 v[36:39], v[208:211], v[184:187], v[36:39]
	v_mfma_f32_16x16x32_bf16 v[32:35], v[216:219], v[184:187], v[32:35]
	v_mfma_f32_16x16x32_bf16 v[20:23], v[208:211], v[192:195], v[20:23]
	v_mfma_f32_16x16x32_bf16 v[16:19], v[216:219], v[192:195], v[16:19]
	v_mfma_f32_16x16x32_bf16 v[4:7], v[208:211], v[200:203], v[4:7]
	v_mfma_f32_16x16x32_bf16 v[0:3], v[216:219], v[200:203], v[0:3]
	s_add_i32 s71, s71, 2
	s_add_u32 s50, s50, 0x100
	s_addc_u32 s51, s51, 0
	s_add_u32 s69, s69, 0x100
	s_addc_u32 s70, s70, 0
	s_cmp_gt_u32 s71, 13
	s_barrier
	s_cbranch_scc0 .LBB0_628
	v_lshl_add_u32 v150, s48, 8, v156
	v_cmp_lt_i32_e32 vcc, s64, v150
	s_and_saveexec_b64 s[48:49], vcc
	s_xor_b64 s[48:49], exec, s[48:49]
	v_add_u32_e32 v136, 0xffff0000, v150
	v_lshlrev_b64 v[146:147], 12, v[136:137]
	v_lshl_add_u64 v[152:153], s[38:39], 0, v[146:147]
	v_mov_b32_e32 v151, v137
	s_andn2_saveexec_b64 s[48:49], s[48:49]
	v_ashrrev_i32_e32 v151, 31, v150
	v_lshlrev_b64 v[146:147], 12, v[150:151]
	v_lshl_add_u64 v[152:153], s[36:37], 0, v[146:147]
	s_or_b64 exec, exec, s[48:49]
	v_lshl_or_b32 v146, s46, 8, v158
	v_ashrrev_i32_e32 v147, 31, v146
	v_lshlrev_b64 v[148:149], 2, v[146:147]
	v_lshl_add_u64 v[152:153], v[152:153], 0, v[148:149]
	global_load_dwordx4 v[164:167], v[152:153], off
	global_load_dwordx4 v[168:171], v[152:153], off offset:16
	v_lshlrev_b64 v[172:173], 12, v[150:151]
	v_lshlrev_b64 v[174:175], 11, v[150:151]
	v_lshl_add_u64 v[172:173], s[42:43], 0, v[172:173]
	v_lshl_add_u64 v[174:175], s[84:85], 0, v[174:175]
	v_lshl_add_u64 v[176:177], v[146:147], 1, v[174:175]
	v_lshl_add_u64 v[178:179], v[172:173], 0, v[148:149]
	s_waitcnt vmcnt(0)
	v_pk_add_f32 v[126:127], v[126:127], v[166:167]
	v_pk_add_f32 v[124:125], v[124:125], v[164:165]
	v_pk_add_f32 v[166:167], v[122:123], v[170:171]
	v_pk_add_f32 v[164:165], v[120:121], v[168:169]
	v_cvt_pk_bf16_f32 v120, v124, v125
	v_cvt_pk_bf16_f32 v121, v126, v127
	v_cvt_pk_bf16_f32 v122, v164, v165
	v_cvt_pk_bf16_f32 v123, v166, v167
	global_store_dwordx4 v[178:179], v[124:127], off
	global_store_dwordx4 v[178:179], v[164:167], off offset:16
	global_store_dwordx4 v[176:177], v[120:123], off
	global_load_dwordx4 v[168:171], v[152:153], off offset:512
	global_load_dwordx4 v[172:175], v[152:153], off offset:528
	v_and_b32_e32 v121, 64, v162
	v_xor_b32_e32 v120, 16, v162
	v_add_u32_e32 v121, 64, v121
	v_xor_b32_e32 v122, 32, v162
	v_cmp_lt_i32_e32 vcc, v120, v121
	v_mul_f32_e32 v123, v165, v165
	v_mul_f32_e32 v136, v166, v166
	v_cndmask_b32_e32 v120, v162, v120, vcc
	v_cmp_lt_i32_e32 vcc, v122, v121
	v_fmac_f32_e32 v123, v125, v125
	v_mul_f32_e32 v152, v167, v167
	v_cndmask_b32_e32 v121, v162, v122, vcc
	v_mul_f32_e32 v122, v164, v164
	v_fmac_f32_e32 v122, v124, v124
	v_fmac_f32_e32 v136, v126, v126
	v_add_f32_e32 v122, v122, v123
	v_fmac_f32_e32 v152, v127, v127
	v_add_f32_e32 v122, v136, v122
	v_add_f32_e32 v126, v152, v122
	v_lshlrev_b32_e32 v120, 2, v120
	s_waitcnt vmcnt(0)
	v_pk_add_f32 v[122:123], v[116:117], v[168:169]
	v_pk_add_f32 v[164:165], v[112:113], v[172:173]
	v_pk_add_f32 v[166:167], v[114:115], v[174:175]
	v_mul_f32_e32 v112, v164, v164
	v_mul_f32_e32 v113, v165, v165
	v_fmac_f32_e32 v112, v122, v122
	v_pk_add_f32 v[124:125], v[118:119], v[170:171]
	v_mul_f32_e32 v114, v166, v166
	v_fmac_f32_e32 v113, v123, v123
	v_add_f32_e32 v112, v126, v112
	v_mul_f32_e32 v115, v167, v167
	v_fmac_f32_e32 v114, v124, v124
	v_add_f32_e32 v112, v113, v112
	v_add_f32_e32 v112, v114, v112
	v_fmac_f32_e32 v115, v125, v125
	v_add_f32_e32 v112, v115, v112
	ds_bpermute_b32 v113, v120, v112
	v_lshlrev_b32_e32 v116, 2, v121
	global_store_dwordx4 v[178:179], v[122:125], off offset:512
	global_store_dwordx4 v[178:179], v[164:167], off offset:528
	s_waitcnt lgkmcnt(0)
	v_add_f32_e32 v112, v112, v113
	ds_bpermute_b32 v113, v116, v112
	v_cvt_pk_bf16_f32 v122, v122, v123
	v_cvt_pk_bf16_f32 v123, v124, v125
	v_cvt_pk_bf16_f32 v124, v164, v165
	v_cvt_pk_bf16_f32 v125, v166, v167
	global_store_dwordx4 v[176:177], v[122:125], off offset:256
	s_and_saveexec_b64 s[46:47], s[4:5]
	s_cbranch_execz .LBB0_635
	v_lshl_add_u64 v[114:115], v[150:151], 2, s[18:19]
	s_waitcnt lgkmcnt(0)
	v_add_f32_e32 v112, v112, v113
	global_atomic_add_f32 v[114:115], v112, off

.LBB0_680:
	s_waitcnt lgkmcnt(0)
	s_barrier
	s_setprio 0
	s_and_saveexec_b64 s[4:5], s[80:81]
	s_cbranch_execz .LBB0_690
	buffer_wbl2 sc1
	s_waitcnt vmcnt(0)
	s_load_dwordx2 s[6:7], s[78:79], -0x8
	s_load_dword s0, s[78:79], 0x0
	v_mov_b32_e32 v0, 0
	v_mov_b32_e32 v1, 1
	v_mov_b32_e32 v3, 0
	s_mov_b64 s[14:15], 0
	s_waitcnt lgkmcnt(0)
	s_add_u32 s6, s6, 0x2300080
	s_addc_u32 s7, s7, 0
	s_mul_i32 s0, s0, 7
	global_atomic_add v0, v1, s[6:7]

.LBB0_693:
	s_lshl_b32 s6, s6, 5
	s_mov_b64 s[14:15], 0x80
	s_and_b32 s17, s6, 0x60
	s_add_i32 m0, s47, 0x18000
	v_lshl_add_u64 v[6:7], v[6:7], 0, s[14:15]
	s_lshl_b32 s16, s5, 13
	s_lshl_b32 s20, s17, 7
	s_waitcnt vmcnt(4)
	s_barrier
	global_load_lds_dwordx4 v[6:7], off
	v_lshl_add_u64 v[4:5], v[4:5], 0, s[14:15]
	s_add_i32 m0, s47, 0x1a000
	s_add_i32 s57, s47, 0x8000
	s_add_i32 s58, s47, 0xa000
	global_load_lds_dwordx4 v[4:5], off
	v_lshl_add_u64 v[2:3], v[2:3], 0, s[14:15]
	s_mov_b32 m0, s57
	s_add_u32 s6, s48, 0x40080
	global_load_lds_dwordx4 v[2:3], off
	v_lshl_add_u64 v[0:1], v[0:1], 0, s[14:15]
	s_mov_b32 m0, s58
	s_addc_u32 s7, s49, 0
	global_load_lds_dwordx4 v[0:1], off
	s_add_i32 m0, s47, 0x1c000
	v_lshl_add_u64 v[0:1], s[6:7], 0, v[132:133]
	global_load_lds_dwordx4 v[0:1], off
	v_lshl_add_u64 v[0:1], s[6:7], 0, v[128:129]
	s_add_i32 m0, s47, 0x1e000
	s_add_i32 s60, 0, 0x10000
	global_load_lds_dwordx4 v[0:1], off
	v_lshrrev_b32_e32 v1, 1, v9
	v_and_b32_e32 v1, 24, v1
	v_and_b32_e32 v0, 15, v9
	v_lshlrev_b32_e32 v2, 1, v1
	v_lshl_or_b32 v152, s5, 6, v0
	v_lshl_or_b32 v0, v0, 6, v2
	v_lshlrev_b32_e32 v2, 2, v9
	v_and_b32_e32 v2, 32, v2
	v_bitop3_b32 v3, v0, s16, v2 bitop3:0xde
	v_bitop3_b32 v153, v0, s20, v2 bitop3:0xde
	v_lshlrev_b32_e32 v0, 14, v13
	v_and_b32_e32 v0, 0xffff8000, v0
	v_or_b32_e32 v156, s17, v1
	v_lshl_add_u32 v0, v12, 11, v0
	v_and_b32_e32 v1, 1, v13
	v_lshl_or_b32 v0, v1, 6, v0
	v_lshl_add_u32 v136, v14, 1, v0
	v_lshlrev_b32_e32 v0, 14, v8
	v_and_b32_e32 v0, 0xffff8000, v0
	s_waitcnt vmcnt(6)
	v_lshl_add_u32 v0, v10, 11, v0
	v_and_b32_e32 v1, 1, v8
	v_lshl_or_b32 v0, v1, 6, v0
	s_sext_i32_i8 s66, s4
	s_ashr_i32 s59, s3, 31
	v_mov_b32_e32 v137, v133
	v_lshl_add_u32 v138, v11, 1, v0
	v_mov_b32_e32 v139, v133
	v_mov_b64_e32 v[140:141], 0x1800
	v_mov_b64_e32 v[142:143], 0x17ff
	v_add_u32_e32 v157, s60, v153
	v_add_u32_e32 v158, 0, v3
	v_add_u32_e32 v159, s72, v153
	v_mov_b32_e32 v160, 0x358637bd
	s_mov_b32 s61, 0x800000
	s_mov_b64 s[16:17], 0x80000
	s_mov_b32 s62, 0x80000
	s_mov_b64 s[20:21], 0x90000
	s_mov_b32 s63, 0x90000
	s_mov_b64 s[22:23], 0xa0000
	s_mov_b32 s64, 0xa0000
	s_mov_b64 s[24:25], 0xb0000
	s_mov_b32 s65, 0xb0000
	s_barrier
	v_readfirstlane_b32 s4, v154
	s_bitcmp1_b32 s4, 8
	s_cbranch_scc0 .Lprio_694
	s_setprio 1
.Lprio_694:
.LBB0_694:
	s_add_i32 s56, s56, 1
	s_mul_i32 s4, s56, s59
	s_mul_hi_u32 s5, s56, s3
	s_add_i32 s5, s5, s4
	s_mul_i32 s4, s56, s3
	s_add_u32 s6, s4, s2
	s_addc_u32 s7, s5, s35
	v_cmp_gt_i64_e64 s[4:5], s[6:7], v[142:143]
	s_and_b64 vcc, exec, s[4:5]
	s_cbranch_vccnz .LBB0_696
	s_ashr_i32 s36, s6, 31
	s_lshr_b32 s36, s36, 29
	s_add_i32 s36, s6, s36
	s_ashr_i32 s37, s36, 3
	s_and_b32 s36, s36, -8
	s_sub_i32 s36, s6, s36
	s_cmp_lt_i32 s36, 0
	s_cselect_b32 s38, s52, 0x300
	s_mul_i32 s36, s38, s36
	s_add_i32 s36, s36, s37
	s_ashr_i32 s37, s36, 31
	s_lshr_b32 s37, s37, 25
	s_add_i32 s37, s36, s37
	s_ashr_i32 s38, s37, 7
	s_lshl_b32 s38, s38, 3
	s_sub_i32 s39, 0x180, s38
	s_min_i32 s39, s39, 8
	s_abs_i32 s40, s39
	v_cvt_f32_u32_e32 v0, s40
	s_sub_i32 s44, 0, s40
	s_and_b32 s37, s37, 0xffffff80
	s_sub_i32 s37, s36, s37
	v_rcp_iflag_f32_e32 v0, v0
	s_abs_i32 s36, s37
	s_xor_b32 s41, s37, s39
	s_ashr_i32 s41, s41, 31
	v_mul_f32_e32 v0, 0x4f7ffffe, v0
	v_cvt_u32_f32_e32 v0, v0
	s_nop 0
	v_readfirstlane_b32 s45, v0
	s_mul_i32 s44, s44, s45
	s_mul_hi_u32 s44, s45, s44
	s_add_i32 s45, s45, s44
	s_mul_hi_u32 s44, s36, s45
	s_mul_i32 s45, s44, s40
	s_sub_i32 s36, s36, s45
	s_add_i32 s67, s44, 1
	s_sub_i32 s45, s36, s40
	s_cmp_ge_u32 s36, s40
	s_cselect_b32 s44, s67, s44
	s_cselect_b32 s36, s45, s36
	s_add_i32 s45, s44, 1
	s_cmp_ge_u32 s36, s40
	s_cselect_b32 s36, s45, s44
	s_xor_b32 s36, s36, s41
	s_sub_i32 s36, s36, s41
	s_mul_i32 s39, s36, s39
	s_sub_i32 s37, s37, s39
	s_add_i32 s38, s37, s38

.LBB0_697:
	ds_read_b128 v[144:147], v157
	ds_read_b128 v[148:151], v157 offset:1024
	ds_read_b128 v[162:165], v157 offset:2048
	ds_read_b128 v[166:169], v157 offset:3072
	s_add_u32 s48, s6, 0xfffc0080
	s_addc_u32 s49, s7, -1
	s_cmp_eq_u32 s71, 12
	s_cselect_b32 s51, s39, s49
	s_cselect_b32 s50, s67, s48
	s_cselect_b32 s49, s37, s70
	s_cselect_b32 s48, s68, s69
	v_lshl_add_u64 v[202:203], s[6:7], 0, v[136:137]
	s_add_i32 m0, s47, 0xc000
	ds_read_b128 v[170:173], v158
	ds_read_b128 v[174:177], v158 offset:1024
	ds_read_b128 v[178:181], v158 offset:2048
	ds_read_b128 v[182:185], v158 offset:3072
	ds_read_b128 v[186:189], v158 offset:4096
	ds_read_b128 v[190:193], v158 offset:5120
	ds_read_b128 v[194:197], v158 offset:6144
	ds_read_b128 v[198:201], v158 offset:7168
	global_load_lds_dwordx4 v[202:203], off
	v_lshl_add_u64 v[202:203], s[6:7], 0, v[138:139]
	s_add_i32 m0, s47, 0xe000
	s_nop 0
	global_load_lds_dwordx4 v[202:203], off
	s_waitcnt lgkmcnt(8)
	s_barrier
	s_waitcnt lgkmcnt(0)
	s_waitcnt lgkmcnt(0)
	v_mfma_f32_16x16x32_bf16 v[124:127], v[144:147], v[170:173], v[124:127]
	v_mfma_f32_16x16x32_bf16 v[120:123], v[162:165], v[170:173], v[120:123]
	v_mfma_f32_16x16x32_bf16 v[108:111], v[144:147], v[178:181], v[108:111]
	v_mfma_f32_16x16x32_bf16 v[104:107], v[162:165], v[178:181], v[104:107]
	v_mfma_f32_16x16x32_bf16 v[92:95], v[144:147], v[186:189], v[92:95]
	v_mfma_f32_16x16x32_bf16 v[88:91], v[162:165], v[186:189], v[88:91]
	v_mfma_f32_16x16x32_bf16 v[76:79], v[144:147], v[194:197], v[76:79]
	v_mfma_f32_16x16x32_bf16 v[72:75], v[162:165], v[194:197], v[72:75]
	v_mfma_f32_16x16x32_bf16 v[124:127], v[148:151], v[174:177], v[124:127]
	v_mfma_f32_16x16x32_bf16 v[120:123], v[166:169], v[174:177], v[120:123]
	v_mfma_f32_16x16x32_bf16 v[108:111], v[148:151], v[182:185], v[108:111]
	v_mfma_f32_16x16x32_bf16 v[104:107], v[166:169], v[182:185], v[104:107]
	v_mfma_f32_16x16x32_bf16 v[92:95], v[148:151], v[190:193], v[92:95]
	v_mfma_f32_16x16x32_bf16 v[88:91], v[166:169], v[190:193], v[88:91]
	v_mfma_f32_16x16x32_bf16 v[76:79], v[148:151], v[198:201], v[76:79]
	v_mfma_f32_16x16x32_bf16 v[72:75], v[166:169], v[198:201], v[72:75]
	s_barrier
	s_add_i32 s73, s60, s34
	v_lshl_add_u64 v[218:219], s[48:49], 0, v[132:133]
	s_mov_b32 m0, s73
	ds_read_b128 v[202:205], v159
	ds_read_b128 v[206:209], v159 offset:1024
	ds_read_b128 v[210:213], v159 offset:2048
	ds_read_b128 v[214:217], v159 offset:3072
	global_load_lds_dwordx4 v[218:219], off
	v_lshl_add_u64 v[220:221], s[48:49], 0, v[128:129]
	s_add_i32 m0, s73, 0x2000
	s_nop 0
	global_load_lds_dwordx4 v[220:221], off
	s_barrier
	s_waitcnt lgkmcnt(0)
	s_waitcnt lgkmcnt(0)
	v_mfma_f32_16x16x32_bf16 v[116:119], v[202:205], v[170:173], v[116:119]
	v_mfma_f32_16x16x32_bf16 v[112:115], v[210:213], v[170:173], v[112:115]
	v_mfma_f32_16x16x32_bf16 v[100:103], v[202:205], v[178:181], v[100:103]
	v_mfma_f32_16x16x32_bf16 v[96:99], v[210:213], v[178:181], v[96:99]
	v_mfma_f32_16x16x32_bf16 v[84:87], v[202:205], v[186:189], v[84:87]
	v_mfma_f32_16x16x32_bf16 v[80:83], v[210:213], v[186:189], v[80:83]
	v_mfma_f32_16x16x32_bf16 v[68:71], v[202:205], v[194:197], v[68:71]
	v_mfma_f32_16x16x32_bf16 v[64:67], v[210:213], v[194:197], v[64:67]
	v_mfma_f32_16x16x32_bf16 v[116:119], v[206:209], v[174:177], v[116:119]
	v_mfma_f32_16x16x32_bf16 v[112:115], v[214:217], v[174:177], v[112:115]
	v_mfma_f32_16x16x32_bf16 v[100:103], v[206:209], v[182:185], v[100:103]
	v_mfma_f32_16x16x32_bf16 v[96:99], v[214:217], v[182:185], v[96:99]
	v_mfma_f32_16x16x32_bf16 v[84:87], v[206:209], v[190:193], v[84:87]
	v_mfma_f32_16x16x32_bf16 v[80:83], v[214:217], v[190:193], v[80:83]
	v_mfma_f32_16x16x32_bf16 v[68:71], v[206:209], v[198:201], v[68:71]
	v_mfma_f32_16x16x32_bf16 v[64:67], v[214:217], v[198:201], v[64:67]
	s_mov_b32 m0, s47
	v_lshl_add_u64 v[222:223], s[50:51], 0, v[134:135]
	s_barrier
	ds_read_b128 v[170:173], v158 offset:16384
	ds_read_b128 v[174:177], v158 offset:17408
	ds_read_b128 v[178:181], v158 offset:18432
	ds_read_b128 v[182:185], v158 offset:19456
	ds_read_b128 v[186:189], v158 offset:20480
	ds_read_b128 v[190:193], v158 offset:21504
	ds_read_b128 v[194:197], v158 offset:22528
	ds_read_b128 v[198:201], v158 offset:23552
	global_load_lds_dwordx4 v[222:223], off
	v_lshl_add_u64 v[224:225], s[50:51], 0, v[130:131]
	s_mov_b32 m0, s53
	s_nop 0
	global_load_lds_dwordx4 v[224:225], off
	s_barrier
	s_waitcnt lgkmcnt(0)
	s_waitcnt lgkmcnt(0)
	v_mfma_f32_16x16x32_bf16 v[60:63], v[144:147], v[170:173], v[60:63]
	v_mfma_f32_16x16x32_bf16 v[56:59], v[162:165], v[170:173], v[56:59]
	v_mfma_f32_16x16x32_bf16 v[44:47], v[144:147], v[178:181], v[44:47]
	v_mfma_f32_16x16x32_bf16 v[40:43], v[162:165], v[178:181], v[40:43]
	v_mfma_f32_16x16x32_bf16 v[28:31], v[144:147], v[186:189], v[28:31]
	v_mfma_f32_16x16x32_bf16 v[24:27], v[162:165], v[186:189], v[24:27]
	v_mfma_f32_16x16x32_bf16 v[12:15], v[144:147], v[194:197], v[12:15]
	v_mfma_f32_16x16x32_bf16 v[8:11], v[162:165], v[194:197], v[8:11]
	v_mfma_f32_16x16x32_bf16 v[60:63], v[148:151], v[174:177], v[60:63]
	v_mfma_f32_16x16x32_bf16 v[56:59], v[166:169], v[174:177], v[56:59]
	v_mfma_f32_16x16x32_bf16 v[44:47], v[148:151], v[182:185], v[44:47]
	v_mfma_f32_16x16x32_bf16 v[40:43], v[166:169], v[182:185], v[40:43]
	v_mfma_f32_16x16x32_bf16 v[28:31], v[148:151], v[190:193], v[28:31]
	v_mfma_f32_16x16x32_bf16 v[24:27], v[166:169], v[190:193], v[24:27]
	v_mfma_f32_16x16x32_bf16 v[12:15], v[148:151], v[198:201], v[12:15]
	v_mfma_f32_16x16x32_bf16 v[8:11], v[166:169], v[198:201], v[8:11]
	s_barrier
	s_add_u32 s74, s48, 0x40000
	s_addc_u32 s75, s49, 0
	s_add_i32 s73, s72, s34
	v_lshl_add_u64 v[144:145], s[74:75], 0, v[132:133]
	s_mov_b32 m0, s73
	s_nop 0
	global_load_lds_dwordx4 v[144:145], off
	v_lshl_add_u64 v[144:145], s[74:75], 0, v[128:129]
	s_add_i32 m0, s73, 0x2000
	s_nop 0
	global_load_lds_dwordx4 v[144:145], off
	s_waitcnt vmcnt(6)
	s_barrier
	v_mfma_f32_16x16x32_bf16 v[52:55], v[202:205], v[170:173], v[52:55]
	v_mfma_f32_16x16x32_bf16 v[48:51], v[210:213], v[170:173], v[48:51]
	v_mfma_f32_16x16x32_bf16 v[36:39], v[202:205], v[178:181], v[36:39]
	v_mfma_f32_16x16x32_bf16 v[32:35], v[210:213], v[178:181], v[32:35]
	v_mfma_f32_16x16x32_bf16 v[20:23], v[202:205], v[186:189], v[20:23]
	v_mfma_f32_16x16x32_bf16 v[16:19], v[210:213], v[186:189], v[16:19]
	v_mfma_f32_16x16x32_bf16 v[4:7], v[202:205], v[194:197], v[4:7]
	v_mfma_f32_16x16x32_bf16 v[0:3], v[210:213], v[194:197], v[0:3]
	v_mfma_f32_16x16x32_bf16 v[52:55], v[206:209], v[174:177], v[52:55]
	v_mfma_f32_16x16x32_bf16 v[48:51], v[214:217], v[174:177], v[48:51]
	v_mfma_f32_16x16x32_bf16 v[36:39], v[206:209], v[182:185], v[36:39]
	v_mfma_f32_16x16x32_bf16 v[32:35], v[214:217], v[182:185], v[32:35]
	v_mfma_f32_16x16x32_bf16 v[20:23], v[206:209], v[190:193], v[20:23]
	v_mfma_f32_16x16x32_bf16 v[16:19], v[214:217], v[190:193], v[16:19]
	v_mfma_f32_16x16x32_bf16 v[4:7], v[206:209], v[198:201], v[4:7]
	v_mfma_f32_16x16x32_bf16 v[0:3], v[214:217], v[198:201], v[0:3]
	s_add_i32 s73, 0, 0x18000
	v_add_u32_e32 v161, s73, v153
	s_barrier
	ds_read_b128 v[144:147], v161
	ds_read_b128 v[148:151], v161 offset:1024
	ds_read_b128 v[162:165], v161 offset:2048
	ds_read_b128 v[166:169], v161 offset:3072
	s_add_u32 s50, s50, 0x40000
	s_addc_u32 s51, s51, 0
	s_mov_b32 m0, s54
	v_lshl_add_u64 v[202:203], s[50:51], 0, v[134:135]
	ds_read_b128 v[170:173], v158 offset:32768
	ds_read_b128 v[174:177], v158 offset:33792
	ds_read_b128 v[178:181], v158 offset:34816
	ds_read_b128 v[182:185], v158 offset:35840
	ds_read_b128 v[186:189], v158 offset:36864
	ds_read_b128 v[190:193], v158 offset:37888
	ds_read_b128 v[194:197], v158 offset:38912
	ds_read_b128 v[198:201], v158 offset:39936
	global_load_lds_dwordx4 v[202:203], off
	v_lshl_add_u64 v[202:203], s[50:51], 0, v[130:131]
	s_mov_b32 m0, s55
	s_nop 0
	global_load_lds_dwordx4 v[202:203], off
	s_waitcnt lgkmcnt(8)
	s_barrier
	s_waitcnt lgkmcnt(0)
	s_waitcnt lgkmcnt(0)
	v_mfma_f32_16x16x32_bf16 v[124:127], v[144:147], v[170:173], v[124:127]
	v_mfma_f32_16x16x32_bf16 v[120:123], v[162:165], v[170:173], v[120:123]
	v_mfma_f32_16x16x32_bf16 v[108:111], v[144:147], v[178:181], v[108:111]
	v_mfma_f32_16x16x32_bf16 v[104:107], v[162:165], v[178:181], v[104:107]
	v_mfma_f32_16x16x32_bf16 v[92:95], v[144:147], v[186:189], v[92:95]
	v_mfma_f32_16x16x32_bf16 v[88:91], v[162:165], v[186:189], v[88:91]
	v_mfma_f32_16x16x32_bf16 v[76:79], v[144:147], v[194:197], v[76:79]
	v_mfma_f32_16x16x32_bf16 v[72:75], v[162:165], v[194:197], v[72:75]
	v_mfma_f32_16x16x32_bf16 v[124:127], v[148:151], v[174:177], v[124:127]
	v_mfma_f32_16x16x32_bf16 v[120:123], v[166:169], v[174:177], v[120:123]
	v_mfma_f32_16x16x32_bf16 v[108:111], v[148:151], v[182:185], v[108:111]
	v_mfma_f32_16x16x32_bf16 v[104:107], v[166:169], v[182:185], v[104:107]
	v_mfma_f32_16x16x32_bf16 v[92:95], v[148:151], v[190:193], v[92:95]
	v_mfma_f32_16x16x32_bf16 v[88:91], v[166:169], v[190:193], v[88:91]
	v_mfma_f32_16x16x32_bf16 v[76:79], v[148:151], v[198:201], v[76:79]
	v_mfma_f32_16x16x32_bf16 v[72:75], v[166:169], v[198:201], v[72:75]
	s_barrier
	s_add_i32 s50, s73, s34
	v_add_u32_e32 v161, s97, v153
	v_lshl_add_u64 v[218:219], v[218:219], 0, s[14:15]
	s_mov_b32 m0, s50
	ds_read_b128 v[202:205], v161
	ds_read_b128 v[206:209], v161 offset:1024
	ds_read_b128 v[210:213], v161 offset:2048
	ds_read_b128 v[214:217], v161 offset:3072
	global_load_lds_dwordx4 v[218:219], off
	v_lshl_add_u64 v[218:219], v[220:221], 0, s[14:15]
	s_add_i32 m0, s50, 0x2000
	s_nop 0
	global_load_lds_dwordx4 v[218:219], off
	s_barrier
	s_waitcnt lgkmcnt(0)
	s_waitcnt lgkmcnt(0)
	v_mfma_f32_16x16x32_bf16 v[116:119], v[202:205], v[170:173], v[116:119]
	v_mfma_f32_16x16x32_bf16 v[112:115], v[210:213], v[170:173], v[112:115]
	v_mfma_f32_16x16x32_bf16 v[100:103], v[202:205], v[178:181], v[100:103]
	v_mfma_f32_16x16x32_bf16 v[96:99], v[210:213], v[178:181], v[96:99]
	v_mfma_f32_16x16x32_bf16 v[84:87], v[202:205], v[186:189], v[84:87]
	v_mfma_f32_16x16x32_bf16 v[80:83], v[210:213], v[186:189], v[80:83]
	v_mfma_f32_16x16x32_bf16 v[68:71], v[202:205], v[194:197], v[68:71]
	v_mfma_f32_16x16x32_bf16 v[64:67], v[210:213], v[194:197], v[64:67]
	v_mfma_f32_16x16x32_bf16 v[116:119], v[206:209], v[174:177], v[116:119]
	v_mfma_f32_16x16x32_bf16 v[112:115], v[214:217], v[174:177], v[112:115]
	v_mfma_f32_16x16x32_bf16 v[100:103], v[206:209], v[182:185], v[100:103]
	v_mfma_f32_16x16x32_bf16 v[96:99], v[214:217], v[182:185], v[96:99]
	v_mfma_f32_16x16x32_bf16 v[84:87], v[206:209], v[190:193], v[84:87]
	v_mfma_f32_16x16x32_bf16 v[80:83], v[214:217], v[190:193], v[80:83]
	v_mfma_f32_16x16x32_bf16 v[68:71], v[206:209], v[198:201], v[68:71]
	v_mfma_f32_16x16x32_bf16 v[64:67], v[214:217], v[198:201], v[64:67]
	s_mov_b32 m0, s57
	v_lshl_add_u64 v[218:219], v[222:223], 0, s[14:15]
	s_barrier
	ds_read_b128 v[170:173], v158 offset:49152
	ds_read_b128 v[174:177], v158 offset:50176
	ds_read_b128 v[178:181], v158 offset:51200
	ds_read_b128 v[182:185], v158 offset:52224
	ds_read_b128 v[186:189], v158 offset:53248
	ds_read_b128 v[190:193], v158 offset:54272
	ds_read_b128 v[194:197], v158 offset:55296
	ds_read_b128 v[198:201], v158 offset:56320
	global_load_lds_dwordx4 v[218:219], off
	v_lshl_add_u64 v[218:219], v[224:225], 0, s[14:15]
	s_mov_b32 m0, s58
	s_nop 0
	global_load_lds_dwordx4 v[218:219], off
	s_barrier
	s_waitcnt lgkmcnt(0)
	s_waitcnt lgkmcnt(0)
	v_mfma_f32_16x16x32_bf16 v[60:63], v[144:147], v[170:173], v[60:63]
	v_mfma_f32_16x16x32_bf16 v[56:59], v[162:165], v[170:173], v[56:59]
	v_mfma_f32_16x16x32_bf16 v[44:47], v[144:147], v[178:181], v[44:47]
	v_mfma_f32_16x16x32_bf16 v[40:43], v[162:165], v[178:181], v[40:43]
	v_mfma_f32_16x16x32_bf16 v[28:31], v[144:147], v[186:189], v[28:31]
	v_mfma_f32_16x16x32_bf16 v[24:27], v[162:165], v[186:189], v[24:27]
	v_mfma_f32_16x16x32_bf16 v[12:15], v[144:147], v[194:197], v[12:15]
	v_mfma_f32_16x16x32_bf16 v[8:11], v[162:165], v[194:197], v[8:11]
	v_mfma_f32_16x16x32_bf16 v[60:63], v[148:151], v[174:177], v[60:63]
	v_mfma_f32_16x16x32_bf16 v[56:59], v[166:169], v[174:177], v[56:59]
	v_mfma_f32_16x16x32_bf16 v[44:47], v[148:151], v[182:185], v[44:47]
	v_mfma_f32_16x16x32_bf16 v[40:43], v[166:169], v[182:185], v[40:43]
	v_mfma_f32_16x16x32_bf16 v[28:31], v[148:151], v[190:193], v[28:31]
	v_mfma_f32_16x16x32_bf16 v[24:27], v[166:169], v[190:193], v[24:27]
	v_mfma_f32_16x16x32_bf16 v[12:15], v[148:151], v[198:201], v[12:15]
	v_mfma_f32_16x16x32_bf16 v[8:11], v[166:169], v[198:201], v[8:11]
	s_barrier
	s_add_u32 s48, s48, 0x40080
	s_addc_u32 s49, s49, 0
	s_add_i32 s50, s97, s34
	v_lshl_add_u64 v[144:145], s[48:49], 0, v[132:133]
	s_mov_b32 m0, s50
	s_nop 0
	global_load_lds_dwordx4 v[144:145], off
	v_lshl_add_u64 v[144:145], s[48:49], 0, v[128:129]
	s_add_i32 m0, s50, 0x2000
	s_nop 0
	global_load_lds_dwordx4 v[144:145], off
	s_waitcnt vmcnt(6)
	s_barrier
	v_mfma_f32_16x16x32_bf16 v[52:55], v[202:205], v[170:173], v[52:55]
	v_mfma_f32_16x16x32_bf16 v[48:51], v[210:213], v[170:173], v[48:51]
	v_mfma_f32_16x16x32_bf16 v[36:39], v[202:205], v[178:181], v[36:39]
	v_mfma_f32_16x16x32_bf16 v[32:35], v[210:213], v[178:181], v[32:35]
	v_mfma_f32_16x16x32_bf16 v[20:23], v[202:205], v[186:189], v[20:23]
	v_mfma_f32_16x16x32_bf16 v[16:19], v[210:213], v[186:189], v[16:19]
	v_mfma_f32_16x16x32_bf16 v[4:7], v[202:205], v[194:197], v[4:7]
	v_mfma_f32_16x16x32_bf16 v[0:3], v[210:213], v[194:197], v[0:3]
	v_mfma_f32_16x16x32_bf16 v[52:55], v[206:209], v[174:177], v[52:55]
	v_mfma_f32_16x16x32_bf16 v[48:51], v[214:217], v[174:177], v[48:51]
	v_mfma_f32_16x16x32_bf16 v[36:39], v[206:209], v[182:185], v[36:39]
	v_mfma_f32_16x16x32_bf16 v[32:35], v[214:217], v[182:185], v[32:35]
	v_mfma_f32_16x16x32_bf16 v[20:23], v[206:209], v[190:193], v[20:23]
	v_mfma_f32_16x16x32_bf16 v[16:19], v[214:217], v[190:193], v[16:19]
	v_mfma_f32_16x16x32_bf16 v[4:7], v[206:209], v[198:201], v[4:7]
	v_mfma_f32_16x16x32_bf16 v[0:3], v[214:217], v[198:201], v[0:3]
	s_add_i32 s71, s71, 2
	s_add_u32 s6, s6, 0x100
	s_addc_u32 s7, s7, 0
	s_add_u32 s69, s69, 0x100
	s_addc_u32 s70, s70, 0
	s_cmp_gt_u32 s71, 13
	s_barrier
	s_cbranch_scc0 .LBB0_697
	v_lshl_add_u32 v148, s46, 8, v152
	v_ashrrev_i32_e32 v149, 31, v148
	v_lshl_add_u64 v[144:145], v[148:149], 2, s[18:19]
	global_load_dword v151, v[144:145], off
	v_lshlrev_b64 v[146:147], 12, v[148:149]
	s_cmp_lt_i32 s66, 8
	s_cselect_b32 s7, s1, s29
	s_cselect_b32 s6, s0, s28
	s_cselect_b32 s37, 0, 0xfffff800
	s_lshl_b32 s39, s66, 8
	s_add_i32 s37, s37, s39
	v_or_b32_e32 v150, s37, v156
	v_or_b32_e32 v162, 16, v148
	v_lshl_add_u64 v[146:147], s[6:7], 0, v[146:147]
	v_ashrrev_i32_e32 v163, 31, v162
	v_lshl_add_u64 v[164:165], v[162:163], 2, s[18:19]
	s_mov_b32 s46, s38
	s_mov_b64 s[48:49], s[44:45]
	s_mov_b64 s[50:51], s[40:41]
	s_mov_b32 s66, s36
	s_waitcnt vmcnt(0)
	v_fmamk_f32 v149, v151, 0x3a800000, v160
	v_mul_f32_e32 v151, 0x4b800000, v149
	v_cmp_gt_f32_e32 vcc, s61, v149
	s_nop 1
	v_cndmask_b32_e32 v149, v149, v151, vcc
	v_rsq_f32_e32 v149, v149
	v_ashrrev_i32_e32 v151, 31, v150
	v_lshlrev_b64 v[150:151], 1, v[150:151]
	v_lshl_add_u64 v[146:147], v[146:147], 0, v[150:151]
	v_mul_f32_e32 v161, 0x45800000, v149
	v_cndmask_b32_e32 v149, v149, v161, vcc
	v_mul_f32_e32 v124, v124, v149
	v_mul_f32_e32 v120, v120, v149
	v_mul_f32_e32 v125, v125, v149
	v_mul_f32_e32 v121, v121, v149
	v_mul_f32_e32 v126, v126, v149
	v_mul_f32_e32 v122, v122, v149
	v_mul_f32_e32 v127, v127, v149
	v_mul_f32_e32 v123, v123, v149
	v_mul_f32_e32 v161, v116, v149
	v_mul_f32_e32 v166, v112, v149
	v_mul_f32_e32 v167, v117, v149
	v_mul_f32_e32 v168, v113, v149
	v_mul_f32_e32 v169, v118, v149
	v_mul_f32_e32 v170, v114, v149
	v_mul_f32_e32 v171, v119, v149
	v_mul_f32_e32 v149, v115, v149
	v_max_f32_e32 v112, 0, v124
	v_max_f32_e32 v114, 0, v120
	v_max_f32_e32 v113, 0, v125
	v_max_f32_e32 v115, 0, v121
	v_max_f32_e32 v116, 0, v126
	v_max_f32_e32 v118, 0, v122
	v_max_f32_e32 v117, 0, v127
	v_max_f32_e32 v119, 0, v123
	v_max_f32_e32 v120, 0, v161
	v_max_f32_e32 v122, 0, v166
	v_max_f32_e32 v121, 0, v167
	v_max_f32_e32 v123, 0, v168
	v_max_f32_e32 v124, 0, v169
	v_max_f32_e32 v126, 0, v170
	v_max_f32_e32 v125, 0, v171
	v_max_f32_e32 v127, 0, v149
	v_pk_mul_f32 v[112:113], v[112:113], v[112:113]
	v_pk_mul_f32 v[114:115], v[114:115], v[114:115]
	v_pk_mul_f32 v[116:117], v[116:117], v[116:117]
	v_pk_mul_f32 v[118:119], v[118:119], v[118:119]
	v_pk_mul_f32 v[120:121], v[120:121], v[120:121]
	v_pk_mul_f32 v[122:123], v[122:123], v[122:123]
	v_pk_mul_f32 v[124:125], v[124:125], v[124:125]
	v_pk_mul_f32 v[126:127], v[126:127], v[126:127]
	v_cvt_pk_bf16_f32 v112, v112, v113
	v_cvt_pk_bf16_f32 v113, v116, v117
	v_cvt_pk_bf16_f32 v114, v114, v115
	v_cvt_pk_bf16_f32 v115, v118, v119
	v_cvt_pk_bf16_f32 v116, v120, v121
	v_cvt_pk_bf16_f32 v117, v124, v125
	v_cvt_pk_bf16_f32 v118, v122, v123
	v_cvt_pk_bf16_f32 v119, v126, v127
	global_store_dwordx4 v[146:147], v[112:115], off
	global_store_dwordx4 v[146:147], v[116:119], off offset:256
	global_load_dword v116, v[164:165], off
	v_lshlrev_b64 v[114:115], 12, v[162:163]
	v_or_b32_e32 v112, 32, v148
	v_lshl_add_u64 v[114:115], s[6:7], 0, v[114:115]
	v_ashrrev_i32_e32 v113, 31, v112
	v_lshl_add_u64 v[114:115], v[114:115], 0, v[150:151]
	s_waitcnt vmcnt(0)
	v_fmamk_f32 v116, v116, 0x3a800000, v160
	v_mul_f32_e32 v117, 0x4b800000, v116
	v_cmp_gt_f32_e32 vcc, s61, v116
	s_nop 1
	v_cndmask_b32_e32 v116, v116, v117, vcc
	v_rsq_f32_e32 v118, v116
	v_lshl_add_u64 v[116:117], v[112:113], 2, s[18:19]
	v_mul_f32_e32 v119, 0x45800000, v118
	v_cndmask_b32_e32 v118, v118, v119, vcc
	v_mul_f32_e32 v108, v108, v118
	v_mul_f32_e32 v104, v104, v118
	v_mul_f32_e32 v109, v109, v118
	v_mul_f32_e32 v105, v105, v118
	v_mul_f32_e32 v110, v110, v118
	v_mul_f32_e32 v106, v106, v118
	v_mul_f32_e32 v111, v111, v118
	v_mul_f32_e32 v107, v107, v118
	v_mul_f32_e32 v119, v100, v118
	v_mul_f32_e32 v120, v96, v118
	v_mul_f32_e32 v121, v101, v118
	v_mul_f32_e32 v122, v97, v118
	v_mul_f32_e32 v123, v102, v118
	v_mul_f32_e32 v124, v98, v118
	v_mul_f32_e32 v125, v103, v118
	v_mul_f32_e32 v118, v99, v118
	v_max_f32_e32 v96, 0, v108
	v_max_f32_e32 v98, 0, v104
	v_max_f32_e32 v97, 0, v109
	v_max_f32_e32 v99, 0, v105
	v_max_f32_e32 v100, 0, v110
	v_max_f32_e32 v102, 0, v106
	v_max_f32_e32 v101, 0, v111
	v_max_f32_e32 v103, 0, v107
	v_max_f32_e32 v104, 0, v119
	v_max_f32_e32 v106, 0, v120
	v_max_f32_e32 v105, 0, v121
	v_max_f32_e32 v107, 0, v122
	v_max_f32_e32 v108, 0, v123
	v_max_f32_e32 v110, 0, v124
	v_max_f32_e32 v109, 0, v125
	v_max_f32_e32 v111, 0, v118
	v_pk_mul_f32 v[96:97], v[96:97], v[96:97]
	v_pk_mul_f32 v[98:99], v[98:99], v[98:99]
	v_pk_mul_f32 v[100:101], v[100:101], v[100:101]
	v_pk_mul_f32 v[102:103], v[102:103], v[102:103]
	v_pk_mul_f32 v[104:105], v[104:105], v[104:105]
	v_pk_mul_f32 v[106:107], v[106:107], v[106:107]
	v_pk_mul_f32 v[108:109], v[108:109], v[108:109]
	v_pk_mul_f32 v[110:111], v[110:111], v[110:111]
	v_cvt_pk_bf16_f32 v96, v96, v97
	v_cvt_pk_bf16_f32 v97, v100, v101
	v_cvt_pk_bf16_f32 v98, v98, v99
	v_cvt_pk_bf16_f32 v99, v102, v103
	v_cvt_pk_bf16_f32 v100, v104, v105
	v_cvt_pk_bf16_f32 v101, v108, v109
	v_cvt_pk_bf16_f32 v102, v106, v107
	v_cvt_pk_bf16_f32 v103, v110, v111
	global_store_dwordx4 v[114:115], v[96:99], off
	global_store_dwordx4 v[114:115], v[100:103], off offset:256
	global_load_dword v100, v[116:117], off
	v_lshlrev_b64 v[98:99], 12, v[112:113]
	v_or_b32_e32 v96, 48, v148
	v_lshl_add_u64 v[98:99], s[6:7], 0, v[98:99]
	v_ashrrev_i32_e32 v97, 31, v96
	v_lshl_add_u64 v[98:99], v[98:99], 0, v[150:151]
	s_waitcnt vmcnt(0)
	v_fmamk_f32 v100, v100, 0x3a800000, v160
	v_mul_f32_e32 v101, 0x4b800000, v100
	v_cmp_gt_f32_e32 vcc, s61, v100
	s_nop 1
	v_cndmask_b32_e32 v100, v100, v101, vcc
	v_rsq_f32_e32 v102, v100
	v_lshl_add_u64 v[100:101], v[96:97], 2, s[18:19]
	v_mul_f32_e32 v103, 0x45800000, v102
	v_cndmask_b32_e32 v102, v102, v103, vcc
	v_mul_f32_e32 v92, v92, v102
	v_mul_f32_e32 v88, v88, v102
	v_mul_f32_e32 v93, v93, v102
	v_mul_f32_e32 v89, v89, v102
	v_mul_f32_e32 v94, v94, v102
	v_mul_f32_e32 v90, v90, v102
	v_mul_f32_e32 v95, v95, v102
	v_mul_f32_e32 v91, v91, v102
	v_mul_f32_e32 v103, v84, v102
	v_mul_f32_e32 v104, v80, v102
	v_mul_f32_e32 v105, v85, v102
	v_mul_f32_e32 v106, v81, v102
	v_mul_f32_e32 v107, v86, v102
	v_mul_f32_e32 v108, v82, v102
	v_mul_f32_e32 v109, v87, v102
	v_mul_f32_e32 v102, v83, v102
	v_max_f32_e32 v80, 0, v92
	v_max_f32_e32 v82, 0, v88
	v_max_f32_e32 v81, 0, v93
	v_max_f32_e32 v83, 0, v89
	v_max_f32_e32 v84, 0, v94
	v_max_f32_e32 v86, 0, v90
	v_max_f32_e32 v85, 0, v95
	v_max_f32_e32 v87, 0, v91
	v_max_f32_e32 v88, 0, v103
	v_max_f32_e32 v90, 0, v104
	v_max_f32_e32 v89, 0, v105
	v_max_f32_e32 v91, 0, v106
	v_max_f32_e32 v92, 0, v107
	v_max_f32_e32 v94, 0, v108
	v_max_f32_e32 v93, 0, v109
	v_max_f32_e32 v95, 0, v102
	v_pk_mul_f32 v[80:81], v[80:81], v[80:81]
	v_pk_mul_f32 v[82:83], v[82:83], v[82:83]
	v_pk_mul_f32 v[84:85], v[84:85], v[84:85]
	v_pk_mul_f32 v[86:87], v[86:87], v[86:87]
	v_pk_mul_f32 v[88:89], v[88:89], v[88:89]
	v_pk_mul_f32 v[90:91], v[90:91], v[90:91]
	v_pk_mul_f32 v[92:93], v[92:93], v[92:93]
	v_pk_mul_f32 v[94:95], v[94:95], v[94:95]
	v_cvt_pk_bf16_f32 v80, v80, v81
	v_cvt_pk_bf16_f32 v81, v84, v85
	v_cvt_pk_bf16_f32 v82, v82, v83
	v_cvt_pk_bf16_f32 v83, v86, v87
	v_cvt_pk_bf16_f32 v84, v88, v89
	v_cvt_pk_bf16_f32 v85, v92, v93
	v_cvt_pk_bf16_f32 v86, v90, v91
	v_cvt_pk_bf16_f32 v87, v94, v95
	global_store_dwordx4 v[98:99], v[80:83], off
	global_store_dwordx4 v[98:99], v[84:87], off offset:256
	global_load_dword v80, v[100:101], off
	s_waitcnt vmcnt(0)
	v_fmamk_f32 v80, v80, 0x3a800000, v160
	v_mul_f32_e32 v81, 0x4b800000, v80
	v_cmp_gt_f32_e32 vcc, s61, v80
	s_nop 1
	v_cndmask_b32_e32 v80, v80, v81, vcc
	v_rsq_f32_e32 v82, v80
	v_lshlrev_b64 v[80:81], 12, v[96:97]
	v_lshl_add_u64 v[80:81], s[6:7], 0, v[80:81]
	v_lshl_add_u64 v[80:81], v[80:81], 0, v[150:151]
	v_mul_f32_e32 v83, 0x45800000, v82
	v_cndmask_b32_e32 v82, v82, v83, vcc
	v_mul_f32_e32 v76, v76, v82
	v_mul_f32_e32 v72, v72, v82
	v_mul_f32_e32 v77, v77, v82
	v_mul_f32_e32 v73, v73, v82
	v_mul_f32_e32 v78, v78, v82
	v_mul_f32_e32 v74, v74, v82
	v_mul_f32_e32 v79, v79, v82
	v_mul_f32_e32 v75, v75, v82
	v_mul_f32_e32 v83, v68, v82
	v_mul_f32_e32 v84, v64, v82
	v_mul_f32_e32 v85, v69, v82
	v_mul_f32_e32 v86, v65, v82
	v_mul_f32_e32 v87, v70, v82
	v_mul_f32_e32 v88, v66, v82
	v_mul_f32_e32 v89, v71, v82
	v_mul_f32_e32 v82, v67, v82
	v_max_f32_e32 v64, 0, v76
	v_max_f32_e32 v66, 0, v72
	v_max_f32_e32 v65, 0, v77
	v_max_f32_e32 v67, 0, v73
	v_max_f32_e32 v68, 0, v78
	v_max_f32_e32 v70, 0, v74
	v_max_f32_e32 v69, 0, v79
	v_max_f32_e32 v71, 0, v75
	v_max_f32_e32 v72, 0, v83
	v_max_f32_e32 v74, 0, v84
	v_max_f32_e32 v73, 0, v85
	v_max_f32_e32 v75, 0, v86
	v_max_f32_e32 v76, 0, v87
	v_max_f32_e32 v78, 0, v88
	v_max_f32_e32 v77, 0, v89
	v_max_f32_e32 v79, 0, v82
	v_pk_mul_f32 v[64:65], v[64:65], v[64:65]
	v_pk_mul_f32 v[66:67], v[66:67], v[66:67]
	v_pk_mul_f32 v[68:69], v[68:69], v[68:69]
	v_pk_mul_f32 v[70:71], v[70:71], v[70:71]
	v_pk_mul_f32 v[72:73], v[72:73], v[72:73]
	v_pk_mul_f32 v[74:75], v[74:75], v[74:75]
	v_pk_mul_f32 v[76:77], v[76:77], v[76:77]
	v_pk_mul_f32 v[78:79], v[78:79], v[78:79]
	v_cvt_pk_bf16_f32 v64, v64, v65
	v_cvt_pk_bf16_f32 v65, v68, v69
	v_cvt_pk_bf16_f32 v66, v66, v67
	v_cvt_pk_bf16_f32 v67, v70, v71
	v_cvt_pk_bf16_f32 v68, v72, v73
	v_cvt_pk_bf16_f32 v69, v76, v77
	v_cvt_pk_bf16_f32 v70, v74, v75
	v_cvt_pk_bf16_f32 v71, v78, v79
	global_store_dwordx4 v[80:81], v[64:67], off
	global_store_dwordx4 v[80:81], v[68:71], off offset:256
	global_load_dword v66, v[144:145], off offset:512
	v_lshl_add_u64 v[64:65], v[146:147], 0, s[16:17]
	s_waitcnt vmcnt(0)
	v_fmamk_f32 v66, v66, 0x3a800000, v160
	v_mul_f32_e32 v67, 0x4b800000, v66
	v_cmp_gt_f32_e32 vcc, s61, v66
	s_nop 1
	v_cndmask_b32_e32 v66, v66, v67, vcc
	v_rsq_f32_e32 v68, v66
	v_add_co_u32_e64 v66, s[6:7], s62, v146
	v_mul_f32_e32 v69, 0x45800000, v68
	v_cndmask_b32_e32 v68, v68, v69, vcc
	v_mul_f32_e32 v60, v60, v68
	v_mul_f32_e32 v56, v56, v68
	v_mul_f32_e32 v61, v61, v68
	v_mul_f32_e32 v57, v57, v68
	v_mul_f32_e32 v62, v62, v68
	v_mul_f32_e32 v58, v58, v68
	v_mul_f32_e32 v63, v63, v68
	v_mul_f32_e32 v59, v59, v68
	v_mul_f32_e32 v69, v52, v68
	v_mul_f32_e32 v70, v48, v68
	v_mul_f32_e32 v71, v53, v68
	v_mul_f32_e32 v72, v49, v68
	v_mul_f32_e32 v73, v54, v68
	v_mul_f32_e32 v74, v50, v68
	v_mul_f32_e32 v75, v55, v68
	v_mul_f32_e32 v68, v51, v68
	v_max_f32_e32 v48, 0, v60
	v_max_f32_e32 v50, 0, v56
	v_max_f32_e32 v49, 0, v61
	v_max_f32_e32 v51, 0, v57
	v_max_f32_e32 v52, 0, v62
	v_max_f32_e32 v54, 0, v58
	v_max_f32_e32 v53, 0, v63
	v_max_f32_e32 v55, 0, v59
	v_max_f32_e32 v56, 0, v69
	v_max_f32_e32 v58, 0, v70
	v_max_f32_e32 v57, 0, v71
	v_max_f32_e32 v59, 0, v72
	v_max_f32_e32 v60, 0, v73
	v_max_f32_e32 v62, 0, v74
	v_max_f32_e32 v61, 0, v75
	v_max_f32_e32 v63, 0, v68
	v_pk_mul_f32 v[48:49], v[48:49], v[48:49]
	v_pk_mul_f32 v[50:51], v[50:51], v[50:51]
	v_pk_mul_f32 v[52:53], v[52:53], v[52:53]
	v_pk_mul_f32 v[54:55], v[54:55], v[54:55]
	v_addc_co_u32_e64 v67, s[6:7], 0, v147, s[6:7]
	v_pk_mul_f32 v[56:57], v[56:57], v[56:57]
	v_pk_mul_f32 v[58:59], v[58:59], v[58:59]
	v_pk_mul_f32 v[60:61], v[60:61], v[60:61]
	v_pk_mul_f32 v[62:63], v[62:63], v[62:63]
	v_cvt_pk_bf16_f32 v48, v48, v49
	v_cvt_pk_bf16_f32 v49, v52, v53
	v_cvt_pk_bf16_f32 v50, v50, v51
	v_cvt_pk_bf16_f32 v51, v54, v55
	v_cvt_pk_bf16_f32 v52, v56, v57
	v_cvt_pk_bf16_f32 v53, v60, v61
	v_cvt_pk_bf16_f32 v54, v58, v59
	v_cvt_pk_bf16_f32 v55, v62, v63
	global_store_dwordx4 v[66:67], v[48:51], off
	global_store_dwordx4 v[64:65], v[52:55], off offset:256
	global_load_dword v50, v[144:145], off offset:576
	v_lshl_add_u64 v[48:49], v[146:147], 0, s[20:21]
	s_waitcnt vmcnt(0)
	v_fmamk_f32 v50, v50, 0x3a800000, v160
	v_mul_f32_e32 v51, 0x4b800000, v50
	v_cmp_gt_f32_e32 vcc, s61, v50
	s_nop 1
	v_cndmask_b32_e32 v50, v50, v51, vcc
	v_rsq_f32_e32 v52, v50
	v_add_co_u32_e64 v50, s[6:7], s63, v146
	v_mul_f32_e32 v53, 0x45800000, v52
	v_cndmask_b32_e32 v52, v52, v53, vcc
	v_mul_f32_e32 v44, v44, v52
	v_mul_f32_e32 v40, v40, v52
	v_mul_f32_e32 v45, v45, v52
	v_mul_f32_e32 v41, v41, v52
	v_mul_f32_e32 v46, v46, v52
	v_mul_f32_e32 v42, v42, v52
	v_mul_f32_e32 v47, v47, v52
	v_mul_f32_e32 v43, v43, v52
	v_mul_f32_e32 v53, v36, v52
	v_mul_f32_e32 v54, v32, v52
	v_mul_f32_e32 v55, v37, v52
	v_mul_f32_e32 v56, v33, v52
	v_mul_f32_e32 v57, v38, v52
	v_mul_f32_e32 v58, v34, v52
	v_mul_f32_e32 v59, v39, v52
	v_mul_f32_e32 v52, v35, v52
	v_max_f32_e32 v32, 0, v44
	v_max_f32_e32 v34, 0, v40
	v_max_f32_e32 v33, 0, v45
	v_max_f32_e32 v35, 0, v41
	v_max_f32_e32 v36, 0, v46
	v_max_f32_e32 v38, 0, v42
	v_max_f32_e32 v37, 0, v47
	v_max_f32_e32 v39, 0, v43
	v_max_f32_e32 v40, 0, v53
	v_max_f32_e32 v42, 0, v54
	v_max_f32_e32 v41, 0, v55
	v_max_f32_e32 v43, 0, v56
	v_max_f32_e32 v44, 0, v57
	v_max_f32_e32 v46, 0, v58
	v_max_f32_e32 v45, 0, v59
	v_max_f32_e32 v47, 0, v52
	v_pk_mul_f32 v[32:33], v[32:33], v[32:33]
	v_pk_mul_f32 v[34:35], v[34:35], v[34:35]
	v_pk_mul_f32 v[36:37], v[36:37], v[36:37]
	v_pk_mul_f32 v[38:39], v[38:39], v[38:39]
	v_addc_co_u32_e64 v51, s[6:7], 0, v147, s[6:7]
	v_pk_mul_f32 v[40:41], v[40:41], v[40:41]
	v_pk_mul_f32 v[42:43], v[42:43], v[42:43]
	v_pk_mul_f32 v[44:45], v[44:45], v[44:45]
	v_pk_mul_f32 v[46:47], v[46:47], v[46:47]
	v_cvt_pk_bf16_f32 v32, v32, v33
	v_cvt_pk_bf16_f32 v33, v36, v37
	v_cvt_pk_bf16_f32 v34, v34, v35
	v_cvt_pk_bf16_f32 v35, v38, v39
	v_cvt_pk_bf16_f32 v36, v40, v41
	v_cvt_pk_bf16_f32 v37, v44, v45
	v_cvt_pk_bf16_f32 v38, v42, v43
	v_cvt_pk_bf16_f32 v39, v46, v47
	global_store_dwordx4 v[50:51], v[32:35], off
	global_store_dwordx4 v[48:49], v[36:39], off offset:256
	global_load_dword v34, v[144:145], off offset:640
	v_lshl_add_u64 v[32:33], v[146:147], 0, s[22:23]
	s_waitcnt vmcnt(0)
	v_fmamk_f32 v34, v34, 0x3a800000, v160
	v_mul_f32_e32 v35, 0x4b800000, v34
	v_cmp_gt_f32_e32 vcc, s61, v34
	s_nop 1
	v_cndmask_b32_e32 v34, v34, v35, vcc
	v_rsq_f32_e32 v36, v34
	v_add_co_u32_e64 v34, s[6:7], s64, v146
	v_mul_f32_e32 v37, 0x45800000, v36
	v_cndmask_b32_e32 v36, v36, v37, vcc
	v_mul_f32_e32 v28, v28, v36
	v_mul_f32_e32 v24, v24, v36
	v_mul_f32_e32 v29, v29, v36
	v_mul_f32_e32 v25, v25, v36
	v_mul_f32_e32 v30, v30, v36
	v_mul_f32_e32 v26, v26, v36
	v_mul_f32_e32 v31, v31, v36
	v_mul_f32_e32 v27, v27, v36
	v_mul_f32_e32 v37, v20, v36
	v_mul_f32_e32 v38, v16, v36
	v_mul_f32_e32 v39, v21, v36
	v_mul_f32_e32 v40, v17, v36
	v_mul_f32_e32 v41, v22, v36
	v_mul_f32_e32 v42, v18, v36
	v_mul_f32_e32 v43, v23, v36
	v_mul_f32_e32 v36, v19, v36
	v_max_f32_e32 v16, 0, v28
	v_max_f32_e32 v18, 0, v24
	v_max_f32_e32 v17, 0, v29
	v_max_f32_e32 v19, 0, v25
	v_max_f32_e32 v20, 0, v30
	v_max_f32_e32 v22, 0, v26
	v_max_f32_e32 v21, 0, v31
	v_max_f32_e32 v23, 0, v27
	v_max_f32_e32 v24, 0, v37
	v_max_f32_e32 v26, 0, v38
	v_max_f32_e32 v25, 0, v39
	v_max_f32_e32 v27, 0, v40
	v_max_f32_e32 v28, 0, v41
	v_max_f32_e32 v30, 0, v42
	v_max_f32_e32 v29, 0, v43
	v_max_f32_e32 v31, 0, v36
	v_pk_mul_f32 v[16:17], v[16:17], v[16:17]
	v_pk_mul_f32 v[18:19], v[18:19], v[18:19]
	v_pk_mul_f32 v[20:21], v[20:21], v[20:21]
	v_pk_mul_f32 v[22:23], v[22:23], v[22:23]
	v_addc_co_u32_e64 v35, s[6:7], 0, v147, s[6:7]
	v_pk_mul_f32 v[24:25], v[24:25], v[24:25]
	v_pk_mul_f32 v[26:27], v[26:27], v[26:27]
	v_pk_mul_f32 v[28:29], v[28:29], v[28:29]
	v_pk_mul_f32 v[30:31], v[30:31], v[30:31]
	v_cvt_pk_bf16_f32 v16, v16, v17
	v_cvt_pk_bf16_f32 v17, v20, v21
	v_cvt_pk_bf16_f32 v18, v18, v19
	v_cvt_pk_bf16_f32 v19, v22, v23
	v_cvt_pk_bf16_f32 v20, v24, v25
	v_cvt_pk_bf16_f32 v21, v28, v29
	v_cvt_pk_bf16_f32 v22, v26, v27
	v_cvt_pk_bf16_f32 v23, v30, v31
	global_store_dwordx4 v[34:35], v[16:19], off
	global_store_dwordx4 v[32:33], v[20:23], off offset:256
	global_load_dword v18, v[144:145], off offset:704
	s_and_b64 vcc, exec, s[4:5]
	v_lshl_add_u64 v[16:17], v[146:147], 0, s[24:25]
	s_waitcnt vmcnt(0)
	v_fmamk_f32 v18, v18, 0x3a800000, v160
	v_mul_f32_e32 v19, 0x4b800000, v18
	v_cmp_gt_f32_e64 s[4:5], s61, v18
	s_nop 1
	v_cndmask_b32_e64 v18, v18, v19, s[4:5]
	v_rsq_f32_e32 v20, v18
	v_add_co_u32_e64 v18, s[6:7], s65, v146
	v_mul_f32_e32 v21, 0x45800000, v20
	v_cndmask_b32_e64 v20, v20, v21, s[4:5]
	v_mul_f32_e32 v12, v12, v20
	v_mul_f32_e32 v8, v8, v20
	v_mul_f32_e32 v13, v13, v20
	v_mul_f32_e32 v9, v9, v20
	v_mul_f32_e32 v14, v14, v20
	v_mul_f32_e32 v10, v10, v20
	v_mul_f32_e32 v15, v15, v20
	v_mul_f32_e32 v11, v11, v20
	v_mul_f32_e32 v21, v4, v20
	v_mul_f32_e32 v22, v0, v20
	v_mul_f32_e32 v23, v5, v20
	v_mul_f32_e32 v24, v1, v20
	v_mul_f32_e32 v25, v6, v20
	v_mul_f32_e32 v26, v2, v20
	v_mul_f32_e32 v27, v7, v20
	v_mul_f32_e32 v20, v3, v20
	v_max_f32_e32 v0, 0, v12
	v_max_f32_e32 v2, 0, v8
	v_max_f32_e32 v1, 0, v13
	v_max_f32_e32 v3, 0, v9
	v_max_f32_e32 v4, 0, v14
	v_max_f32_e32 v6, 0, v10
	v_max_f32_e32 v5, 0, v15
	v_max_f32_e32 v7, 0, v11
	v_max_f32_e32 v8, 0, v21
	v_max_f32_e32 v10, 0, v22
	v_max_f32_e32 v9, 0, v23
	v_max_f32_e32 v11, 0, v24
	v_max_f32_e32 v12, 0, v25
	v_max_f32_e32 v14, 0, v26
	v_max_f32_e32 v13, 0, v27
	v_max_f32_e32 v15, 0, v20
	v_pk_mul_f32 v[0:1], v[0:1], v[0:1]
	v_pk_mul_f32 v[2:3], v[2:3], v[2:3]
	v_pk_mul_f32 v[4:5], v[4:5], v[4:5]
	v_pk_mul_f32 v[6:7], v[6:7], v[6:7]
	v_addc_co_u32_e64 v19, s[6:7], 0, v147, s[6:7]
	v_pk_mul_f32 v[8:9], v[8:9], v[8:9]
	v_pk_mul_f32 v[10:11], v[10:11], v[10:11]
	v_pk_mul_f32 v[12:13], v[12:13], v[12:13]
	v_pk_mul_f32 v[14:15], v[14:15], v[14:15]
	v_cvt_pk_bf16_f32 v0, v0, v1
	v_cvt_pk_bf16_f32 v1, v4, v5
	v_cvt_pk_bf16_f32 v2, v2, v3
	v_cvt_pk_bf16_f32 v3, v6, v7
	v_cvt_pk_bf16_f32 v4, v8, v9
	v_cvt_pk_bf16_f32 v5, v12, v13
	v_cvt_pk_bf16_f32 v6, v10, v11
	v_cvt_pk_bf16_f32 v7, v14, v15
	global_store_dwordx4 v[18:19], v[0:3], off
	global_store_dwordx4 v[16:17], v[4:7], off offset:256
	s_cbranch_vccz .LBB0_694
	s_waitcnt vmcnt(0)
	s_cmpk_gt_u32 s33, 0xff
	s_cbranch_scc1 .LBB0_701
	s_barrier

.LBB0_702:
	s_waitcnt lgkmcnt(0)
	s_barrier
	s_setprio 0
	s_and_saveexec_b64 s[4:5], s[80:81]
	s_cbranch_execz .LBB0_712
	buffer_wbl2 sc1
	s_waitcnt vmcnt(0)
	s_load_dwordx2 s[6:7], s[78:79], -0x8
	s_load_dword s14, s[78:79], 0x0
	v_mov_b32_e32 v0, 0
	v_mov_b32_e32 v1, 1
	v_mov_b32_e32 v3, 0
	s_mov_b64 s[12:13], 0
	s_waitcnt lgkmcnt(0)
	s_add_u32 s6, s6, 0x2300080
	s_addc_u32 s7, s7, 0
	s_mul_i32 s14, s14, 8
	global_atomic_add v0, v1, s[6:7]

.LBB0_718:
	s_or_b64 exec, exec, s[36:37]
	s_add_u32 s19, s28, s24
	s_addc_u32 s21, s29, s25
	s_and_b64 s[6:7], s[14:15], s[6:7]
	s_and_b64 s[6:7], s[6:7], exec
	s_cselect_b32 s58, s21, s58
	s_cselect_b32 s59, s19, s59
	s_and_b64 vcc, exec, s[4:5]
	s_mov_b32 s36, s18
	s_mov_b32 s38, s20
	s_mov_b64 s[40:41], s[30:31]
	s_mov_b64 s[44:45], s[22:23]
	s_cbranch_vccnz .LBB0_744
	v_readfirstlane_b32 s4, v154
	s_bitcmp1_b32 s4, 8
	s_cbranch_scc0 .Lprio_719
	s_setprio 1
.Lprio_719:
.LBB0_719:
	s_add_i32 s56, s56, 1
	s_mul_i32 s4, s56, s62
	s_mul_hi_u32 s5, s56, s3
	s_add_i32 s5, s5, s4
	s_mul_i32 s4, s56, s3
	s_add_u32 s22, s4, s2
	s_addc_u32 s23, s5, s63
	v_cmp_gt_i64_e64 s[4:5], s[22:23], v[138:139]
	v_cmp_lt_i64_e64 s[6:7], s[22:23], v[136:137]
	s_and_b64 vcc, exec, s[4:5]
	s_cbranch_vccnz .LBB0_721
	s_ashr_i32 s18, s22, 31
	s_lshr_b32 s18, s18, 29
	s_add_i32 s18, s22, s18
	s_ashr_i32 s19, s18, 3
	s_and_b32 s18, s18, -8
	s_sub_i32 s18, s22, s18
	s_cmp_lt_i32 s18, 0
	s_cselect_b32 s20, s64, 0xc0
	s_mul_i32 s18, s20, s18
	s_add_i32 s18, s18, s19
	s_ashr_i32 s19, s18, 31
	s_lshr_b32 s19, s19, 27
	s_add_i32 s19, s18, s19
	s_ashr_i32 s20, s19, 5
	s_lshl_b32 s20, s20, 3
	s_sub_i32 s21, 0x180, s20
	s_min_i32 s21, s21, 8
	s_abs_i32 s22, s21
	v_cvt_f32_u32_e32 v0, s22
	s_sub_i32 s24, 0, s22
	s_andn2_b32 s19, s19, 31
	s_sub_i32 s19, s18, s19
	v_rcp_iflag_f32_e32 v0, v0
	s_abs_i32 s18, s19
	s_xor_b32 s23, s19, s21
	s_ashr_i32 s23, s23, 31
	v_mul_f32_e32 v0, 0x4f7ffffe, v0
	v_cvt_u32_f32_e32 v0, v0
	s_nop 0
	v_readfirstlane_b32 s25, v0
	s_mul_i32 s24, s24, s25
	s_mul_hi_u32 s24, s25, s24
	s_add_i32 s25, s25, s24
	s_mul_hi_u32 s24, s18, s25
	s_mul_i32 s25, s24, s22
	s_sub_i32 s18, s18, s25
	s_add_i32 s30, s24, 1
	s_sub_i32 s25, s18, s22
	s_cmp_ge_u32 s18, s22
	s_cselect_b32 s24, s30, s24
	s_cselect_b32 s18, s25, s18
	s_add_i32 s25, s24, 1
	s_cmp_ge_u32 s18, s22
	s_cselect_b32 s18, s25, s24
	s_xor_b32 s18, s18, s23
	s_sub_i32 s18, s18, s23
	s_mul_i32 s21, s18, s21
	s_sub_i32 s19, s19, s21
	s_add_i32 s20, s19, s20

.LBB0_722:
	s_or_b32 s52, s37, 1
	s_sub_i32 s53, s52, s57
	s_min_u32 s53, s52, s53
	s_cmp_lt_u32 s52, s57
	s_cselect_b32 s52, s45, s58
	s_cselect_b32 s67, s44, s59
	s_lshl_b32 s53, s53, 7
	v_add_u32_e32 v149, s65, v145
	s_add_u32 s53, s67, s53
	ds_read_b128 v[140:143], v149
	ds_read_b128 v[150:153], v149 offset:1024
	ds_read_b128 v[156:159], v149 offset:2048
	ds_read_b128 v[160:163], v149 offset:3072
	s_addc_u32 s67, s52, 0
	s_lshl_b32 s52, s37, 7
	s_add_u32 s52, s40, s52
	s_addc_u32 s68, s41, 0
	s_add_u32 s52, s52, 0x100
	s_addc_u32 s68, s68, 0
	s_and_b64 s[50:51], exec, s[50:51]
	s_cselect_b32 s51, s19, s68
	s_cselect_b32 s50, s21, s52
	s_add_u32 s52, s53, 0x80000
	s_addc_u32 s53, s67, 0
	v_lshl_add_u64 v[196:197], s[52:53], 0, v[128:129]
	s_add_i32 m0, s35, 0xc000
	ds_read_b128 v[164:167], v147
	ds_read_b128 v[168:171], v147 offset:1024
	ds_read_b128 v[172:175], v147 offset:2048
	ds_read_b128 v[176:179], v147 offset:3072
	ds_read_b128 v[180:183], v147 offset:4096
	ds_read_b128 v[184:187], v147 offset:5120
	ds_read_b128 v[188:191], v147 offset:6144
	ds_read_b128 v[192:195], v147 offset:7168
	global_load_lds_dwordx4 v[196:197], off
	v_lshl_add_u64 v[196:197], s[52:53], 0, v[132:133]
	s_add_i32 m0, s35, 0xe000
	s_nop 0
	global_load_lds_dwordx4 v[196:197], off
	s_waitcnt lgkmcnt(8)
	s_barrier
	s_waitcnt lgkmcnt(0)
	s_waitcnt lgkmcnt(0)
	v_mfma_f32_16x16x32_bf16 v[124:127], v[140:143], v[164:167], v[124:127]
	v_mfma_f32_16x16x32_bf16 v[120:123], v[156:159], v[164:167], v[120:123]
	v_mfma_f32_16x16x32_bf16 v[108:111], v[140:143], v[172:175], v[108:111]
	v_mfma_f32_16x16x32_bf16 v[104:107], v[156:159], v[172:175], v[104:107]
	v_mfma_f32_16x16x32_bf16 v[92:95], v[140:143], v[180:183], v[92:95]
	v_mfma_f32_16x16x32_bf16 v[88:91], v[156:159], v[180:183], v[88:91]
	v_mfma_f32_16x16x32_bf16 v[76:79], v[140:143], v[188:191], v[76:79]
	v_mfma_f32_16x16x32_bf16 v[72:75], v[156:159], v[188:191], v[72:75]
	v_mfma_f32_16x16x32_bf16 v[124:127], v[150:153], v[168:171], v[124:127]
	v_mfma_f32_16x16x32_bf16 v[120:123], v[160:163], v[168:171], v[120:123]
	v_mfma_f32_16x16x32_bf16 v[108:111], v[150:153], v[176:179], v[108:111]
	v_mfma_f32_16x16x32_bf16 v[104:107], v[160:163], v[176:179], v[104:107]
	v_mfma_f32_16x16x32_bf16 v[92:95], v[150:153], v[184:187], v[92:95]
	v_mfma_f32_16x16x32_bf16 v[88:91], v[160:163], v[184:187], v[88:91]
	v_mfma_f32_16x16x32_bf16 v[76:79], v[150:153], v[192:195], v[76:79]
	v_mfma_f32_16x16x32_bf16 v[72:75], v[160:163], v[192:195], v[72:75]
	s_barrier
	s_add_i32 s52, s65, s34
	v_add_u32_e32 v149, s72, v145
	v_lshl_add_u64 v[212:213], s[50:51], 0, v[130:131]
	s_mov_b32 m0, s52
	ds_read_b128 v[196:199], v149
	ds_read_b128 v[200:203], v149 offset:1024
	ds_read_b128 v[204:207], v149 offset:2048
	ds_read_b128 v[208:211], v149 offset:3072
	global_load_lds_dwordx4 v[212:213], off
	v_lshl_add_u64 v[214:215], s[50:51], 0, v[134:135]
	s_add_i32 m0, s52, 0x2000
	s_nop 0
	global_load_lds_dwordx4 v[214:215], off
	s_barrier
	s_waitcnt lgkmcnt(0)
	s_waitcnt lgkmcnt(0)
	v_mfma_f32_16x16x32_bf16 v[116:119], v[196:199], v[164:167], v[116:119]
	v_mfma_f32_16x16x32_bf16 v[112:115], v[204:207], v[164:167], v[112:115]
	v_mfma_f32_16x16x32_bf16 v[100:103], v[196:199], v[172:175], v[100:103]
	v_mfma_f32_16x16x32_bf16 v[96:99], v[204:207], v[172:175], v[96:99]
	v_mfma_f32_16x16x32_bf16 v[84:87], v[196:199], v[180:183], v[84:87]
	v_mfma_f32_16x16x32_bf16 v[80:83], v[204:207], v[180:183], v[80:83]
	v_mfma_f32_16x16x32_bf16 v[68:71], v[196:199], v[188:191], v[68:71]
	v_mfma_f32_16x16x32_bf16 v[64:67], v[204:207], v[188:191], v[64:67]
	v_mfma_f32_16x16x32_bf16 v[116:119], v[200:203], v[168:171], v[116:119]
	v_mfma_f32_16x16x32_bf16 v[112:115], v[208:211], v[168:171], v[112:115]
	v_mfma_f32_16x16x32_bf16 v[100:103], v[200:203], v[176:179], v[100:103]
	v_mfma_f32_16x16x32_bf16 v[96:99], v[208:211], v[176:179], v[96:99]
	v_mfma_f32_16x16x32_bf16 v[84:87], v[200:203], v[184:187], v[84:87]
	v_mfma_f32_16x16x32_bf16 v[80:83], v[208:211], v[184:187], v[80:83]
	v_mfma_f32_16x16x32_bf16 v[68:71], v[200:203], v[192:195], v[68:71]
	v_mfma_f32_16x16x32_bf16 v[64:67], v[208:211], v[192:195], v[64:67]
	s_mov_b32 m0, s35
	v_lshl_add_u64 v[216:217], s[48:49], 0, v[128:129]
	s_barrier
	ds_read_b128 v[164:167], v147 offset:16384
	ds_read_b128 v[168:171], v147 offset:17408
	ds_read_b128 v[172:175], v147 offset:18432
	ds_read_b128 v[176:179], v147 offset:19456
	ds_read_b128 v[180:183], v147 offset:20480
	ds_read_b128 v[184:187], v147 offset:21504
	ds_read_b128 v[188:191], v147 offset:22528
	ds_read_b128 v[192:195], v147 offset:23552
	global_load_lds_dwordx4 v[216:217], off
	v_lshl_add_u64 v[218:219], s[48:49], 0, v[132:133]
	s_mov_b32 m0, s39
	s_nop 0
	global_load_lds_dwordx4 v[218:219], off
	s_barrier
	s_waitcnt lgkmcnt(0)
	s_waitcnt lgkmcnt(0)
	v_mfma_f32_16x16x32_bf16 v[60:63], v[140:143], v[164:167], v[60:63]
	v_mfma_f32_16x16x32_bf16 v[56:59], v[156:159], v[164:167], v[56:59]
	v_mfma_f32_16x16x32_bf16 v[44:47], v[140:143], v[172:175], v[44:47]
	v_mfma_f32_16x16x32_bf16 v[40:43], v[156:159], v[172:175], v[40:43]
	v_mfma_f32_16x16x32_bf16 v[28:31], v[140:143], v[180:183], v[28:31]
	v_mfma_f32_16x16x32_bf16 v[24:27], v[156:159], v[180:183], v[24:27]
	v_mfma_f32_16x16x32_bf16 v[12:15], v[140:143], v[188:191], v[12:15]
	v_mfma_f32_16x16x32_bf16 v[8:11], v[156:159], v[188:191], v[8:11]
	v_mfma_f32_16x16x32_bf16 v[60:63], v[150:153], v[168:171], v[60:63]
	v_mfma_f32_16x16x32_bf16 v[56:59], v[160:163], v[168:171], v[56:59]
	v_mfma_f32_16x16x32_bf16 v[44:47], v[150:153], v[176:179], v[44:47]
	v_mfma_f32_16x16x32_bf16 v[40:43], v[160:163], v[176:179], v[40:43]
	v_mfma_f32_16x16x32_bf16 v[28:31], v[150:153], v[184:187], v[28:31]
	v_mfma_f32_16x16x32_bf16 v[24:27], v[160:163], v[184:187], v[24:27]
	v_mfma_f32_16x16x32_bf16 v[12:15], v[150:153], v[192:195], v[12:15]
	v_mfma_f32_16x16x32_bf16 v[8:11], v[160:163], v[192:195], v[8:11]
	s_barrier
	s_add_u32 s52, s50, 0x100000
	s_addc_u32 s53, s51, 0
	s_add_i32 s67, s72, s34
	v_lshl_add_u64 v[140:141], s[52:53], 0, v[130:131]
	s_mov_b32 m0, s67
	s_nop 0
	global_load_lds_dwordx4 v[140:141], off
	v_lshl_add_u64 v[140:141], s[52:53], 0, v[134:135]
	s_add_i32 m0, s67, 0x2000
	s_nop 0
	global_load_lds_dwordx4 v[140:141], off
	s_waitcnt vmcnt(6)
	s_barrier
	v_mfma_f32_16x16x32_bf16 v[52:55], v[196:199], v[164:167], v[52:55]
	v_mfma_f32_16x16x32_bf16 v[48:51], v[204:207], v[164:167], v[48:51]
	v_mfma_f32_16x16x32_bf16 v[36:39], v[196:199], v[172:175], v[36:39]
	v_mfma_f32_16x16x32_bf16 v[32:35], v[204:207], v[172:175], v[32:35]
	v_mfma_f32_16x16x32_bf16 v[20:23], v[196:199], v[180:183], v[20:23]
	v_mfma_f32_16x16x32_bf16 v[16:19], v[204:207], v[180:183], v[16:19]
	v_mfma_f32_16x16x32_bf16 v[4:7], v[196:199], v[188:191], v[4:7]
	v_mfma_f32_16x16x32_bf16 v[0:3], v[204:207], v[188:191], v[0:3]
	v_mfma_f32_16x16x32_bf16 v[52:55], v[200:203], v[168:171], v[52:55]
	v_mfma_f32_16x16x32_bf16 v[48:51], v[208:211], v[168:171], v[48:51]
	v_mfma_f32_16x16x32_bf16 v[36:39], v[200:203], v[176:179], v[36:39]
	v_mfma_f32_16x16x32_bf16 v[32:35], v[208:211], v[176:179], v[32:35]
	v_mfma_f32_16x16x32_bf16 v[20:23], v[200:203], v[184:187], v[20:23]
	v_mfma_f32_16x16x32_bf16 v[16:19], v[208:211], v[184:187], v[16:19]
	v_mfma_f32_16x16x32_bf16 v[4:7], v[200:203], v[192:195], v[4:7]
	v_mfma_f32_16x16x32_bf16 v[0:3], v[208:211], v[192:195], v[0:3]
	s_add_i32 s52, 0, 0x18000
	v_add_u32_e32 v149, s52, v145
	s_barrier
	ds_read_b128 v[140:143], v149
	ds_read_b128 v[150:153], v149 offset:1024
	ds_read_b128 v[156:159], v149 offset:2048
	ds_read_b128 v[160:163], v149 offset:3072
	s_add_u32 s48, s48, 0x80000
	s_addc_u32 s49, s49, 0
	s_mov_b32 m0, s54
	v_lshl_add_u64 v[196:197], s[48:49], 0, v[128:129]
	ds_read_b128 v[164:167], v147 offset:32768
	ds_read_b128 v[168:171], v147 offset:33792
	ds_read_b128 v[172:175], v147 offset:34816
	ds_read_b128 v[176:179], v147 offset:35840
	ds_read_b128 v[180:183], v147 offset:36864
	ds_read_b128 v[184:187], v147 offset:37888
	ds_read_b128 v[188:191], v147 offset:38912
	ds_read_b128 v[192:195], v147 offset:39936
	global_load_lds_dwordx4 v[196:197], off
	v_lshl_add_u64 v[196:197], s[48:49], 0, v[132:133]
	s_mov_b32 m0, s55
	s_nop 0
	global_load_lds_dwordx4 v[196:197], off
	s_waitcnt lgkmcnt(8)
	s_barrier
	s_waitcnt lgkmcnt(0)
	s_waitcnt lgkmcnt(0)
	v_mfma_f32_16x16x32_bf16 v[124:127], v[140:143], v[164:167], v[124:127]
	v_mfma_f32_16x16x32_bf16 v[120:123], v[156:159], v[164:167], v[120:123]
	v_mfma_f32_16x16x32_bf16 v[108:111], v[140:143], v[172:175], v[108:111]
	v_mfma_f32_16x16x32_bf16 v[104:107], v[156:159], v[172:175], v[104:107]
	v_mfma_f32_16x16x32_bf16 v[92:95], v[140:143], v[180:183], v[92:95]
	v_mfma_f32_16x16x32_bf16 v[88:91], v[156:159], v[180:183], v[88:91]
	v_mfma_f32_16x16x32_bf16 v[76:79], v[140:143], v[188:191], v[76:79]
	v_mfma_f32_16x16x32_bf16 v[72:75], v[156:159], v[188:191], v[72:75]
	v_mfma_f32_16x16x32_bf16 v[124:127], v[150:153], v[168:171], v[124:127]
	v_mfma_f32_16x16x32_bf16 v[120:123], v[160:163], v[168:171], v[120:123]
	v_mfma_f32_16x16x32_bf16 v[108:111], v[150:153], v[176:179], v[108:111]
	v_mfma_f32_16x16x32_bf16 v[104:107], v[160:163], v[176:179], v[104:107]
	v_mfma_f32_16x16x32_bf16 v[92:95], v[150:153], v[184:187], v[92:95]
	v_mfma_f32_16x16x32_bf16 v[88:91], v[160:163], v[184:187], v[88:91]
	v_mfma_f32_16x16x32_bf16 v[76:79], v[150:153], v[192:195], v[76:79]
	v_mfma_f32_16x16x32_bf16 v[72:75], v[160:163], v[192:195], v[72:75]
	s_barrier
	s_add_i32 s48, s52, s34
	v_add_u32_e32 v149, s97, v145
	v_lshl_add_u64 v[212:213], v[212:213], 0, s[16:17]
	s_mov_b32 m0, s48
	ds_read_b128 v[196:199], v149
	ds_read_b128 v[200:203], v149 offset:1024
	ds_read_b128 v[204:207], v149 offset:2048
	ds_read_b128 v[208:211], v149 offset:3072
	global_load_lds_dwordx4 v[212:213], off
	v_lshl_add_u64 v[212:213], v[214:215], 0, s[16:17]
	s_add_i32 m0, s48, 0x2000
	s_nop 0
	global_load_lds_dwordx4 v[212:213], off
	s_barrier
	s_waitcnt lgkmcnt(0)
	s_waitcnt lgkmcnt(0)
	v_mfma_f32_16x16x32_bf16 v[116:119], v[196:199], v[164:167], v[116:119]
	v_mfma_f32_16x16x32_bf16 v[112:115], v[204:207], v[164:167], v[112:115]
	v_mfma_f32_16x16x32_bf16 v[100:103], v[196:199], v[172:175], v[100:103]
	v_mfma_f32_16x16x32_bf16 v[96:99], v[204:207], v[172:175], v[96:99]
	v_mfma_f32_16x16x32_bf16 v[84:87], v[196:199], v[180:183], v[84:87]
	v_mfma_f32_16x16x32_bf16 v[80:83], v[204:207], v[180:183], v[80:83]
	v_mfma_f32_16x16x32_bf16 v[68:71], v[196:199], v[188:191], v[68:71]
	v_mfma_f32_16x16x32_bf16 v[64:67], v[204:207], v[188:191], v[64:67]
	v_mfma_f32_16x16x32_bf16 v[116:119], v[200:203], v[168:171], v[116:119]
	v_mfma_f32_16x16x32_bf16 v[112:115], v[208:211], v[168:171], v[112:115]
	v_mfma_f32_16x16x32_bf16 v[100:103], v[200:203], v[176:179], v[100:103]
	v_mfma_f32_16x16x32_bf16 v[96:99], v[208:211], v[176:179], v[96:99]
	v_mfma_f32_16x16x32_bf16 v[84:87], v[200:203], v[184:187], v[84:87]
	v_mfma_f32_16x16x32_bf16 v[80:83], v[208:211], v[184:187], v[80:83]
	v_mfma_f32_16x16x32_bf16 v[68:71], v[200:203], v[192:195], v[68:71]
	v_mfma_f32_16x16x32_bf16 v[64:67], v[208:211], v[192:195], v[64:67]
	s_mov_b32 m0, s60
	v_lshl_add_u64 v[212:213], v[216:217], 0, s[16:17]
	s_barrier
	ds_read_b128 v[164:167], v147 offset:49152
	ds_read_b128 v[168:171], v147 offset:50176
	ds_read_b128 v[172:175], v147 offset:51200
	ds_read_b128 v[176:179], v147 offset:52224
	ds_read_b128 v[180:183], v147 offset:53248
	ds_read_b128 v[184:187], v147 offset:54272
	ds_read_b128 v[188:191], v147 offset:55296
	ds_read_b128 v[192:195], v147 offset:56320
	global_load_lds_dwordx4 v[212:213], off
	v_lshl_add_u64 v[212:213], v[218:219], 0, s[16:17]
	s_mov_b32 m0, s61
	s_nop 0
	global_load_lds_dwordx4 v[212:213], off
	s_barrier
	s_waitcnt lgkmcnt(0)
	s_waitcnt lgkmcnt(0)
	v_mfma_f32_16x16x32_bf16 v[60:63], v[140:143], v[164:167], v[60:63]
	v_mfma_f32_16x16x32_bf16 v[56:59], v[156:159], v[164:167], v[56:59]
	v_mfma_f32_16x16x32_bf16 v[44:47], v[140:143], v[172:175], v[44:47]
	v_mfma_f32_16x16x32_bf16 v[40:43], v[156:159], v[172:175], v[40:43]
	v_mfma_f32_16x16x32_bf16 v[28:31], v[140:143], v[180:183], v[28:31]
	v_mfma_f32_16x16x32_bf16 v[24:27], v[156:159], v[180:183], v[24:27]
	v_mfma_f32_16x16x32_bf16 v[12:15], v[140:143], v[188:191], v[12:15]
	v_mfma_f32_16x16x32_bf16 v[8:11], v[156:159], v[188:191], v[8:11]
	v_mfma_f32_16x16x32_bf16 v[60:63], v[150:153], v[168:171], v[60:63]
	v_mfma_f32_16x16x32_bf16 v[56:59], v[160:163], v[168:171], v[56:59]
	v_mfma_f32_16x16x32_bf16 v[44:47], v[150:153], v[176:179], v[44:47]
	v_mfma_f32_16x16x32_bf16 v[40:43], v[160:163], v[176:179], v[40:43]
	v_mfma_f32_16x16x32_bf16 v[28:31], v[150:153], v[184:187], v[28:31]
	v_mfma_f32_16x16x32_bf16 v[24:27], v[160:163], v[184:187], v[24:27]
	v_mfma_f32_16x16x32_bf16 v[12:15], v[150:153], v[192:195], v[12:15]
	v_mfma_f32_16x16x32_bf16 v[8:11], v[160:163], v[192:195], v[8:11]
	s_barrier
	s_add_u32 s48, s50, 0x100080
	s_addc_u32 s49, s51, 0
	s_add_i32 s50, s97, s34
	v_lshl_add_u64 v[140:141], s[48:49], 0, v[130:131]
	s_mov_b32 m0, s50
	s_nop 0
	global_load_lds_dwordx4 v[140:141], off
	v_lshl_add_u64 v[140:141], s[48:49], 0, v[134:135]
	s_add_i32 m0, s50, 0x2000
	s_nop 0
	global_load_lds_dwordx4 v[140:141], off
	s_waitcnt vmcnt(6)
	s_barrier
	v_mfma_f32_16x16x32_bf16 v[52:55], v[196:199], v[164:167], v[52:55]
	v_mfma_f32_16x16x32_bf16 v[48:51], v[204:207], v[164:167], v[48:51]
	v_mfma_f32_16x16x32_bf16 v[36:39], v[196:199], v[172:175], v[36:39]
	v_mfma_f32_16x16x32_bf16 v[32:35], v[204:207], v[172:175], v[32:35]
	v_mfma_f32_16x16x32_bf16 v[20:23], v[196:199], v[180:183], v[20:23]
	v_mfma_f32_16x16x32_bf16 v[16:19], v[204:207], v[180:183], v[16:19]
	v_mfma_f32_16x16x32_bf16 v[4:7], v[196:199], v[188:191], v[4:7]
	v_mfma_f32_16x16x32_bf16 v[0:3], v[204:207], v[188:191], v[0:3]
	v_mfma_f32_16x16x32_bf16 v[52:55], v[200:203], v[168:171], v[52:55]
	v_mfma_f32_16x16x32_bf16 v[48:51], v[208:211], v[168:171], v[48:51]
	v_mfma_f32_16x16x32_bf16 v[36:39], v[200:203], v[176:179], v[36:39]
	v_mfma_f32_16x16x32_bf16 v[32:35], v[208:211], v[176:179], v[32:35]
	v_mfma_f32_16x16x32_bf16 v[20:23], v[200:203], v[184:187], v[20:23]
	v_mfma_f32_16x16x32_bf16 v[16:19], v[208:211], v[184:187], v[16:19]
	v_mfma_f32_16x16x32_bf16 v[4:7], v[200:203], v[192:195], v[4:7]
	v_mfma_f32_16x16x32_bf16 v[0:3], v[208:211], v[192:195], v[0:3]
	s_cmp_gt_u32 s37, 61
	s_mov_b32 s37, s66
	s_barrier
	s_cbranch_scc1 .LBB0_728

.LBB0_747:
	s_waitcnt lgkmcnt(0)
	s_barrier
	s_setprio 0
	s_and_saveexec_b64 s[2:3], s[80:81]
	s_cbranch_execz .LBB0_757
	buffer_wbl2 sc1
	s_waitcnt vmcnt(0)
	s_load_dwordx2 s[0:1], s[78:79], -0x8
	s_load_dword s6, s[78:79], 0x0
	v_mov_b32_e32 v0, 0
	v_mov_b32_e32 v1, 1
	v_mov_b32_e32 v3, 0
	s_mov_b64 s[4:5], 0
	s_waitcnt lgkmcnt(0)
	s_add_u32 s0, s0, 0x2300080
	s_addc_u32 s1, s1, 0
	s_mul_i32 s6, s6, 9
	global_atomic_add v0, v1, s[0:1]
